# v41 + LDS base VGPR definition hoisted out of the three peeled K-loops (no VALU left in the heaviest load segment); bit-identical
# baseline (speedup 1.0000x reference)
; #define PG8_WAIT_V(n) asm volatile("s_waitcnt vmcnt(" #n ")" ::: "memory")
; #define PG8_WAIT_L(n) asm volatile("s_waitcnt lgkmcnt(" #n ")" ::: "memory")
; #define PG8_BAR __builtin_amdgcn_s_barrier()
; #define PG8_SCHED __builtin_amdgcn_sched_barrier(0)
; template <class Epi, class AddrA, class AddrB>
; __device__ __forceinline__ void gemm_phase(const Sched S, const int lda, const int ldb, const int K, const AddrA addrA,
;                                            const AddrB addrB, const Epi E) {
;     ...
;       PG8_LDB(B0, 0, 0); PG8_SCHED; PG8_LDA(At, 0, 0); PG8_STAGE(PG8_SA(1, 1), a1 + hstepA, voffA);
;       PG8_WAIT_L(8); PG8_BAR; PG8_WAIT_L(0); PG8_MMA(0, 0, At, B0); PG8_BAR; PG8_SCHED;
;       PG8_LDB(B1, 0, 1); PG8_STAGE(PG8_SB(0, 0), b2, voffB);
;       PG8_BAR; PG8_WAIT_L(0); PG8_MMA(0, 1, At, B1); PG8_BAR;
;       PG8_LDA(At, 0, 1); PG8_STAGE(PG8_SA(0, 0), a2, voffA);
;       PG8_BAR; PG8_WAIT_L(0); PG8_MMA(1, 0, At, B0); PG8_BAR; PG8_SCHED;
;       PG8_STAGE(PG8_SB(0, 1), b2 + hstepB, voffB);
;       PG8_WAIT_V(6); PG8_BAR; PG8_MMA(1, 1, At, B1); PG8_BAR;
.LBB0_109:
	s_add_i32 s40, 0, 0x10000
	ds_read_b128 v[148:151], v246
	ds_read_b128 v[152:155], v246 offset:1024
	ds_read_b128 v[156:159], v246 offset:2048
	ds_read_b128 v[160:163], v246 offset:3072
	s_add_i32 m0, s24, 0xc000
	ds_read_b128 v[168:171], v146
	ds_read_b128 v[172:175], v146 offset:1024
	ds_read_b128 v[176:179], v146 offset:2048
	ds_read_b128 v[180:183], v146 offset:3072
	ds_read_b128 v[184:187], v146 offset:4096
	ds_read_b128 v[188:191], v146 offset:5120
	ds_read_b128 v[192:195], v146 offset:6144
	ds_read_b128 v[212:215], v146 offset:7168
	global_load_lds_dwordx4 v140, s[12:13]
	s_add_i32 m0, s24, 0xe000
	s_nop 0
	global_load_lds_dwordx4 v138, s[12:13]
	s_waitcnt lgkmcnt(6)
	s_setprio 1
	s_barrier
	v_mfma_f32_16x16x32_bf16 v[128:131], v[148:151], v[168:171], v[128:131]
	v_mfma_f32_16x16x32_bf16 v[128:131], v[152:155], v[172:175], v[128:131]
	s_waitcnt lgkmcnt(0)
	v_mfma_f32_16x16x32_bf16 v[120:123], v[148:151], v[176:179], v[120:123]
	v_mfma_f32_16x16x32_bf16 v[120:123], v[152:155], v[180:183], v[120:123]
	v_mfma_f32_16x16x32_bf16 v[104:107], v[148:151], v[184:187], v[104:107]
	v_mfma_f32_16x16x32_bf16 v[104:107], v[152:155], v[188:191], v[104:107]
	v_mfma_f32_16x16x32_bf16 v[88:91], v[148:151], v[192:195], v[88:91]
	v_mfma_f32_16x16x32_bf16 v[88:91], v[152:155], v[212:215], v[88:91]
	v_mfma_f32_16x16x32_bf16 v[124:127], v[156:159], v[168:171], v[124:127]
	v_mfma_f32_16x16x32_bf16 v[124:127], v[160:163], v[172:175], v[124:127]
	v_mfma_f32_16x16x32_bf16 v[112:115], v[156:159], v[176:179], v[112:115]
	v_mfma_f32_16x16x32_bf16 v[112:115], v[160:163], v[180:183], v[112:115]
	v_mfma_f32_16x16x32_bf16 v[96:99], v[156:159], v[184:187], v[96:99]
	v_mfma_f32_16x16x32_bf16 v[96:99], v[160:163], v[188:191], v[96:99]
	v_mfma_f32_16x16x32_bf16 v[80:83], v[156:159], v[192:195], v[80:83]
	v_mfma_f32_16x16x32_bf16 v[80:83], v[160:163], v[212:215], v[80:83]
	s_barrier
	s_setprio 0
	s_add_u32 s14, s12, 0xfff80080
	s_addc_u32 s15, s13, -1
	s_cmp_eq_u32 s39, 28
	s_cselect_b32 s17, s1, s15
	s_cselect_b32 s16, s11, s14
	s_cselect_b32 s15, s3, s38
	s_cselect_b32 s14, s36, s37
	s_add_i32 s42, 0, 0x14000
	s_add_i32 s40, s40, s19
	ds_read_b128 v[216:219], v246 offset:16384
	ds_read_b128 v[220:223], v246 offset:17408
	ds_read_b128 v[224:227], v246 offset:18432
	ds_read_b128 v[228:231], v246 offset:19456
	s_add_u32 s98, s14, 0x80
	s_addc_u32 s99, s15, 0
	s_mov_b32 m0, s40
	s_nop 0
	global_load_lds_dwordx4 v134, s[14:15]
	s_add_i32 m0, s40, 0x2000
	s_nop 0
	global_load_lds_dwordx4 v0, s[14:15]
	s_mov_b32 m0, s24
	s_add_u32 s100, s16, 0x80
	s_addc_u32 s101, s17, 0
	s_waitcnt vmcnt(10)
	s_waitcnt lgkmcnt(2)
	s_setprio 1
	s_barrier
	v_mfma_f32_16x16x32_bf16 v[116:119], v[216:219], v[168:171], v[116:119]
	v_mfma_f32_16x16x32_bf16 v[116:119], v[220:223], v[172:175], v[116:119]
	s_waitcnt lgkmcnt(0)
	v_mfma_f32_16x16x32_bf16 v[100:103], v[216:219], v[176:179], v[100:103]
	v_mfma_f32_16x16x32_bf16 v[100:103], v[220:223], v[180:183], v[100:103]
	v_mfma_f32_16x16x32_bf16 v[84:87], v[216:219], v[184:187], v[84:87]
	v_mfma_f32_16x16x32_bf16 v[84:87], v[220:223], v[188:191], v[84:87]
	v_mfma_f32_16x16x32_bf16 v[72:75], v[216:219], v[192:195], v[72:75]
	v_mfma_f32_16x16x32_bf16 v[72:75], v[220:223], v[212:215], v[72:75]
	v_mfma_f32_16x16x32_bf16 v[108:111], v[224:227], v[168:171], v[108:111]
	v_mfma_f32_16x16x32_bf16 v[108:111], v[228:231], v[172:175], v[108:111]
	v_mfma_f32_16x16x32_bf16 v[92:95], v[224:227], v[176:179], v[92:95]
	v_mfma_f32_16x16x32_bf16 v[92:95], v[228:231], v[180:183], v[92:95]
	v_mfma_f32_16x16x32_bf16 v[76:79], v[224:227], v[184:187], v[76:79]
	v_mfma_f32_16x16x32_bf16 v[76:79], v[228:231], v[188:191], v[76:79]
	v_mfma_f32_16x16x32_bf16 v[68:71], v[224:227], v[192:195], v[68:71]
	v_mfma_f32_16x16x32_bf16 v[68:71], v[228:231], v[212:215], v[68:71]
	s_barrier
	s_setprio 0
	ds_read_b128 v[168:171], v146 offset:16384
	ds_read_b128 v[172:175], v146 offset:17408
	ds_read_b128 v[176:179], v146 offset:18432
	ds_read_b128 v[180:183], v146 offset:19456
	ds_read_b128 v[184:187], v146 offset:20480
	ds_read_b128 v[188:191], v146 offset:21504
	ds_read_b128 v[192:195], v146 offset:22528
	ds_read_b128 v[212:215], v146 offset:23552
	global_load_lds_dwordx4 v136, s[16:17]
	s_mov_b32 m0, s25
	s_nop 0
	global_load_lds_dwordx4 v132, s[16:17]
	s_waitcnt lgkmcnt(6)
	s_setprio 1
	s_barrier
	v_mfma_f32_16x16x32_bf16 v[64:67], v[148:151], v[168:171], v[64:67]
	v_mfma_f32_16x16x32_bf16 v[64:67], v[152:155], v[172:175], v[64:67]
	s_waitcnt lgkmcnt(0)
	v_mfma_f32_16x16x32_bf16 v[56:59], v[148:151], v[176:179], v[56:59]
	v_mfma_f32_16x16x32_bf16 v[56:59], v[152:155], v[180:183], v[56:59]
	v_mfma_f32_16x16x32_bf16 v[40:43], v[148:151], v[184:187], v[40:43]
	v_mfma_f32_16x16x32_bf16 v[40:43], v[152:155], v[188:191], v[40:43]
	v_mfma_f32_16x16x32_bf16 v[24:27], v[148:151], v[192:195], v[24:27]
	v_mfma_f32_16x16x32_bf16 v[24:27], v[152:155], v[212:215], v[24:27]
	v_mfma_f32_16x16x32_bf16 v[60:63], v[156:159], v[168:171], v[60:63]
	v_mfma_f32_16x16x32_bf16 v[60:63], v[160:163], v[172:175], v[60:63]
	v_mfma_f32_16x16x32_bf16 v[48:51], v[156:159], v[176:179], v[48:51]
	v_mfma_f32_16x16x32_bf16 v[48:51], v[160:163], v[180:183], v[48:51]
	v_mfma_f32_16x16x32_bf16 v[32:35], v[156:159], v[184:187], v[32:35]
	v_mfma_f32_16x16x32_bf16 v[32:35], v[160:163], v[188:191], v[32:35]
	v_mfma_f32_16x16x32_bf16 v[16:19], v[156:159], v[192:195], v[16:19]
	v_mfma_f32_16x16x32_bf16 v[16:19], v[160:163], v[212:215], v[16:19]
	s_barrier
	s_setprio 0
	s_add_u32 s40, s14, 0x80000
	s_addc_u32 s41, s15, 0
	s_add_i32 s42, s42, s19
	s_mov_b32 m0, s42
	s_nop 0
	global_load_lds_dwordx4 v134, s[40:41]
	s_add_i32 m0, s42, 0x2000
	s_nop 0
	global_load_lds_dwordx4 v0, s[40:41]
	s_add_i32 s40, 0, 0x18000
	s_waitcnt vmcnt(8)
	s_setprio 1
	s_barrier
; #define PG8_WAIT_V(n) asm volatile("s_waitcnt vmcnt(" #n ")" ::: "memory")
; #define PG8_WAIT_L(n) asm volatile("s_waitcnt lgkmcnt(" #n ")" ::: "memory")
; #define PG8_BAR __builtin_amdgcn_s_barrier()
; #define PG8_SCHED __builtin_amdgcn_sched_barrier(0)
; template <class Epi, class AddrA, class AddrB>
; __device__ __forceinline__ void gemm_phase(const Sched S, const int lda, const int ldb, const int K, const AddrA addrA,
;                                            const AddrB addrB, const Epi E) {
;     ...
;       PG8_WAIT_V(6); PG8_BAR; PG8_MMA(1, 1, At, B1); PG8_BAR;
;       PG8_LDB(B0, 1, 0); PG8_SCHED; PG8_LDA(At, 1, 0); PG8_STAGE(PG8_SA(0, 1), a2 + hstepA, voffA);
;       PG8_WAIT_L(8); PG8_BAR; PG8_WAIT_L(0); PG8_MMA(0, 0, At, B0); PG8_BAR; PG8_SCHED;
;       PG8_LDB(B1, 1, 1); PG8_STAGE(PG8_SB(1, 0), b3, voffB);
;       PG8_BAR; PG8_WAIT_L(0); PG8_MMA(0, 1, At, B1); PG8_BAR;
	v_mfma_f32_16x16x32_bf16 v[52:55], v[216:219], v[168:171], v[52:55]
	v_mfma_f32_16x16x32_bf16 v[52:55], v[220:223], v[172:175], v[52:55]
	v_mfma_f32_16x16x32_bf16 v[36:39], v[216:219], v[176:179], v[36:39]
	v_mfma_f32_16x16x32_bf16 v[36:39], v[220:223], v[180:183], v[36:39]
	v_mfma_f32_16x16x32_bf16 v[20:23], v[216:219], v[184:187], v[20:23]
	v_mfma_f32_16x16x32_bf16 v[20:23], v[220:223], v[188:191], v[20:23]
	v_mfma_f32_16x16x32_bf16 v[8:11], v[216:219], v[192:195], v[8:11]
	v_mfma_f32_16x16x32_bf16 v[8:11], v[220:223], v[212:215], v[8:11]
	v_mfma_f32_16x16x32_bf16 v[44:47], v[224:227], v[168:171], v[44:47]
	v_mfma_f32_16x16x32_bf16 v[44:47], v[228:231], v[172:175], v[44:47]
	v_mfma_f32_16x16x32_bf16 v[28:31], v[224:227], v[176:179], v[28:31]
	v_mfma_f32_16x16x32_bf16 v[28:31], v[228:231], v[180:183], v[28:31]
	v_mfma_f32_16x16x32_bf16 v[12:15], v[224:227], v[184:187], v[12:15]
	v_mfma_f32_16x16x32_bf16 v[12:15], v[228:231], v[188:191], v[12:15]
	v_mfma_f32_16x16x32_bf16 v[4:7], v[224:227], v[192:195], v[4:7]
	v_mfma_f32_16x16x32_bf16 v[4:7], v[228:231], v[212:215], v[4:7]
	s_barrier
	s_setprio 0
	ds_read_b128 v[148:151], v246 offset:32768
	ds_read_b128 v[152:155], v246 offset:33792
	ds_read_b128 v[156:159], v246 offset:34816
	ds_read_b128 v[160:163], v246 offset:35840
	s_add_u32 s16, s16, 0x80000
	s_addc_u32 s17, s17, 0
	s_mov_b32 m0, s26
	ds_read_b128 v[168:171], v146 offset:32768
	ds_read_b128 v[172:175], v146 offset:33792
	ds_read_b128 v[176:179], v146 offset:34816
	ds_read_b128 v[180:183], v146 offset:35840
	ds_read_b128 v[184:187], v146 offset:36864
	ds_read_b128 v[188:191], v146 offset:37888
	ds_read_b128 v[192:195], v146 offset:38912
	ds_read_b128 v[212:215], v146 offset:39936
	global_load_lds_dwordx4 v136, s[16:17]
	s_mov_b32 m0, s27
	s_nop 0
	global_load_lds_dwordx4 v132, s[16:17]
	s_waitcnt lgkmcnt(6)
	s_setprio 1
	s_barrier
	v_mfma_f32_16x16x32_bf16 v[128:131], v[148:151], v[168:171], v[128:131]
	v_mfma_f32_16x16x32_bf16 v[128:131], v[152:155], v[172:175], v[128:131]
	s_waitcnt lgkmcnt(0)
	v_mfma_f32_16x16x32_bf16 v[120:123], v[148:151], v[176:179], v[120:123]
	v_mfma_f32_16x16x32_bf16 v[120:123], v[152:155], v[180:183], v[120:123]
	v_mfma_f32_16x16x32_bf16 v[104:107], v[148:151], v[184:187], v[104:107]
	v_mfma_f32_16x16x32_bf16 v[104:107], v[152:155], v[188:191], v[104:107]
	v_mfma_f32_16x16x32_bf16 v[88:91], v[148:151], v[192:195], v[88:91]
	v_mfma_f32_16x16x32_bf16 v[88:91], v[152:155], v[212:215], v[88:91]
	v_mfma_f32_16x16x32_bf16 v[124:127], v[156:159], v[168:171], v[124:127]
	v_mfma_f32_16x16x32_bf16 v[124:127], v[160:163], v[172:175], v[124:127]
	v_mfma_f32_16x16x32_bf16 v[112:115], v[156:159], v[176:179], v[112:115]
	v_mfma_f32_16x16x32_bf16 v[112:115], v[160:163], v[180:183], v[112:115]
	v_mfma_f32_16x16x32_bf16 v[96:99], v[156:159], v[184:187], v[96:99]
	v_mfma_f32_16x16x32_bf16 v[96:99], v[160:163], v[188:191], v[96:99]
	v_mfma_f32_16x16x32_bf16 v[80:83], v[156:159], v[192:195], v[80:83]
	v_mfma_f32_16x16x32_bf16 v[80:83], v[160:163], v[212:215], v[80:83]
	s_barrier
	s_setprio 0
	s_add_i32 s16, 0, 0x1c000
	s_add_i32 s17, s40, s19
	s_mov_b32 m0, s17
	ds_read_b128 v[216:219], v246 offset:49152
	ds_read_b128 v[220:223], v246 offset:50176
	ds_read_b128 v[224:227], v246 offset:51200
	ds_read_b128 v[228:231], v246 offset:52224
	global_load_lds_dwordx4 v134, s[98:99]
	s_add_i32 m0, s17, 0x2000
	s_nop 0
	global_load_lds_dwordx4 v0, s[98:99]
	s_mov_b32 m0, s30
	s_waitcnt vmcnt(10)
	s_waitcnt lgkmcnt(2)
	s_setprio 1
	s_barrier
	v_mfma_f32_16x16x32_bf16 v[116:119], v[216:219], v[168:171], v[116:119]
	v_mfma_f32_16x16x32_bf16 v[116:119], v[220:223], v[172:175], v[116:119]
	s_waitcnt lgkmcnt(0)
	v_mfma_f32_16x16x32_bf16 v[100:103], v[216:219], v[176:179], v[100:103]
	v_mfma_f32_16x16x32_bf16 v[100:103], v[220:223], v[180:183], v[100:103]
	v_mfma_f32_16x16x32_bf16 v[84:87], v[216:219], v[184:187], v[84:87]
	v_mfma_f32_16x16x32_bf16 v[84:87], v[220:223], v[188:191], v[84:87]
	v_mfma_f32_16x16x32_bf16 v[72:75], v[216:219], v[192:195], v[72:75]
	v_mfma_f32_16x16x32_bf16 v[72:75], v[220:223], v[212:215], v[72:75]
	v_mfma_f32_16x16x32_bf16 v[108:111], v[224:227], v[168:171], v[108:111]
	v_mfma_f32_16x16x32_bf16 v[108:111], v[228:231], v[172:175], v[108:111]
	v_mfma_f32_16x16x32_bf16 v[92:95], v[224:227], v[176:179], v[92:95]
	v_mfma_f32_16x16x32_bf16 v[92:95], v[228:231], v[180:183], v[92:95]
	v_mfma_f32_16x16x32_bf16 v[76:79], v[224:227], v[184:187], v[76:79]
	v_mfma_f32_16x16x32_bf16 v[76:79], v[228:231], v[188:191], v[76:79]
	v_mfma_f32_16x16x32_bf16 v[68:71], v[224:227], v[192:195], v[68:71]
	v_mfma_f32_16x16x32_bf16 v[68:71], v[228:231], v[212:215], v[68:71]
	s_barrier
	s_setprio 0
	ds_read_b128 v[168:171], v146 offset:49152
	ds_read_b128 v[172:175], v146 offset:50176
	ds_read_b128 v[176:179], v146 offset:51200
	ds_read_b128 v[180:183], v146 offset:52224
	ds_read_b128 v[184:187], v146 offset:53248
	ds_read_b128 v[188:191], v146 offset:54272
	ds_read_b128 v[192:195], v146 offset:55296
	ds_read_b128 v[212:215], v146 offset:56320
	global_load_lds_dwordx4 v136, s[100:101]
	s_mov_b32 m0, s31
	s_nop 0
	global_load_lds_dwordx4 v132, s[100:101]
	s_waitcnt lgkmcnt(6)
	s_setprio 1
	s_barrier
; #define PG8_WAIT_V(n) asm volatile("s_waitcnt vmcnt(" #n ")" ::: "memory")
; #define PG8_WAIT_L(n) asm volatile("s_waitcnt lgkmcnt(" #n ")" ::: "memory")
; #define PG8_BAR __builtin_amdgcn_s_barrier()
; #define PG8_SCHED __builtin_amdgcn_sched_barrier(0)
; template <class Epi, class AddrA, class AddrB>
; __device__ __forceinline__ void gemm_phase(const Sched S, const int lda, const int ldb, const int K, const AddrA addrA,
;                                            const AddrB addrB, const Epi E) {
;     ...
;       PG8_BAR; PG8_WAIT_L(0); PG8_MMA(1, 0, At, B0); PG8_BAR; PG8_SCHED;
;       PG8_STAGE(PG8_SB(1, 1), b3 + hstepB, voffB);
;       PG8_WAIT_V(6); PG8_BAR; PG8_MMA(1, 1, At, B1); PG8_BAR;
;   __device__ __forceinline__ void operator()(EPI_ARGS) const {
;     bf16_t* base = proj + ((size_t)u.pn * MTOK + (size_t)(u.pm * 256 + wr * 64 + fr)) * PLD + wc * 32 + 8 * fq;
; #pragma unroll
;     for (int ai = 0; ai < 2; ++ai)
; #pragma unroll
;       for (int m = 0; m < 4; ++m) {
;         bf16_t* rowp = base + (size_t)(ai * HALF + m * 16) * PLD;
; #pragma unroll
;         for (int bj = 0; bj < 2; ++bj) {
;           const f32x4 v0 = acc[ai][bj][m][0], v1 = acc[ai][bj][m][1];
;           u32x4 o;
;           o.x = pack2(v0[0], v0[1]); o.y = pack2(v0[2], v0[3]); o.z = pack2(v1[0], v1[1]); o.w = pack2(v1[2], v1[3]);
;           *(u32x4*)(rowp + bj * HALF) = o;
;         }
	v_mfma_f32_16x16x32_bf16 v[64:67], v[148:151], v[168:171], v[64:67]
	v_mfma_f32_16x16x32_bf16 v[64:67], v[152:155], v[172:175], v[64:67]
	s_waitcnt lgkmcnt(0)
	v_mfma_f32_16x16x32_bf16 v[56:59], v[148:151], v[176:179], v[56:59]
	v_mfma_f32_16x16x32_bf16 v[56:59], v[152:155], v[180:183], v[56:59]
	v_mfma_f32_16x16x32_bf16 v[40:43], v[148:151], v[184:187], v[40:43]
	v_mfma_f32_16x16x32_bf16 v[40:43], v[152:155], v[188:191], v[40:43]
	v_mfma_f32_16x16x32_bf16 v[24:27], v[148:151], v[192:195], v[24:27]
	v_mfma_f32_16x16x32_bf16 v[24:27], v[152:155], v[212:215], v[24:27]
	v_mfma_f32_16x16x32_bf16 v[60:63], v[156:159], v[168:171], v[60:63]
	v_mfma_f32_16x16x32_bf16 v[60:63], v[160:163], v[172:175], v[60:63]
	v_mfma_f32_16x16x32_bf16 v[48:51], v[156:159], v[176:179], v[48:51]
	v_mfma_f32_16x16x32_bf16 v[48:51], v[160:163], v[180:183], v[48:51]
	v_mfma_f32_16x16x32_bf16 v[32:35], v[156:159], v[184:187], v[32:35]
	v_mfma_f32_16x16x32_bf16 v[32:35], v[160:163], v[188:191], v[32:35]
	v_mfma_f32_16x16x32_bf16 v[16:19], v[156:159], v[192:195], v[16:19]
	v_mfma_f32_16x16x32_bf16 v[16:19], v[160:163], v[212:215], v[16:19]
	s_barrier
	s_setprio 0
	s_add_u32 s14, s14, 0x80080
	s_addc_u32 s15, s15, 0
	s_add_i32 s16, s16, s19
	s_mov_b32 m0, s16
	s_nop 0
	global_load_lds_dwordx4 v134, s[14:15]
	s_add_i32 m0, s16, 0x2000
	s_nop 0
	global_load_lds_dwordx4 v0, s[14:15]
	s_add_i32 s39, s39, 2
	s_add_u32 s37, s37, 0x100
	s_addc_u32 s38, s38, 0
	s_add_u32 s12, s12, 0x100
	s_addc_u32 s13, s13, 0
	s_waitcnt vmcnt(8)
	s_setprio 1
	s_barrier
	v_mfma_f32_16x16x32_bf16 v[52:55], v[216:219], v[168:171], v[52:55]
	v_mfma_f32_16x16x32_bf16 v[52:55], v[220:223], v[172:175], v[52:55]
	v_mfma_f32_16x16x32_bf16 v[36:39], v[216:219], v[176:179], v[36:39]
	v_mfma_f32_16x16x32_bf16 v[36:39], v[220:223], v[180:183], v[36:39]
	v_mfma_f32_16x16x32_bf16 v[20:23], v[216:219], v[184:187], v[20:23]
	v_mfma_f32_16x16x32_bf16 v[20:23], v[220:223], v[188:191], v[20:23]
	v_mfma_f32_16x16x32_bf16 v[8:11], v[216:219], v[192:195], v[8:11]
	v_mfma_f32_16x16x32_bf16 v[8:11], v[220:223], v[212:215], v[8:11]
	v_mfma_f32_16x16x32_bf16 v[44:47], v[224:227], v[168:171], v[44:47]
	v_mfma_f32_16x16x32_bf16 v[44:47], v[228:231], v[172:175], v[44:47]
	v_mfma_f32_16x16x32_bf16 v[28:31], v[224:227], v[176:179], v[28:31]
	v_mfma_f32_16x16x32_bf16 v[28:31], v[228:231], v[180:183], v[28:31]
	v_mfma_f32_16x16x32_bf16 v[12:15], v[224:227], v[184:187], v[12:15]
	v_mfma_f32_16x16x32_bf16 v[12:15], v[228:231], v[188:191], v[12:15]
	v_mfma_f32_16x16x32_bf16 v[4:7], v[224:227], v[192:195], v[4:7]
	v_mfma_f32_16x16x32_bf16 v[4:7], v[228:231], v[212:215], v[4:7]
	s_barrier
	s_setprio 0
	s_cmp_gt_u32 s39, 29
	s_cbranch_scc0 .LBB0_109
	s_ashr_i32 s11, s10, 31
	v_lshl_add_u32 v142, s35, 8, v144
	s_lshl_b64 s[10:11], s[10:11], 23
	v_ashrrev_i32_e32 v143, 31, v142
	s_add_u32 s10, s28, s10
	s_addc_u32 s11, s29, s11
	v_lshlrev_b64 v[142:143], 9, v[142:143]
	v_lshl_add_u64 v[142:143], s[10:11], 0, v[142:143]
	v_lshl_add_u64 v[142:143], v[142:143], 0, s[72:73]
	v_lshl_add_u64 v[142:143], v[142:143], 0, v[2:3]
	v_cvt_pk_bf16_f32 v116, v116, v117
	v_cvt_pk_bf16_f32 v117, v118, v119
	v_cvt_pk_bf16_f32 v119, v110, v111
	v_cvt_pk_bf16_f32 v110, v112, v113
	v_add_co_u32_e32 v112, vcc, s96, v142
	s_movk_i32 s1, 0x4000
	s_nop 0
	v_addc_co_u32_e32 v113, vcc, 0, v143, vcc
	v_cvt_pk_bf16_f32 v100, v100, v101
	v_cvt_pk_bf16_f32 v101, v102, v103
	v_cvt_pk_bf16_f32 v103, v94, v95
	v_cvt_pk_bf16_f32 v94, v96, v97
	v_add_co_u32_e32 v96, vcc, s1, v142
	s_movk_i32 s1, 0x6000
	s_nop 0
	v_addc_co_u32_e32 v97, vcc, 0, v143, vcc
	v_cvt_pk_bf16_f32 v84, v84, v85
	v_cvt_pk_bf16_f32 v85, v86, v87
	v_cvt_pk_bf16_f32 v87, v78, v79
	v_cvt_pk_bf16_f32 v78, v80, v81
	v_add_co_u32_e32 v80, vcc, s1, v142
	v_cvt_pk_bf16_f32 v64, v64, v65
	v_cvt_pk_bf16_f32 v65, v66, v67
	v_cvt_pk_bf16_f32 v66, v60, v61
	s_mov_b32 s1, 0x12000
	s_nop 0
	v_addc_co_u32_e32 v81, vcc, 0, v143, vcc
	v_add_co_u32_e32 v60, vcc, s67, v142
	v_cvt_pk_bf16_f32 v52, v52, v53
	v_cvt_pk_bf16_f32 v53, v54, v55
	v_cvt_pk_bf16_f32 v55, v46, v47
	v_cvt_pk_bf16_f32 v46, v48, v49
	s_nop 1
	v_addc_co_u32_e32 v61, vcc, 0, v143, vcc
	v_add_co_u32_e32 v48, vcc, s1, v142
	s_mov_b32 s1, 0x14000
	s_nop 0
	v_addc_co_u32_e32 v49, vcc, 0, v143, vcc
	v_cvt_pk_bf16_f32 v36, v36, v37
	v_cvt_pk_bf16_f32 v37, v38, v39
	v_cvt_pk_bf16_f32 v39, v30, v31
	v_cvt_pk_bf16_f32 v30, v32, v33
	v_add_co_u32_e32 v32, vcc, s1, v142
	s_mov_b32 s1, 0x16000
	s_nop 0
	v_addc_co_u32_e32 v33, vcc, 0, v143, vcc
	v_cvt_pk_bf16_f32 v20, v20, v21
	v_cvt_pk_bf16_f32 v21, v22, v23
	v_cvt_pk_bf16_f32 v23, v14, v15
	v_cvt_pk_bf16_f32 v14, v16, v17
	v_add_co_u32_e32 v16, vcc, s1, v142
	s_mov_b32 s10, s2
	s_nop 0
	v_addc_co_u32_e32 v17, vcc, 0, v143, vcc
	s_and_b64 vcc, exec, s[4:5]
	s_mov_b32 s35, s0
	s_mov_b64 s[12:13], s[8:9]
	s_mov_b64 s[14:15], s[6:7]
	v_cvt_pk_bf16_f32 v128, v128, v129
	v_cvt_pk_bf16_f32 v129, v130, v131
	v_cvt_pk_bf16_f32 v130, v124, v125
	v_cvt_pk_bf16_f32 v131, v126, v127
	flat_store_dwordx4 v[142:143], v[128:131]
	v_cvt_pk_bf16_f32 v118, v108, v109
	flat_store_dwordx4 v[142:143], v[116:119] offset:256
	v_cvt_pk_bf16_f32 v108, v120, v121
	v_cvt_pk_bf16_f32 v109, v122, v123
	v_cvt_pk_bf16_f32 v111, v114, v115
	flat_store_dwordx4 v[112:113], v[108:111]
	v_cvt_pk_bf16_f32 v102, v92, v93
	flat_store_dwordx4 v[112:113], v[100:103] offset:256
	v_cvt_pk_bf16_f32 v92, v104, v105
	v_cvt_pk_bf16_f32 v93, v106, v107
	v_cvt_pk_bf16_f32 v95, v98, v99
	flat_store_dwordx4 v[96:97], v[92:95]
	v_cvt_pk_bf16_f32 v86, v76, v77
	flat_store_dwordx4 v[96:97], v[84:87] offset:256
	v_cvt_pk_bf16_f32 v76, v88, v89
	v_cvt_pk_bf16_f32 v77, v90, v91
	v_cvt_pk_bf16_f32 v79, v82, v83
	flat_store_dwordx4 v[80:81], v[76:79]
	v_cvt_pk_bf16_f32 v72, v72, v73
	v_cvt_pk_bf16_f32 v73, v74, v75
	v_cvt_pk_bf16_f32 v74, v68, v69
	v_cvt_pk_bf16_f32 v75, v70, v71
	flat_store_dwordx4 v[80:81], v[72:75] offset:256
	v_cvt_pk_bf16_f32 v67, v62, v63
	flat_store_dwordx4 v[60:61], v[64:67]
	v_cvt_pk_bf16_f32 v54, v44, v45
	flat_store_dwordx4 v[60:61], v[52:55] offset:256
	v_cvt_pk_bf16_f32 v44, v56, v57
	v_cvt_pk_bf16_f32 v45, v58, v59
	v_cvt_pk_bf16_f32 v47, v50, v51
	flat_store_dwordx4 v[48:49], v[44:47]
	v_cvt_pk_bf16_f32 v38, v28, v29
	flat_store_dwordx4 v[48:49], v[36:39] offset:256
	v_cvt_pk_bf16_f32 v28, v40, v41
	v_cvt_pk_bf16_f32 v29, v42, v43
	v_cvt_pk_bf16_f32 v31, v34, v35
	flat_store_dwordx4 v[32:33], v[28:31]
	v_cvt_pk_bf16_f32 v22, v12, v13
	flat_store_dwordx4 v[32:33], v[20:23] offset:256
	v_cvt_pk_bf16_f32 v12, v24, v25
	v_cvt_pk_bf16_f32 v13, v26, v27
	v_cvt_pk_bf16_f32 v15, v18, v19
	flat_store_dwordx4 v[16:17], v[12:15]
	v_cvt_pk_bf16_f32 v8, v8, v9
	v_cvt_pk_bf16_f32 v9, v10, v11
	v_cvt_pk_bf16_f32 v10, v4, v5
	v_cvt_pk_bf16_f32 v11, v6, v7
	flat_store_dwordx4 v[16:17], v[8:11] offset:256
	s_cbranch_vccz .LBB0_106
	s_waitcnt vmcnt(0)
	s_cmpk_gt_u32 s18, 0xff
	s_cbranch_scc1 .LBB0_113
	s_barrier

; #define PG8_WAIT_V(n) asm volatile("s_waitcnt vmcnt(" #n ")" ::: "memory")
; #define PG8_WAIT_L(n) asm volatile("s_waitcnt lgkmcnt(" #n ")" ::: "memory")
; #define PG8_BAR __builtin_amdgcn_s_barrier()
; #define PG8_SCHED __builtin_amdgcn_sched_barrier(0)
; template <class Epi, class AddrA, class AddrB>
; __device__ __forceinline__ void gemm_phase(const Sched S, const int lda, const int ldb, const int K, const AddrA addrA,
;                                            const AddrB addrB, const Epi E) {
;     ...
;       PG8_LDB(B0, 0, 0); PG8_SCHED; PG8_LDA(At, 0, 0); PG8_STAGE(PG8_SA(1, 1), a1 + hstepA, voffA);
;       PG8_WAIT_L(8); PG8_BAR; PG8_WAIT_L(0); PG8_MMA(0, 0, At, B0); PG8_BAR; PG8_SCHED;
;       PG8_LDB(B1, 0, 1); PG8_STAGE(PG8_SB(0, 0), b2, voffB);
;       PG8_BAR; PG8_WAIT_L(0); PG8_MMA(0, 1, At, B1); PG8_BAR;
;       PG8_LDA(At, 0, 1); PG8_STAGE(PG8_SA(0, 0), a2, voffA);
;       PG8_BAR; PG8_WAIT_L(0); PG8_MMA(1, 0, At, B0); PG8_BAR; PG8_SCHED;
;       PG8_STAGE(PG8_SB(0, 1), b2 + hstepB, voffB);
;       PG8_WAIT_V(6); PG8_BAR; PG8_MMA(1, 1, At, B1); PG8_BAR;
.LBB0_485:
	s_add_i32 s44, 0, 0x10000
	ds_read_b128 v[92:95], v246
	ds_read_b128 v[100:103], v246 offset:1024
	ds_read_b128 v[132:135], v246 offset:2048
	ds_read_b128 v[144:147], v246 offset:3072
	s_add_i32 m0, s30, 0xc000
	ds_read_b128 v[148:151], v169
	ds_read_b128 v[152:155], v169 offset:1024
	ds_read_b128 v[176:179], v169 offset:2048
	ds_read_b128 v[180:183], v169 offset:3072
	ds_read_b128 v[184:187], v169 offset:4096
	ds_read_b128 v[188:191], v169 offset:5120
	ds_read_b128 v[192:195], v169 offset:6144
	ds_read_b128 v[212:215], v169 offset:7168
	global_load_lds_dwordx4 v172, s[4:5]
	s_add_i32 m0, s30, 0xe000
	s_nop 0
	global_load_lds_dwordx4 v170, s[4:5]
	s_waitcnt lgkmcnt(6)
	s_setprio 1
	s_barrier
	v_mfma_f32_16x16x32_bf16 v[140:143], v[92:95], v[148:151], v[140:143]
	v_mfma_f32_16x16x32_bf16 v[140:143], v[100:103], v[152:155], v[140:143]
	s_waitcnt lgkmcnt(0)
	v_mfma_f32_16x16x32_bf16 v[128:131], v[92:95], v[176:179], v[128:131]
	v_mfma_f32_16x16x32_bf16 v[128:131], v[100:103], v[180:183], v[128:131]
	v_mfma_f32_16x16x32_bf16 v[120:123], v[92:95], v[184:187], v[120:123]
	v_mfma_f32_16x16x32_bf16 v[120:123], v[100:103], v[188:191], v[120:123]
	v_mfma_f32_16x16x32_bf16 v[112:115], v[92:95], v[192:195], v[112:115]
	v_mfma_f32_16x16x32_bf16 v[112:115], v[100:103], v[212:215], v[112:115]
	v_mfma_f32_16x16x32_bf16 v[136:139], v[132:135], v[148:151], v[136:139]
	v_mfma_f32_16x16x32_bf16 v[136:139], v[144:147], v[152:155], v[136:139]
	v_mfma_f32_16x16x32_bf16 v[124:127], v[132:135], v[176:179], v[124:127]
	v_mfma_f32_16x16x32_bf16 v[124:127], v[144:147], v[180:183], v[124:127]
	v_mfma_f32_16x16x32_bf16 v[116:119], v[132:135], v[184:187], v[116:119]
	v_mfma_f32_16x16x32_bf16 v[116:119], v[144:147], v[188:191], v[116:119]
	v_mfma_f32_16x16x32_bf16 v[108:111], v[132:135], v[192:195], v[108:111]
	v_mfma_f32_16x16x32_bf16 v[108:111], v[144:147], v[212:215], v[108:111]
	s_barrier
	s_setprio 0
	s_add_u32 s6, s4, 0xfff80080
	s_addc_u32 s7, s5, -1
	s_cmp_eq_u32 s43, 4
	s_cselect_b32 s11, s3, s7
	s_cselect_b32 s10, s15, s6
	s_cselect_b32 s7, s17, s42
	s_cselect_b32 s6, s40, s41
	s_add_i32 s46, 0, 0x14000
	s_add_i32 s44, s44, s29
	s_add_u32 s98, s6, 0x80
	s_addc_u32 s99, s7, 0
	s_mov_b32 m0, s44
	ds_read_b128 v[216:219], v246 offset:16384
	ds_read_b128 v[220:223], v246 offset:17408
	ds_read_b128 v[224:227], v246 offset:18432
	ds_read_b128 v[228:231], v246 offset:19456
	global_load_lds_dwordx4 v158, s[6:7]
	s_add_i32 m0, s44, 0x2000
	s_nop 0
	global_load_lds_dwordx4 v0, s[6:7]
	s_mov_b32 m0, s30
	s_add_u32 s100, s10, 0x80
	s_addc_u32 s101, s11, 0
	s_waitcnt vmcnt(10)
	s_waitcnt lgkmcnt(2)
	s_setprio 1
	s_barrier
	v_mfma_f32_16x16x32_bf16 v[64:67], v[216:219], v[148:151], v[64:67]
	v_mfma_f32_16x16x32_bf16 v[64:67], v[220:223], v[152:155], v[64:67]
	s_waitcnt lgkmcnt(0)
	v_mfma_f32_16x16x32_bf16 v[56:59], v[216:219], v[176:179], v[56:59]
	v_mfma_f32_16x16x32_bf16 v[56:59], v[220:223], v[180:183], v[56:59]
	v_mfma_f32_16x16x32_bf16 v[48:51], v[216:219], v[184:187], v[48:51]
	v_mfma_f32_16x16x32_bf16 v[48:51], v[220:223], v[188:191], v[48:51]
	v_mfma_f32_16x16x32_bf16 v[40:43], v[216:219], v[192:195], v[40:43]
	v_mfma_f32_16x16x32_bf16 v[40:43], v[220:223], v[212:215], v[40:43]
	v_mfma_f32_16x16x32_bf16 v[60:63], v[224:227], v[148:151], v[60:63]
	v_mfma_f32_16x16x32_bf16 v[60:63], v[228:231], v[152:155], v[60:63]
	v_mfma_f32_16x16x32_bf16 v[52:55], v[224:227], v[176:179], v[52:55]
	v_mfma_f32_16x16x32_bf16 v[52:55], v[228:231], v[180:183], v[52:55]
	v_mfma_f32_16x16x32_bf16 v[44:47], v[224:227], v[184:187], v[44:47]
	v_mfma_f32_16x16x32_bf16 v[44:47], v[228:231], v[188:191], v[44:47]
	v_mfma_f32_16x16x32_bf16 v[36:39], v[224:227], v[192:195], v[36:39]
	v_mfma_f32_16x16x32_bf16 v[36:39], v[228:231], v[212:215], v[36:39]
	s_barrier
	s_setprio 0
	ds_read_b128 v[148:151], v169 offset:16384
	ds_read_b128 v[152:155], v169 offset:17408
	ds_read_b128 v[176:179], v169 offset:18432
	ds_read_b128 v[180:183], v169 offset:19456
	ds_read_b128 v[184:187], v169 offset:20480
	ds_read_b128 v[188:191], v169 offset:21504
	ds_read_b128 v[192:195], v169 offset:22528
	ds_read_b128 v[212:215], v169 offset:23552
	global_load_lds_dwordx4 v160, s[10:11]
	s_mov_b32 m0, s31
	s_nop 0
	global_load_lds_dwordx4 v156, s[10:11]
	s_waitcnt lgkmcnt(6)
	s_setprio 1
	s_barrier
	v_mfma_f32_16x16x32_bf16 v[104:107], v[92:95], v[148:151], v[104:107]
	v_mfma_f32_16x16x32_bf16 v[104:107], v[100:103], v[152:155], v[104:107]
	s_waitcnt lgkmcnt(0)
	v_mfma_f32_16x16x32_bf16 v[88:91], v[92:95], v[176:179], v[88:91]
	v_mfma_f32_16x16x32_bf16 v[88:91], v[100:103], v[180:183], v[88:91]
	v_mfma_f32_16x16x32_bf16 v[80:83], v[92:95], v[184:187], v[80:83]
	v_mfma_f32_16x16x32_bf16 v[80:83], v[100:103], v[188:191], v[80:83]
	v_mfma_f32_16x16x32_bf16 v[72:75], v[92:95], v[192:195], v[72:75]
	v_mfma_f32_16x16x32_bf16 v[72:75], v[100:103], v[212:215], v[72:75]
	v_mfma_f32_16x16x32_bf16 v[96:99], v[132:135], v[148:151], v[96:99]
	v_mfma_f32_16x16x32_bf16 v[96:99], v[144:147], v[152:155], v[96:99]
	v_mfma_f32_16x16x32_bf16 v[84:87], v[132:135], v[176:179], v[84:87]
	v_mfma_f32_16x16x32_bf16 v[84:87], v[144:147], v[180:183], v[84:87]
	v_mfma_f32_16x16x32_bf16 v[76:79], v[132:135], v[184:187], v[76:79]
	v_mfma_f32_16x16x32_bf16 v[76:79], v[144:147], v[188:191], v[76:79]
	v_mfma_f32_16x16x32_bf16 v[68:71], v[132:135], v[192:195], v[68:71]
	v_mfma_f32_16x16x32_bf16 v[68:71], v[144:147], v[212:215], v[68:71]
	s_barrier
	s_setprio 0
	s_add_u32 s44, s6, 0x20000
	s_addc_u32 s45, s7, 0
	s_add_i32 s46, s46, s29
	s_mov_b32 m0, s46
	s_nop 0
	global_load_lds_dwordx4 v158, s[44:45]
	s_add_i32 m0, s46, 0x2000
	s_nop 0
	global_load_lds_dwordx4 v0, s[44:45]
	s_add_i32 s44, 0, 0x18000
	s_waitcnt vmcnt(8)
	s_setprio 1
	s_barrier
; #define PG8_WAIT_V(n) asm volatile("s_waitcnt vmcnt(" #n ")" ::: "memory")
; #define PG8_WAIT_L(n) asm volatile("s_waitcnt lgkmcnt(" #n ")" ::: "memory")
; #define PG8_BAR __builtin_amdgcn_s_barrier()
; #define PG8_SCHED __builtin_amdgcn_sched_barrier(0)
; template <class Epi, class AddrA, class AddrB>
; __device__ __forceinline__ void gemm_phase(const Sched S, const int lda, const int ldb, const int K, const AddrA addrA,
;                                            const AddrB addrB, const Epi E) {
;     ...
;       PG8_WAIT_V(6); PG8_BAR; PG8_MMA(1, 1, At, B1); PG8_BAR;
;       PG8_LDB(B0, 1, 0); PG8_SCHED; PG8_LDA(At, 1, 0); PG8_STAGE(PG8_SA(0, 1), a2 + hstepA, voffA);
;       PG8_WAIT_L(8); PG8_BAR; PG8_WAIT_L(0); PG8_MMA(0, 0, At, B0); PG8_BAR; PG8_SCHED;
;       PG8_LDB(B1, 1, 1); PG8_STAGE(PG8_SB(1, 0), b3, voffB);
;       PG8_BAR; PG8_WAIT_L(0); PG8_MMA(0, 1, At, B1); PG8_BAR;
	v_mfma_f32_16x16x32_bf16 v[32:35], v[216:219], v[148:151], v[32:35]
	v_mfma_f32_16x16x32_bf16 v[32:35], v[220:223], v[152:155], v[32:35]
	v_mfma_f32_16x16x32_bf16 v[24:27], v[216:219], v[176:179], v[24:27]
	v_mfma_f32_16x16x32_bf16 v[24:27], v[220:223], v[180:183], v[24:27]
	v_mfma_f32_16x16x32_bf16 v[16:19], v[216:219], v[184:187], v[16:19]
	v_mfma_f32_16x16x32_bf16 v[16:19], v[220:223], v[188:191], v[16:19]
	v_mfma_f32_16x16x32_bf16 v[8:11], v[216:219], v[192:195], v[8:11]
	v_mfma_f32_16x16x32_bf16 v[8:11], v[220:223], v[212:215], v[8:11]
	v_mfma_f32_16x16x32_bf16 v[28:31], v[224:227], v[148:151], v[28:31]
	v_mfma_f32_16x16x32_bf16 v[28:31], v[228:231], v[152:155], v[28:31]
	v_mfma_f32_16x16x32_bf16 v[20:23], v[224:227], v[176:179], v[20:23]
	v_mfma_f32_16x16x32_bf16 v[20:23], v[228:231], v[180:183], v[20:23]
	v_mfma_f32_16x16x32_bf16 v[12:15], v[224:227], v[184:187], v[12:15]
	v_mfma_f32_16x16x32_bf16 v[12:15], v[228:231], v[188:191], v[12:15]
	v_mfma_f32_16x16x32_bf16 v[4:7], v[224:227], v[192:195], v[4:7]
	v_mfma_f32_16x16x32_bf16 v[4:7], v[228:231], v[212:215], v[4:7]
	s_barrier
	s_setprio 0
	ds_read_b128 v[92:95], v246 offset:32768
	ds_read_b128 v[100:103], v246 offset:33792
	ds_read_b128 v[132:135], v246 offset:34816
	ds_read_b128 v[144:147], v246 offset:35840
	s_add_u32 s10, s10, 0x80000
	s_addc_u32 s11, s11, 0
	s_mov_b32 m0, s34
	ds_read_b128 v[148:151], v169 offset:32768
	ds_read_b128 v[152:155], v169 offset:33792
	ds_read_b128 v[176:179], v169 offset:34816
	ds_read_b128 v[180:183], v169 offset:35840
	ds_read_b128 v[184:187], v169 offset:36864
	ds_read_b128 v[188:191], v169 offset:37888
	ds_read_b128 v[192:195], v169 offset:38912
	ds_read_b128 v[212:215], v169 offset:39936
	global_load_lds_dwordx4 v160, s[10:11]
	s_mov_b32 m0, s35
	s_nop 0
	global_load_lds_dwordx4 v156, s[10:11]
	s_waitcnt lgkmcnt(6)
	s_setprio 1
	s_barrier
	v_mfma_f32_16x16x32_bf16 v[140:143], v[92:95], v[148:151], v[140:143]
	v_mfma_f32_16x16x32_bf16 v[140:143], v[100:103], v[152:155], v[140:143]
	s_waitcnt lgkmcnt(0)
	v_mfma_f32_16x16x32_bf16 v[128:131], v[92:95], v[176:179], v[128:131]
	v_mfma_f32_16x16x32_bf16 v[128:131], v[100:103], v[180:183], v[128:131]
	v_mfma_f32_16x16x32_bf16 v[120:123], v[92:95], v[184:187], v[120:123]
	v_mfma_f32_16x16x32_bf16 v[120:123], v[100:103], v[188:191], v[120:123]
	v_mfma_f32_16x16x32_bf16 v[112:115], v[92:95], v[192:195], v[112:115]
	v_mfma_f32_16x16x32_bf16 v[112:115], v[100:103], v[212:215], v[112:115]
	v_mfma_f32_16x16x32_bf16 v[136:139], v[132:135], v[148:151], v[136:139]
	v_mfma_f32_16x16x32_bf16 v[136:139], v[144:147], v[152:155], v[136:139]
	v_mfma_f32_16x16x32_bf16 v[124:127], v[132:135], v[176:179], v[124:127]
	v_mfma_f32_16x16x32_bf16 v[124:127], v[144:147], v[180:183], v[124:127]
	v_mfma_f32_16x16x32_bf16 v[116:119], v[132:135], v[184:187], v[116:119]
	v_mfma_f32_16x16x32_bf16 v[116:119], v[144:147], v[188:191], v[116:119]
	v_mfma_f32_16x16x32_bf16 v[108:111], v[132:135], v[192:195], v[108:111]
	v_mfma_f32_16x16x32_bf16 v[108:111], v[144:147], v[212:215], v[108:111]
	s_barrier
	s_setprio 0
	s_add_i32 s10, 0, 0x1c000
	s_add_i32 s11, s44, s29
	s_mov_b32 m0, s11
	ds_read_b128 v[216:219], v246 offset:49152
	ds_read_b128 v[220:223], v246 offset:50176
	ds_read_b128 v[224:227], v246 offset:51200
	ds_read_b128 v[228:231], v246 offset:52224
	global_load_lds_dwordx4 v158, s[98:99]
	s_add_i32 m0, s11, 0x2000
	s_nop 0
	global_load_lds_dwordx4 v0, s[98:99]
	s_mov_b32 m0, s37
	s_waitcnt vmcnt(10)
	s_waitcnt lgkmcnt(2)
	s_setprio 1
	s_barrier
	v_mfma_f32_16x16x32_bf16 v[64:67], v[216:219], v[148:151], v[64:67]
	v_mfma_f32_16x16x32_bf16 v[64:67], v[220:223], v[152:155], v[64:67]
	s_waitcnt lgkmcnt(0)
	v_mfma_f32_16x16x32_bf16 v[56:59], v[216:219], v[176:179], v[56:59]
	v_mfma_f32_16x16x32_bf16 v[56:59], v[220:223], v[180:183], v[56:59]
	v_mfma_f32_16x16x32_bf16 v[48:51], v[216:219], v[184:187], v[48:51]
	v_mfma_f32_16x16x32_bf16 v[48:51], v[220:223], v[188:191], v[48:51]
	v_mfma_f32_16x16x32_bf16 v[40:43], v[216:219], v[192:195], v[40:43]
	v_mfma_f32_16x16x32_bf16 v[40:43], v[220:223], v[212:215], v[40:43]
	v_mfma_f32_16x16x32_bf16 v[60:63], v[224:227], v[148:151], v[60:63]
	v_mfma_f32_16x16x32_bf16 v[60:63], v[228:231], v[152:155], v[60:63]
	v_mfma_f32_16x16x32_bf16 v[52:55], v[224:227], v[176:179], v[52:55]
	v_mfma_f32_16x16x32_bf16 v[52:55], v[228:231], v[180:183], v[52:55]
	v_mfma_f32_16x16x32_bf16 v[44:47], v[224:227], v[184:187], v[44:47]
	v_mfma_f32_16x16x32_bf16 v[44:47], v[228:231], v[188:191], v[44:47]
	v_mfma_f32_16x16x32_bf16 v[36:39], v[224:227], v[192:195], v[36:39]
	v_mfma_f32_16x16x32_bf16 v[36:39], v[228:231], v[212:215], v[36:39]
	s_barrier
	s_setprio 0
	ds_read_b128 v[148:151], v169 offset:49152
	ds_read_b128 v[152:155], v169 offset:50176
	ds_read_b128 v[176:179], v169 offset:51200
	ds_read_b128 v[180:183], v169 offset:52224
	ds_read_b128 v[184:187], v169 offset:53248
	ds_read_b128 v[188:191], v169 offset:54272
	ds_read_b128 v[192:195], v169 offset:55296
	ds_read_b128 v[212:215], v169 offset:56320
	global_load_lds_dwordx4 v160, s[100:101]
	s_mov_b32 m0, s38
	s_nop 0
	global_load_lds_dwordx4 v156, s[100:101]
	s_waitcnt lgkmcnt(6)
	s_setprio 1
	s_barrier
; __device__ __forceinline__ size_t pidx(size_t row, int col) { return ((size_t)(col >> 8) * MTOK + row) * PLD + (col & 255); }
; __device__ __forceinline__ float bflo(unsigned v) { return __uint_as_float(v << 16); }
; __device__ __forceinline__ float bfhi(unsigned v) { return __uint_as_float(v & 0xffff0000u); }
; __device__ __forceinline__ float siluf_(float x) { return x * __builtin_amdgcn_rcpf(1.0f + __expf(-x)); }
; #define PG8_WAIT_V(n) asm volatile("s_waitcnt vmcnt(" #n ")" ::: "memory")
; #define PG8_WAIT_L(n) asm volatile("s_waitcnt lgkmcnt(" #n ")" ::: "memory")
; #define PG8_BAR __builtin_amdgcn_s_barrier()
; #define PG8_SCHED __builtin_amdgcn_sched_barrier(0)
; template <class Epi, class AddrA, class AddrB>
; __device__ __forceinline__ void gemm_phase(const Sched S, const int lda, const int ldb, const int K, const AddrA addrA,
;                                            const AddrB addrB, const Epi E) {
;     ...
;       PG8_BAR; PG8_WAIT_L(0); PG8_MMA(1, 0, At, B0); PG8_BAR; PG8_SCHED;
;       PG8_STAGE(PG8_SB(1, 1), b3 + hstepB, voffB);
;       PG8_WAIT_V(6); PG8_BAR; PG8_MMA(1, 1, At, B1); PG8_BAR;
;   __device__ __forceinline__ void operator()(EPI_ARGS) const {
;     const size_t row0 = (size_t)u.pm * 256 + wr * 64 + fr;
;     const int col0 = u.pn * 256 + wc * 32 + 8 * fq;
; #pragma unroll
;     for (int bj = 0; bj < 2; ++bj) {
;       const int c = col0 + bj * HALF;
;       const f32x4 s0 = *(const f32x4*)(psc + c), s1 = *(const f32x4*)(psc + c + 4);
; #pragma unroll
;       for (int ai = 0; ai < 2; ++ai) {
;         u32x4 z[4];
; #pragma unroll
;         for (int m = 0; m < 4; ++m) z[m] = *(const u32x4*)(proj + pidx(row0 + ai * HALF + m * 16, PZ + c));
;         __builtin_amdgcn_sched_barrier(0);
; #pragma unroll
;         for (int m = 0; m < 4; ++m) {
;           const size_t row = row0 + ai * HALF + m * 16;
;           const f32x4 v0 = acc[ai][bj][m][0], v1 = acc[ai][bj][m][1];
;           u32x4 o;
;           o.x = pack2(v0[0] * s0[0] * siluf_(bflo(z[m].x)), v0[1] * s0[1] * siluf_(bfhi(z[m].x)));
;           o.y = pack2(v0[2] * s0[2] * siluf_(bflo(z[m].y)), v0[3] * s0[3] * siluf_(bfhi(z[m].y)));
;           o.z = pack2(v1[0] * s1[0] * siluf_(bflo(z[m].z)), v1[1] * s1[1] * siluf_(bfhi(z[m].z)));
;           o.w = pack2(v1[2] * s1[2] * siluf_(bflo(z[m].w)), v1[3] * s1[3] * siluf_(bfhi(z[m].w)));
	v_mfma_f32_16x16x32_bf16 v[104:107], v[92:95], v[148:151], v[104:107]
	v_mfma_f32_16x16x32_bf16 v[104:107], v[100:103], v[152:155], v[104:107]
	s_waitcnt lgkmcnt(0)
	v_mfma_f32_16x16x32_bf16 v[88:91], v[92:95], v[176:179], v[88:91]
	v_mfma_f32_16x16x32_bf16 v[88:91], v[100:103], v[180:183], v[88:91]
	v_mfma_f32_16x16x32_bf16 v[80:83], v[92:95], v[184:187], v[80:83]
	v_mfma_f32_16x16x32_bf16 v[80:83], v[100:103], v[188:191], v[80:83]
	v_mfma_f32_16x16x32_bf16 v[72:75], v[92:95], v[192:195], v[72:75]
	v_mfma_f32_16x16x32_bf16 v[72:75], v[100:103], v[212:215], v[72:75]
	v_mfma_f32_16x16x32_bf16 v[96:99], v[132:135], v[148:151], v[96:99]
	v_mfma_f32_16x16x32_bf16 v[96:99], v[144:147], v[152:155], v[96:99]
	v_mfma_f32_16x16x32_bf16 v[84:87], v[132:135], v[176:179], v[84:87]
	v_mfma_f32_16x16x32_bf16 v[84:87], v[144:147], v[180:183], v[84:87]
	v_mfma_f32_16x16x32_bf16 v[76:79], v[132:135], v[184:187], v[76:79]
	v_mfma_f32_16x16x32_bf16 v[76:79], v[144:147], v[188:191], v[76:79]
	v_mfma_f32_16x16x32_bf16 v[68:71], v[132:135], v[192:195], v[68:71]
	v_mfma_f32_16x16x32_bf16 v[68:71], v[144:147], v[212:215], v[68:71]
	s_barrier
	s_setprio 0
	s_add_u32 s6, s6, 0x20080
	s_addc_u32 s7, s7, 0
	s_add_i32 s10, s10, s29
	s_mov_b32 m0, s10
	s_nop 0
	global_load_lds_dwordx4 v158, s[6:7]
	s_add_i32 m0, s10, 0x2000
	s_nop 0
	global_load_lds_dwordx4 v0, s[6:7]
	s_add_i32 s43, s43, 2
	s_add_u32 s41, s41, 0x100
	s_addc_u32 s42, s42, 0
	s_add_u32 s4, s4, 0x100
	s_addc_u32 s5, s5, 0
	s_waitcnt vmcnt(8)
	s_setprio 1
	s_barrier
	v_mfma_f32_16x16x32_bf16 v[32:35], v[216:219], v[148:151], v[32:35]
	v_mfma_f32_16x16x32_bf16 v[32:35], v[220:223], v[152:155], v[32:35]
	v_mfma_f32_16x16x32_bf16 v[24:27], v[216:219], v[176:179], v[24:27]
	v_mfma_f32_16x16x32_bf16 v[24:27], v[220:223], v[180:183], v[24:27]
	v_mfma_f32_16x16x32_bf16 v[16:19], v[216:219], v[184:187], v[16:19]
	v_mfma_f32_16x16x32_bf16 v[16:19], v[220:223], v[188:191], v[16:19]
	v_mfma_f32_16x16x32_bf16 v[8:11], v[216:219], v[192:195], v[8:11]
	v_mfma_f32_16x16x32_bf16 v[8:11], v[220:223], v[212:215], v[8:11]
	v_mfma_f32_16x16x32_bf16 v[28:31], v[224:227], v[148:151], v[28:31]
	v_mfma_f32_16x16x32_bf16 v[28:31], v[228:231], v[152:155], v[28:31]
	v_mfma_f32_16x16x32_bf16 v[20:23], v[224:227], v[176:179], v[20:23]
	v_mfma_f32_16x16x32_bf16 v[20:23], v[228:231], v[180:183], v[20:23]
	v_mfma_f32_16x16x32_bf16 v[12:15], v[224:227], v[184:187], v[12:15]
	v_mfma_f32_16x16x32_bf16 v[12:15], v[228:231], v[188:191], v[12:15]
	v_mfma_f32_16x16x32_bf16 v[4:7], v[224:227], v[192:195], v[4:7]
	v_mfma_f32_16x16x32_bf16 v[4:7], v[228:231], v[212:215], v[4:7]
	s_barrier
	s_setprio 0
	s_cmp_gt_u32 s43, 5
	s_cbranch_scc0 .LBB0_485
	s_ashr_i32 s3, s2, 31
	s_lshl_b64 s[2:3], s[2:3], 8
	v_lshl_add_u64 v[186:187], s[2:3], 0, v[162:163]
	s_lshl_b32 s2, s33, 8
	v_or_b32_e32 v196, s2, v168
	s_addk_i32 s2, 0x800
	s_ashr_i32 s2, s2, 8
	s_ashr_i32 s3, s2, 31
	s_lshl_b64 s[2:3], s[2:3], 23
	s_add_u32 s2, s0, s2
	s_addc_u32 s3, s1, s3
	v_lshlrev_b32_e32 v2, 1, v168
	v_or_b32_e32 v194, 16, v186
	v_mov_b32_e32 v195, v187
	v_ashrrev_i32_e32 v197, 31, v196
	v_lshl_add_u64 v[188:189], s[2:3], 0, v[2:3]
	v_lshlrev_b64 v[178:179], 9, v[186:187]
	v_lshlrev_b64 v[180:181], 9, v[194:195]
	v_or_b32_e32 v192, 32, v186
	v_mov_b32_e32 v193, v187
	v_or_b32_e32 v190, 48, v186
	v_mov_b32_e32 v191, v187
	v_lshl_add_u64 v[176:177], v[196:197], 2, s[12:13]
	v_lshl_add_u64 v[132:133], v[188:189], 0, v[178:179]
	v_lshl_add_u64 v[134:135], v[188:189], 0, v[180:181]
	v_lshlrev_b64 v[182:183], 9, v[192:193]
	v_lshlrev_b64 v[184:185], 9, v[190:191]
	global_load_dwordx4 v[92:95], v[176:177], off offset:16
	global_load_dwordx4 v[100:103], v[176:177], off
	flat_load_dwordx4 v[152:155], v[132:133]
	flat_load_dwordx4 v[148:151], v[134:135]
	v_lshl_add_u64 v[132:133], v[188:189], 0, v[182:183]
	v_lshl_add_u64 v[134:135], v[188:189], 0, v[184:185]
	flat_load_dwordx4 v[144:147], v[132:133]
	s_nop 0
	flat_load_dwordx4 v[132:135], v[134:135]
	s_waitcnt vmcnt(0) lgkmcnt(0)
	v_lshlrev_b32_e32 v213, 16, v152
	v_mul_f32_e32 v2, 0xbfb8aa3b, v213
	v_exp_f32_e32 v2, v2
	v_mov_b32_e32 v214, v140
	v_mov_b32_e32 v212, v100
	s_mov_b64 s[4:5], 0x90
	v_add_f32_e32 v2, 1.0, v2
	v_rcp_f32_e32 v215, v2
	s_nop 0
	v_pk_mul_f32 v[212:213], v[214:215], v[212:213]
	s_nop 0
	v_mul_f32_e32 v2, v212, v213
	v_and_b32_e32 v213, 0xffff0000, v152
	v_mul_f32_e32 v140, 0xbfb8aa3b, v213
	v_exp_f32_e32 v140, v140
	v_mov_b32_e32 v214, v141
	v_mov_b32_e32 v212, v101
	v_add_f32_e32 v140, 1.0, v140
	v_rcp_f32_e32 v215, v140
	s_nop 0
	v_pk_mul_f32 v[140:141], v[214:215], v[212:213]
	s_nop 0
	v_mul_f32_e32 v140, v140, v141
	v_lshlrev_b32_e32 v141, 16, v153
	v_cvt_pk_bf16_f32 v152, v2, v140
	v_mul_f32_e32 v2, 0xbfb8aa3b, v141
	v_exp_f32_e32 v2, v2
	v_mov_b32_e32 v212, v142
	v_mov_b32_e32 v140, v102
	v_mov_b32_e32 v142, v136
	v_add_f32_e32 v2, 1.0, v2
	v_rcp_f32_e32 v213, v2
	s_nop 0
	v_pk_mul_f32 v[140:141], v[212:213], v[140:141]
	s_nop 0
	v_mul_f32_e32 v2, v140, v141
	v_and_b32_e32 v141, 0xffff0000, v153
	v_mul_f32_e32 v140, 0xbfb8aa3b, v141
	v_exp_f32_e32 v140, v140
	v_mov_b32_e32 v212, v143
	v_add_f32_e32 v140, 1.0, v140
	v_rcp_f32_e32 v213, v140
	v_mov_b32_e32 v140, v103
	v_pk_mul_f32 v[140:141], v[212:213], v[140:141]
	s_nop 0
	v_mul_f32_e32 v140, v140, v141
	v_lshlrev_b32_e32 v141, 16, v154
	v_cvt_pk_bf16_f32 v153, v2, v140
	v_mul_f32_e32 v2, 0xbfb8aa3b, v141
	v_exp_f32_e32 v2, v2
	v_mov_b32_e32 v140, v92
	v_add_f32_e32 v2, 1.0, v2
	v_rcp_f32_e32 v143, v2
	s_nop 0
	v_pk_mul_f32 v[140:141], v[142:143], v[140:141]
	s_nop 0
	v_mul_f32_e32 v2, v140, v141
	v_and_b32_e32 v141, 0xffff0000, v154
; __device__ __forceinline__ size_t pidx(size_t row, int col) { return ((size_t)(col >> 8) * MTOK + row) * PLD + (col & 255); }
; __device__ __forceinline__ float bflo(unsigned v) { return __uint_as_float(v << 16); }
; __device__ __forceinline__ float bfhi(unsigned v) { return __uint_as_float(v & 0xffff0000u); }
; __device__ __forceinline__ float siluf_(float x) { return x * __builtin_amdgcn_rcpf(1.0f + __expf(-x)); }
;   __device__ __forceinline__ void operator()(EPI_ARGS) const {
;     const size_t row0 = (size_t)u.pm * 256 + wr * 64 + fr;
;     const int col0 = u.pn * 256 + wc * 32 + 8 * fq;
; #pragma unroll
;     for (int bj = 0; bj < 2; ++bj) {
;       const int c = col0 + bj * HALF;
;       const f32x4 s0 = *(const f32x4*)(psc + c), s1 = *(const f32x4*)(psc + c + 4);
; #pragma unroll
;       for (int ai = 0; ai < 2; ++ai) {
;         u32x4 z[4];
; #pragma unroll
;         for (int m = 0; m < 4; ++m) z[m] = *(const u32x4*)(proj + pidx(row0 + ai * HALF + m * 16, PZ + c));
;         __builtin_amdgcn_sched_barrier(0);
; #pragma unroll
;         for (int m = 0; m < 4; ++m) {
;           const size_t row = row0 + ai * HALF + m * 16;
;           const f32x4 v0 = acc[ai][bj][m][0], v1 = acc[ai][bj][m][1];
;           u32x4 o;
;           o.x = pack2(v0[0] * s0[0] * siluf_(bflo(z[m].x)), v0[1] * s0[1] * siluf_(bfhi(z[m].x)));
;           o.y = pack2(v0[2] * s0[2] * siluf_(bflo(z[m].y)), v0[3] * s0[3] * siluf_(bfhi(z[m].y)));
;           o.z = pack2(v1[0] * s1[0] * siluf_(bflo(z[m].z)), v1[1] * s1[1] * siluf_(bfhi(z[m].z)));
;           o.w = pack2(v1[2] * s1[2] * siluf_(bflo(z[m].w)), v1[3] * s1[3] * siluf_(bfhi(z[m].w)));
;           *(u32x4*)(y0 + row * DM + c) = o;
;         }
;       }
;     }
;   }
	v_mul_f32_e32 v136, 0xbfb8aa3b, v141
	v_exp_f32_e32 v136, v136
	v_mov_b32_e32 v142, v137
	v_mov_b32_e32 v140, v93
	v_add_f32_e32 v136, 1.0, v136
	v_rcp_f32_e32 v143, v136
	s_nop 0
	v_pk_mul_f32 v[136:137], v[142:143], v[140:141]
	s_nop 0
	v_mul_f32_e32 v136, v136, v137
	v_lshlrev_b32_e32 v137, 16, v155
	v_cvt_pk_bf16_f32 v154, v2, v136
	v_mul_f32_e32 v2, 0xbfb8aa3b, v137
	v_exp_f32_e32 v2, v2
	v_mov_b32_e32 v140, v138
	v_mov_b32_e32 v136, v94
	v_mov_b32_e32 v142, v128
	v_add_f32_e32 v2, 1.0, v2
	v_rcp_f32_e32 v141, v2
	v_mov_b32_e32 v138, v100
	v_pk_mul_f32 v[136:137], v[140:141], v[136:137]
	s_nop 0
	v_mul_f32_e32 v2, v136, v137
	v_and_b32_e32 v137, 0xffff0000, v155
	v_mul_f32_e32 v136, 0xbfb8aa3b, v137
	v_exp_f32_e32 v136, v136
	v_mov_b32_e32 v140, v139
	v_lshlrev_b32_e32 v139, 16, v148
	v_add_f32_e32 v136, 1.0, v136
	v_rcp_f32_e32 v141, v136
	v_mov_b32_e32 v136, v95
	v_pk_mul_f32 v[136:137], v[140:141], v[136:137]
	s_nop 0
	v_mul_f32_e32 v136, v136, v137
	v_cvt_pk_bf16_f32 v155, v2, v136
	v_mul_f32_e32 v2, 0xbfb8aa3b, v139
	v_exp_f32_e32 v2, v2
	v_lshlrev_b64 v[140:141], 1, v[196:197]
	v_lshlrev_b64 v[136:137], 12, v[186:187]
	v_lshl_add_u64 v[136:137], s[8:9], 0, v[136:137]
	v_add_f32_e32 v2, 1.0, v2
	v_rcp_f32_e32 v143, v2
	v_lshl_add_u64 v[136:137], v[136:137], 0, v[140:141]
	flat_store_dwordx4 v[136:137], v[152:155]
	v_pk_mul_f32 v[138:139], v[142:143], v[138:139]
	s_nop 0
	v_mul_f32_e32 v2, v138, v139
	v_and_b32_e32 v139, 0xffff0000, v148
	v_mul_f32_e32 v128, 0xbfb8aa3b, v139
	v_exp_f32_e32 v128, v128
	v_mov_b32_e32 v142, v129
	v_mov_b32_e32 v138, v101
	v_add_f32_e32 v128, 1.0, v128
	v_rcp_f32_e32 v143, v128
	s_nop 0
	v_pk_mul_f32 v[128:129], v[142:143], v[138:139]
	s_nop 0
	v_mul_f32_e32 v128, v128, v129
	v_lshlrev_b32_e32 v139, 16, v149
	v_cvt_pk_bf16_f32 v128, v2, v128
	v_mul_f32_e32 v2, 0xbfb8aa3b, v139
	v_exp_f32_e32 v2, v2
	v_mov_b32_e32 v142, v130
	v_mov_b32_e32 v138, v102
	v_add_f32_e32 v2, 1.0, v2
	v_rcp_f32_e32 v143, v2
	s_nop 0
	v_pk_mul_f32 v[138:139], v[142:143], v[138:139]
	s_nop 0
	v_mul_f32_e32 v2, v138, v139
	v_and_b32_e32 v139, 0xffff0000, v149
	v_mul_f32_e32 v129, 0xbfb8aa3b, v139
	v_exp_f32_e32 v129, v129
	v_mov_b32_e32 v142, v131
	v_mov_b32_e32 v138, v103
	v_lshl_add_u64 v[148:149], v[186:187], 0, s[52:53]
	v_add_f32_e32 v129, 1.0, v129
	v_rcp_f32_e32 v143, v129
	s_nop 0
	v_pk_mul_f32 v[130:131], v[142:143], v[138:139]
	s_nop 0
	v_mul_f32_e32 v129, v130, v131
	v_lshlrev_b32_e32 v131, 16, v150
	v_cvt_pk_bf16_f32 v129, v2, v129
	v_mul_f32_e32 v2, 0xbfb8aa3b, v131
	v_exp_f32_e32 v2, v2
	v_mov_b32_e32 v138, v124
	v_mov_b32_e32 v130, v92
	v_add_f32_e32 v2, 1.0, v2
	v_rcp_f32_e32 v139, v2
	s_nop 0
	v_pk_mul_f32 v[130:131], v[138:139], v[130:131]
	s_nop 0
	v_mul_f32_e32 v2, v130, v131
	v_and_b32_e32 v131, 0xffff0000, v150
	v_mul_f32_e32 v124, 0xbfb8aa3b, v131
	v_exp_f32_e32 v124, v124
	v_mov_b32_e32 v138, v125
	v_mov_b32_e32 v130, v93
	v_add_f32_e32 v124, 1.0, v124
	v_rcp_f32_e32 v139, v124
	s_nop 0
	v_pk_mul_f32 v[124:125], v[138:139], v[130:131]
	s_nop 0
	v_mul_f32_e32 v124, v124, v125
	v_lshlrev_b32_e32 v125, 16, v151
	v_cvt_pk_bf16_f32 v130, v2, v124
	v_mul_f32_e32 v2, 0xbfb8aa3b, v125
	v_exp_f32_e32 v2, v2
	v_mov_b32_e32 v138, v126
	v_mov_b32_e32 v124, v94
	v_mov_b32_e32 v126, v100
	v_add_f32_e32 v2, 1.0, v2
	v_rcp_f32_e32 v139, v2
	s_nop 0
	v_pk_mul_f32 v[124:125], v[138:139], v[124:125]
	s_nop 0
	v_mul_f32_e32 v2, v124, v125
	v_and_b32_e32 v125, 0xffff0000, v151
	v_mul_f32_e32 v124, 0xbfb8aa3b, v125
	v_exp_f32_e32 v124, v124
	v_mov_b32_e32 v138, v127
	v_lshlrev_b32_e32 v127, 16, v144
	v_add_f32_e32 v124, 1.0, v124
	v_rcp_f32_e32 v139, v124
	v_mov_b32_e32 v124, v95
	v_pk_mul_f32 v[124:125], v[138:139], v[124:125]
	s_nop 0
	v_mul_f32_e32 v124, v124, v125
	v_cvt_pk_bf16_f32 v131, v2, v124
	v_mul_f32_e32 v2, 0xbfb8aa3b, v127
	v_exp_f32_e32 v2, v2
	v_lshlrev_b64 v[124:125], 12, v[194:195]
	v_lshl_add_u64 v[124:125], s[8:9], 0, v[124:125]
	v_lshl_add_u64 v[124:125], v[124:125], 0, v[140:141]
	v_add_f32_e32 v2, 1.0, v2
	flat_store_dwordx4 v[124:125], v[128:131]
	s_nop 1
	v_rcp_f32_e32 v129, v2
	v_mov_b32_e32 v128, v120
	v_lshlrev_b64 v[130:131], 9, v[148:149]
	v_pk_mul_f32 v[126:127], v[128:129], v[126:127]
	s_nop 0
	v_mul_f32_e32 v2, v126, v127
	v_and_b32_e32 v127, 0xffff0000, v144
	v_mul_f32_e32 v120, 0xbfb8aa3b, v127
	v_exp_f32_e32 v120, v120
	v_mov_b32_e32 v128, v121
	v_mov_b32_e32 v126, v101
	v_add_f32_e32 v120, 1.0, v120
	v_rcp_f32_e32 v129, v120
	s_nop 0
	v_pk_mul_f32 v[120:121], v[128:129], v[126:127]
	s_nop 0
	v_mul_f32_e32 v120, v120, v121
	v_lshlrev_b32_e32 v127, 16, v145
	v_cvt_pk_bf16_f32 v120, v2, v120
	v_mul_f32_e32 v2, 0xbfb8aa3b, v127
	v_exp_f32_e32 v2, v2
	v_mov_b32_e32 v128, v122
	v_mov_b32_e32 v126, v102
	v_add_f32_e32 v2, 1.0, v2
	v_rcp_f32_e32 v129, v2
	s_nop 0
	v_pk_mul_f32 v[126:127], v[128:129], v[126:127]
	s_nop 0
	v_mul_f32_e32 v2, v126, v127
	v_and_b32_e32 v127, 0xffff0000, v145
	v_mul_f32_e32 v121, 0xbfb8aa3b, v127
	v_exp_f32_e32 v121, v121
	v_mov_b32_e32 v128, v123
	v_mov_b32_e32 v126, v103
	v_add_f32_e32 v121, 1.0, v121
	v_rcp_f32_e32 v129, v121
	s_nop 0
	v_pk_mul_f32 v[122:123], v[128:129], v[126:127]
	s_nop 0
	v_mul_f32_e32 v121, v122, v123
	v_lshlrev_b32_e32 v123, 16, v146
	v_cvt_pk_bf16_f32 v121, v2, v121
	v_mul_f32_e32 v2, 0xbfb8aa3b, v123
	v_exp_f32_e32 v2, v2
	v_mov_b32_e32 v126, v116
	v_mov_b32_e32 v122, v92
	v_add_f32_e32 v2, 1.0, v2
	v_rcp_f32_e32 v127, v2
	s_nop 0
	v_pk_mul_f32 v[122:123], v[126:127], v[122:123]
	s_nop 0
	v_mul_f32_e32 v2, v122, v123
	v_and_b32_e32 v123, 0xffff0000, v146
	v_mul_f32_e32 v116, 0xbfb8aa3b, v123
	v_exp_f32_e32 v116, v116
	v_mov_b32_e32 v126, v117
; __device__ __forceinline__ size_t pidx(size_t row, int col) { return ((size_t)(col >> 8) * MTOK + row) * PLD + (col & 255); }
; __device__ __forceinline__ float bflo(unsigned v) { return __uint_as_float(v << 16); }
; __device__ __forceinline__ float bfhi(unsigned v) { return __uint_as_float(v & 0xffff0000u); }
; __device__ __forceinline__ float siluf_(float x) { return x * __builtin_amdgcn_rcpf(1.0f + __expf(-x)); }
;   __device__ __forceinline__ void operator()(EPI_ARGS) const {
;     const size_t row0 = (size_t)u.pm * 256 + wr * 64 + fr;
;     const int col0 = u.pn * 256 + wc * 32 + 8 * fq;
; #pragma unroll
;     for (int bj = 0; bj < 2; ++bj) {
;       const int c = col0 + bj * HALF;
;       const f32x4 s0 = *(const f32x4*)(psc + c), s1 = *(const f32x4*)(psc + c + 4);
; #pragma unroll
;       for (int ai = 0; ai < 2; ++ai) {
;         u32x4 z[4];
; #pragma unroll
;         for (int m = 0; m < 4; ++m) z[m] = *(const u32x4*)(proj + pidx(row0 + ai * HALF + m * 16, PZ + c));
;         __builtin_amdgcn_sched_barrier(0);
; #pragma unroll
;         for (int m = 0; m < 4; ++m) {
;           const size_t row = row0 + ai * HALF + m * 16;
;           const f32x4 v0 = acc[ai][bj][m][0], v1 = acc[ai][bj][m][1];
;           u32x4 o;
;           o.x = pack2(v0[0] * s0[0] * siluf_(bflo(z[m].x)), v0[1] * s0[1] * siluf_(bfhi(z[m].x)));
;           o.y = pack2(v0[2] * s0[2] * siluf_(bflo(z[m].y)), v0[3] * s0[3] * siluf_(bfhi(z[m].y)));
;           o.z = pack2(v1[0] * s1[0] * siluf_(bflo(z[m].z)), v1[1] * s1[1] * siluf_(bfhi(z[m].z)));
;           o.w = pack2(v1[2] * s1[2] * siluf_(bflo(z[m].w)), v1[3] * s1[3] * siluf_(bfhi(z[m].w)));
;           *(u32x4*)(y0 + row * DM + c) = o;
;         }
;       }
;     }
;   }
	v_mov_b32_e32 v122, v93
	v_add_f32_e32 v116, 1.0, v116
	v_rcp_f32_e32 v127, v116
	s_nop 0
	v_pk_mul_f32 v[116:117], v[126:127], v[122:123]
	s_nop 0
	v_mul_f32_e32 v116, v116, v117
	v_lshlrev_b32_e32 v117, 16, v147
	v_cvt_pk_bf16_f32 v122, v2, v116
	v_mul_f32_e32 v2, 0xbfb8aa3b, v117
	v_exp_f32_e32 v2, v2
	v_mov_b32_e32 v126, v118
	v_mov_b32_e32 v116, v94
	v_mov_b32_e32 v118, v112
	v_add_f32_e32 v2, 1.0, v2
	v_rcp_f32_e32 v127, v2
	s_nop 0
	v_pk_mul_f32 v[116:117], v[126:127], v[116:117]
	s_nop 0
	v_mul_f32_e32 v2, v116, v117
	v_and_b32_e32 v117, 0xffff0000, v147
	v_mul_f32_e32 v116, 0xbfb8aa3b, v117
	v_exp_f32_e32 v116, v116
	v_mov_b32_e32 v126, v119
	v_lshl_add_u64 v[146:147], v[186:187], 0, s[4:5]
	s_mov_b64 s[4:5], 0xa0
	v_add_f32_e32 v116, 1.0, v116
	v_rcp_f32_e32 v127, v116
	v_mov_b32_e32 v116, v95
	v_lshl_add_u64 v[144:145], v[186:187], 0, s[4:5]
	s_mov_b64 s[4:5], 0xb0
	v_pk_mul_f32 v[116:117], v[126:127], v[116:117]
	v_lshl_add_u64 v[142:143], v[186:187], 0, s[4:5]
	v_mul_f32_e32 v116, v116, v117
	v_cvt_pk_bf16_f32 v123, v2, v116
	v_lshlrev_b64 v[116:117], 12, v[192:193]
	v_lshl_add_u64 v[116:117], s[8:9], 0, v[116:117]
	v_lshl_add_u64 v[128:129], v[116:117], 0, v[140:141]
	v_lshlrev_b32_e32 v117, 16, v132
	v_mul_f32_e32 v2, 0xbfb8aa3b, v117
	v_exp_f32_e32 v2, v2
	v_mov_b32_e32 v116, v100
	flat_store_dwordx4 v[128:129], v[120:123]
	v_lshlrev_b64 v[138:139], 9, v[142:143]
	v_add_f32_e32 v2, 1.0, v2
	v_rcp_f32_e32 v119, v2
	s_nop 0
	v_pk_mul_f32 v[116:117], v[118:119], v[116:117]
	s_nop 0
	v_mul_f32_e32 v2, v116, v117
	v_and_b32_e32 v117, 0xffff0000, v132
	v_mul_f32_e32 v112, 0xbfb8aa3b, v117
	v_exp_f32_e32 v112, v112
	v_mov_b32_e32 v118, v113
	v_mov_b32_e32 v116, v101
	v_add_f32_e32 v112, 1.0, v112
	v_rcp_f32_e32 v119, v112
	s_nop 0
	v_pk_mul_f32 v[112:113], v[118:119], v[116:117]
	s_nop 0
	v_mul_f32_e32 v112, v112, v113
	v_lshlrev_b32_e32 v117, 16, v133
	v_cvt_pk_bf16_f32 v112, v2, v112
	v_mul_f32_e32 v2, 0xbfb8aa3b, v117
	v_exp_f32_e32 v2, v2
	v_mov_b32_e32 v118, v114
	v_mov_b32_e32 v116, v102
	v_add_f32_e32 v2, 1.0, v2
	v_rcp_f32_e32 v119, v2
	s_nop 0
	v_pk_mul_f32 v[116:117], v[118:119], v[116:117]
	s_nop 0
	v_mul_f32_e32 v2, v116, v117
	v_and_b32_e32 v117, 0xffff0000, v133
	v_mul_f32_e32 v113, 0xbfb8aa3b, v117
	v_exp_f32_e32 v113, v113
	v_mov_b32_e32 v118, v115
	v_mov_b32_e32 v116, v103
	v_lshlrev_b64 v[132:133], 9, v[146:147]
	v_add_f32_e32 v113, 1.0, v113
	v_rcp_f32_e32 v119, v113
	s_nop 0
	v_pk_mul_f32 v[114:115], v[118:119], v[116:117]
	s_nop 0
	v_mul_f32_e32 v113, v114, v115
	v_lshlrev_b32_e32 v115, 16, v134
	v_cvt_pk_bf16_f32 v113, v2, v113
	v_mul_f32_e32 v2, 0xbfb8aa3b, v115
	v_exp_f32_e32 v2, v2
	v_mov_b32_e32 v116, v108
	v_mov_b32_e32 v114, v92
	v_add_f32_e32 v2, 1.0, v2
	v_rcp_f32_e32 v117, v2
	s_nop 0
	v_pk_mul_f32 v[114:115], v[116:117], v[114:115]
	s_nop 0
	v_mul_f32_e32 v2, v114, v115
	v_and_b32_e32 v115, 0xffff0000, v134
	v_mul_f32_e32 v108, 0xbfb8aa3b, v115
	v_exp_f32_e32 v108, v108
	v_mov_b32_e32 v116, v109
	v_mov_b32_e32 v114, v93
	v_add_f32_e32 v108, 1.0, v108
	v_rcp_f32_e32 v117, v108
	s_nop 0
	v_pk_mul_f32 v[108:109], v[116:117], v[114:115]
	s_nop 0
	v_mul_f32_e32 v108, v108, v109
	v_lshlrev_b32_e32 v109, 16, v135
	v_cvt_pk_bf16_f32 v114, v2, v108
	v_mul_f32_e32 v2, 0xbfb8aa3b, v109
	v_exp_f32_e32 v2, v2
	v_mov_b32_e32 v116, v110
	v_mov_b32_e32 v108, v94
	v_add_f32_e32 v2, 1.0, v2
	v_rcp_f32_e32 v117, v2
	s_nop 0
	v_pk_mul_f32 v[108:109], v[116:117], v[108:109]
	s_nop 0
	v_mul_f32_e32 v2, v108, v109
	v_and_b32_e32 v109, 0xffff0000, v135
	v_mul_f32_e32 v108, 0xbfb8aa3b, v109
	v_exp_f32_e32 v108, v108
	v_mov_b32_e32 v116, v111
	v_lshlrev_b64 v[134:135], 9, v[144:145]
	v_add_f32_e32 v108, 1.0, v108
	v_rcp_f32_e32 v117, v108
	v_mov_b32_e32 v108, v95
	v_pk_mul_f32 v[108:109], v[116:117], v[108:109]
	s_nop 0
	v_mul_f32_e32 v108, v108, v109
	v_cvt_pk_bf16_f32 v115, v2, v108
	v_lshlrev_b64 v[108:109], 12, v[190:191]
	v_lshl_add_u64 v[108:109], s[8:9], 0, v[108:109]
	v_lshl_add_u64 v[126:127], v[108:109], 0, v[140:141]
	flat_store_dwordx4 v[126:127], v[112:115]
	v_lshl_add_u64 v[108:109], v[188:189], 0, v[130:131]
	flat_load_dwordx4 v[120:123], v[108:109]
	v_lshl_add_u64 v[108:109], v[188:189], 0, v[132:133]
	flat_load_dwordx4 v[116:119], v[108:109]
	v_lshl_add_u64 v[108:109], v[188:189], 0, v[134:135]
	flat_load_dwordx4 v[112:115], v[108:109]
	v_lshl_add_u64 v[108:109], v[188:189], 0, v[138:139]
	flat_load_dwordx4 v[108:111], v[108:109]
	s_waitcnt vmcnt(0) lgkmcnt(0)
; __device__ __forceinline__ size_t pidx(size_t row, int col) { return ((size_t)(col >> 8) * MTOK + row) * PLD + (col & 255); }
; __device__ __forceinline__ float bflo(unsigned v) { return __uint_as_float(v << 16); }
; __device__ __forceinline__ float bfhi(unsigned v) { return __uint_as_float(v & 0xffff0000u); }
; __device__ __forceinline__ float siluf_(float x) { return x * __builtin_amdgcn_rcpf(1.0f + __expf(-x)); }
;   __device__ __forceinline__ void operator()(EPI_ARGS) const {
;     const size_t row0 = (size_t)u.pm * 256 + wr * 64 + fr;
;     const int col0 = u.pn * 256 + wc * 32 + 8 * fq;
; #pragma unroll
;     for (int bj = 0; bj < 2; ++bj) {
;       const int c = col0 + bj * HALF;
;       const f32x4 s0 = *(const f32x4*)(psc + c), s1 = *(const f32x4*)(psc + c + 4);
; #pragma unroll
;       for (int ai = 0; ai < 2; ++ai) {
;         u32x4 z[4];
; #pragma unroll
;         for (int m = 0; m < 4; ++m) z[m] = *(const u32x4*)(proj + pidx(row0 + ai * HALF + m * 16, PZ + c));
;         __builtin_amdgcn_sched_barrier(0);
; #pragma unroll
;         for (int m = 0; m < 4; ++m) {
;           const size_t row = row0 + ai * HALF + m * 16;
;           const f32x4 v0 = acc[ai][bj][m][0], v1 = acc[ai][bj][m][1];
;           u32x4 o;
;           o.x = pack2(v0[0] * s0[0] * siluf_(bflo(z[m].x)), v0[1] * s0[1] * siluf_(bfhi(z[m].x)));
;           o.y = pack2(v0[2] * s0[2] * siluf_(bflo(z[m].y)), v0[3] * s0[3] * siluf_(bfhi(z[m].y)));
;           o.z = pack2(v1[0] * s1[0] * siluf_(bflo(z[m].z)), v1[1] * s1[1] * siluf_(bfhi(z[m].z)));
;           o.w = pack2(v1[2] * s1[2] * siluf_(bflo(z[m].w)), v1[3] * s1[3] * siluf_(bfhi(z[m].w)));
;           *(u32x4*)(y0 + row * DM + c) = o;
;         }
;       }
;     }
;   }
	v_lshlrev_b32_e32 v151, 16, v120
	v_mul_f32_e32 v2, 0xbfb8aa3b, v151
	v_exp_f32_e32 v2, v2
	v_mov_b32_e32 v152, v104
	v_mov_b32_e32 v150, v100
	v_mov_b32_e32 v175, v3
	v_add_f32_e32 v2, 1.0, v2
	v_rcp_f32_e32 v153, v2
	s_nop 0
	v_pk_mul_f32 v[150:151], v[152:153], v[150:151]
	s_nop 0
	v_mul_f32_e32 v2, v150, v151
	v_and_b32_e32 v151, 0xffff0000, v120
	v_mul_f32_e32 v104, 0xbfb8aa3b, v151
	v_exp_f32_e32 v104, v104
	v_mov_b32_e32 v152, v105
	v_mov_b32_e32 v150, v101
	v_mov_b32_e32 v120, v103
	v_add_f32_e32 v104, 1.0, v104
	v_rcp_f32_e32 v153, v104
	s_nop 0
	v_pk_mul_f32 v[104:105], v[152:153], v[150:151]
	s_nop 0
	v_mul_f32_e32 v104, v104, v105
	v_lshlrev_b32_e32 v151, 16, v121
	v_cvt_pk_bf16_f32 v104, v2, v104
	v_mul_f32_e32 v2, 0xbfb8aa3b, v151
	v_exp_f32_e32 v2, v2
	v_and_b32_e32 v121, 0xffff0000, v121
	v_mul_f32_e32 v105, 0xbfb8aa3b, v121
	v_exp_f32_e32 v105, v105
	v_add_f32_e32 v2, 1.0, v2
	v_rcp_f32_e32 v153, v2
	v_mov_b32_e32 v152, v106
	v_mov_b32_e32 v150, v102
	v_add_f32_e32 v105, 1.0, v105
	v_pk_mul_f32 v[150:151], v[152:153], v[150:151]
	s_nop 0
	v_mul_f32_e32 v2, v150, v151
	v_rcp_f32_e32 v151, v105
	v_mov_b32_e32 v150, v107
	v_pk_mul_f32 v[106:107], v[150:151], v[120:121]
	s_nop 0
	v_mul_f32_e32 v105, v106, v107
	v_lshlrev_b32_e32 v107, 16, v122
	v_cvt_pk_bf16_f32 v105, v2, v105
	v_mul_f32_e32 v2, 0xbfb8aa3b, v107
	v_exp_f32_e32 v2, v2
	v_mov_b32_e32 v120, v96
	v_mov_b32_e32 v106, v92
	v_add_f32_e32 v2, 1.0, v2
	v_rcp_f32_e32 v121, v2
	s_nop 0
	v_pk_mul_f32 v[106:107], v[120:121], v[106:107]
	s_nop 0
	v_mul_f32_e32 v2, v106, v107
	v_and_b32_e32 v107, 0xffff0000, v122
	v_mul_f32_e32 v96, 0xbfb8aa3b, v107
	v_exp_f32_e32 v96, v96
	v_mov_b32_e32 v120, v97
	v_mov_b32_e32 v106, v93
	v_add_f32_e32 v96, 1.0, v96
	v_rcp_f32_e32 v121, v96
	s_nop 0
	v_pk_mul_f32 v[96:97], v[120:121], v[106:107]
	s_nop 0
	v_mul_f32_e32 v96, v96, v97
	v_lshlrev_b32_e32 v97, 16, v123
	v_cvt_pk_bf16_f32 v106, v2, v96
	v_mul_f32_e32 v2, 0xbfb8aa3b, v97
	v_exp_f32_e32 v2, v2
	v_mov_b32_e32 v120, v98
	v_mov_b32_e32 v96, v94
	v_mov_b32_e32 v98, v100
	v_add_f32_e32 v2, 1.0, v2
	v_rcp_f32_e32 v121, v2
	s_nop 0
	v_pk_mul_f32 v[96:97], v[120:121], v[96:97]
	s_nop 0
	v_mul_f32_e32 v2, v96, v97
	v_and_b32_e32 v97, 0xffff0000, v123
	v_mul_f32_e32 v96, 0xbfb8aa3b, v97
	v_exp_f32_e32 v96, v96
	v_mov_b32_e32 v120, v99
	v_lshlrev_b32_e32 v99, 16, v116
	v_add_f32_e32 v96, 1.0, v96
	v_rcp_f32_e32 v121, v96
	v_mov_b32_e32 v96, v95
	v_pk_mul_f32 v[96:97], v[120:121], v[96:97]
	s_nop 0
	v_mul_f32_e32 v96, v96, v97
	v_cvt_pk_bf16_f32 v107, v2, v96
	v_mul_f32_e32 v2, 0xbfb8aa3b, v99
	v_exp_f32_e32 v2, v2
	v_lshlrev_b64 v[96:97], 12, v[148:149]
	v_lshl_add_u64 v[96:97], s[8:9], 0, v[96:97]
	v_lshl_add_u64 v[96:97], v[96:97], 0, v[140:141]
	v_add_f32_e32 v2, 1.0, v2
	flat_store_dwordx4 v[96:97], v[104:107]
	s_nop 1
	v_rcp_f32_e32 v105, v2
	v_mov_b32_e32 v104, v88
	v_pk_mul_f32 v[98:99], v[104:105], v[98:99]
	s_nop 0
	v_mul_f32_e32 v2, v98, v99
	v_and_b32_e32 v99, 0xffff0000, v116
	v_mul_f32_e32 v88, 0xbfb8aa3b, v99
	v_exp_f32_e32 v88, v88
	v_mov_b32_e32 v104, v89
	v_mov_b32_e32 v98, v101
	v_add_f32_e32 v88, 1.0, v88
	v_rcp_f32_e32 v105, v88
	s_nop 0
	v_pk_mul_f32 v[88:89], v[104:105], v[98:99]
	s_nop 0
	v_mul_f32_e32 v88, v88, v89
	v_lshlrev_b32_e32 v99, 16, v117
	v_cvt_pk_bf16_f32 v88, v2, v88
	v_mul_f32_e32 v2, 0xbfb8aa3b, v99
	v_exp_f32_e32 v2, v2
	v_mov_b32_e32 v104, v90
	v_mov_b32_e32 v98, v102
	v_add_f32_e32 v2, 1.0, v2
	v_rcp_f32_e32 v105, v2
	s_nop 0
	v_pk_mul_f32 v[98:99], v[104:105], v[98:99]
	s_nop 0
	v_mul_f32_e32 v2, v98, v99
	v_and_b32_e32 v99, 0xffff0000, v117
	v_mul_f32_e32 v89, 0xbfb8aa3b, v99
	v_exp_f32_e32 v89, v89
	v_mov_b32_e32 v104, v91
	v_mov_b32_e32 v98, v103
	v_add_f32_e32 v89, 1.0, v89
	v_rcp_f32_e32 v105, v89
	s_nop 0
	v_pk_mul_f32 v[90:91], v[104:105], v[98:99]
	s_nop 0
	v_mul_f32_e32 v89, v90, v91
	v_lshlrev_b32_e32 v91, 16, v118
	v_cvt_pk_bf16_f32 v89, v2, v89
	v_mul_f32_e32 v2, 0xbfb8aa3b, v91
	v_exp_f32_e32 v2, v2
	v_mov_b32_e32 v98, v84
	v_mov_b32_e32 v90, v92
	v_add_f32_e32 v2, 1.0, v2
	v_rcp_f32_e32 v99, v2
	s_nop 0
	v_pk_mul_f32 v[90:91], v[98:99], v[90:91]
	s_nop 0
	v_mul_f32_e32 v2, v90, v91
	v_and_b32_e32 v91, 0xffff0000, v118
	v_mul_f32_e32 v84, 0xbfb8aa3b, v91
	v_exp_f32_e32 v84, v84
	v_mov_b32_e32 v98, v85
	v_mov_b32_e32 v90, v93
	v_add_f32_e32 v84, 1.0, v84
	v_rcp_f32_e32 v99, v84
	s_nop 0
	v_pk_mul_f32 v[84:85], v[98:99], v[90:91]
	s_nop 0
	v_mul_f32_e32 v84, v84, v85
	v_lshlrev_b32_e32 v85, 16, v119
	v_cvt_pk_bf16_f32 v90, v2, v84
	v_mul_f32_e32 v2, 0xbfb8aa3b, v85
	v_exp_f32_e32 v2, v2
	v_mov_b32_e32 v98, v86
	v_mov_b32_e32 v84, v94
	v_mov_b32_e32 v86, v80
	v_add_f32_e32 v2, 1.0, v2
	v_rcp_f32_e32 v99, v2
	s_nop 0
	v_pk_mul_f32 v[84:85], v[98:99], v[84:85]
	s_nop 0
	v_mul_f32_e32 v2, v84, v85
	v_and_b32_e32 v85, 0xffff0000, v119
	v_mul_f32_e32 v84, 0xbfb8aa3b, v85
	v_exp_f32_e32 v84, v84
	v_mov_b32_e32 v98, v87
	v_add_f32_e32 v84, 1.0, v84
	v_rcp_f32_e32 v99, v84
	v_mov_b32_e32 v84, v95
	v_pk_mul_f32 v[84:85], v[98:99], v[84:85]
	s_nop 0
	v_mul_f32_e32 v84, v84, v85
	v_cvt_pk_bf16_f32 v91, v2, v84
	v_lshlrev_b64 v[84:85], 12, v[146:147]
	v_lshl_add_u64 v[84:85], s[8:9], 0, v[84:85]
	v_lshl_add_u64 v[98:99], v[84:85], 0, v[140:141]
	v_lshlrev_b32_e32 v85, 16, v112
	v_mul_f32_e32 v2, 0xbfb8aa3b, v85
	v_exp_f32_e32 v2, v2
	v_mov_b32_e32 v84, v100
	flat_store_dwordx4 v[98:99], v[88:91]
	v_add_f32_e32 v2, 1.0, v2
	v_rcp_f32_e32 v87, v2
	s_nop 0
	v_pk_mul_f32 v[84:85], v[86:87], v[84:85]
	s_nop 0
	v_mul_f32_e32 v2, v84, v85
	v_and_b32_e32 v85, 0xffff0000, v112
	v_mul_f32_e32 v80, 0xbfb8aa3b, v85
	v_exp_f32_e32 v80, v80
	v_mov_b32_e32 v86, v81
; __device__ __forceinline__ size_t pidx(size_t row, int col) { return ((size_t)(col >> 8) * MTOK + row) * PLD + (col & 255); }
; __device__ __forceinline__ float bflo(unsigned v) { return __uint_as_float(v << 16); }
; __device__ __forceinline__ float bfhi(unsigned v) { return __uint_as_float(v & 0xffff0000u); }
; __device__ __forceinline__ float siluf_(float x) { return x * __builtin_amdgcn_rcpf(1.0f + __expf(-x)); }
;   __device__ __forceinline__ void operator()(EPI_ARGS) const {
;     const size_t row0 = (size_t)u.pm * 256 + wr * 64 + fr;
;     const int col0 = u.pn * 256 + wc * 32 + 8 * fq;
; #pragma unroll
;     for (int bj = 0; bj < 2; ++bj) {
;       const int c = col0 + bj * HALF;
;       const f32x4 s0 = *(const f32x4*)(psc + c), s1 = *(const f32x4*)(psc + c + 4);
; #pragma unroll
;       for (int ai = 0; ai < 2; ++ai) {
;         u32x4 z[4];
; #pragma unroll
;         for (int m = 0; m < 4; ++m) z[m] = *(const u32x4*)(proj + pidx(row0 + ai * HALF + m * 16, PZ + c));
;         __builtin_amdgcn_sched_barrier(0);
; #pragma unroll
;         for (int m = 0; m < 4; ++m) {
;           const size_t row = row0 + ai * HALF + m * 16;
;           const f32x4 v0 = acc[ai][bj][m][0], v1 = acc[ai][bj][m][1];
;           u32x4 o;
;           o.x = pack2(v0[0] * s0[0] * siluf_(bflo(z[m].x)), v0[1] * s0[1] * siluf_(bfhi(z[m].x)));
;           o.y = pack2(v0[2] * s0[2] * siluf_(bflo(z[m].y)), v0[3] * s0[3] * siluf_(bfhi(z[m].y)));
;           o.z = pack2(v1[0] * s1[0] * siluf_(bflo(z[m].z)), v1[1] * s1[1] * siluf_(bfhi(z[m].z)));
;           o.w = pack2(v1[2] * s1[2] * siluf_(bflo(z[m].w)), v1[3] * s1[3] * siluf_(bfhi(z[m].w)));
;           *(u32x4*)(y0 + row * DM + c) = o;
;         }
;       }
;     }
;   }
	v_mov_b32_e32 v84, v101
	v_add_f32_e32 v80, 1.0, v80
	v_rcp_f32_e32 v87, v80
	s_nop 0
	v_pk_mul_f32 v[80:81], v[86:87], v[84:85]
	s_nop 0
	v_mul_f32_e32 v80, v80, v81
	v_lshlrev_b32_e32 v85, 16, v113
	v_cvt_pk_bf16_f32 v80, v2, v80
	v_mul_f32_e32 v2, 0xbfb8aa3b, v85
	v_exp_f32_e32 v2, v2
	v_mov_b32_e32 v86, v82
	v_mov_b32_e32 v84, v102
	v_add_f32_e32 v2, 1.0, v2
	v_rcp_f32_e32 v87, v2
	s_nop 0
	v_pk_mul_f32 v[84:85], v[86:87], v[84:85]
	s_nop 0
	v_mul_f32_e32 v2, v84, v85
	v_and_b32_e32 v85, 0xffff0000, v113
	v_mul_f32_e32 v81, 0xbfb8aa3b, v85
	v_exp_f32_e32 v81, v81
	v_mov_b32_e32 v86, v83
	v_mov_b32_e32 v84, v103
	v_add_f32_e32 v81, 1.0, v81
	v_rcp_f32_e32 v87, v81
	s_nop 0
	v_pk_mul_f32 v[82:83], v[86:87], v[84:85]
	s_nop 0
	v_mul_f32_e32 v81, v82, v83
	v_lshlrev_b32_e32 v83, 16, v114
	v_cvt_pk_bf16_f32 v81, v2, v81
	v_mul_f32_e32 v2, 0xbfb8aa3b, v83
	v_exp_f32_e32 v2, v2
	v_mov_b32_e32 v84, v76
	v_mov_b32_e32 v82, v92
	v_add_f32_e32 v2, 1.0, v2
	v_rcp_f32_e32 v85, v2
	s_nop 0
	v_pk_mul_f32 v[82:83], v[84:85], v[82:83]
	s_nop 0
	v_mul_f32_e32 v2, v82, v83
	v_and_b32_e32 v83, 0xffff0000, v114
	v_mul_f32_e32 v76, 0xbfb8aa3b, v83
	v_exp_f32_e32 v76, v76
	v_mov_b32_e32 v84, v77
	v_mov_b32_e32 v82, v93
	v_add_f32_e32 v76, 1.0, v76
	v_rcp_f32_e32 v85, v76
	s_nop 0
	v_pk_mul_f32 v[76:77], v[84:85], v[82:83]
	s_nop 0
	v_mul_f32_e32 v76, v76, v77
	v_lshlrev_b32_e32 v77, 16, v115
	v_cvt_pk_bf16_f32 v82, v2, v76
	v_mul_f32_e32 v2, 0xbfb8aa3b, v77
	v_exp_f32_e32 v2, v2
	v_mov_b32_e32 v84, v78
	v_mov_b32_e32 v76, v94
	v_mov_b32_e32 v78, v72
	v_add_f32_e32 v2, 1.0, v2
	v_rcp_f32_e32 v85, v2
	s_nop 0
	v_pk_mul_f32 v[76:77], v[84:85], v[76:77]
	s_nop 0
	v_mul_f32_e32 v2, v76, v77
	v_and_b32_e32 v77, 0xffff0000, v115
	v_mul_f32_e32 v76, 0xbfb8aa3b, v77
	v_exp_f32_e32 v76, v76
	v_mov_b32_e32 v84, v79
	v_add_f32_e32 v76, 1.0, v76
	v_rcp_f32_e32 v85, v76
	v_mov_b32_e32 v76, v95
	v_pk_mul_f32 v[76:77], v[84:85], v[76:77]
	s_nop 0
	v_mul_f32_e32 v76, v76, v77
	v_cvt_pk_bf16_f32 v83, v2, v76
	v_lshlrev_b64 v[76:77], 12, v[144:145]
	v_lshl_add_u64 v[76:77], s[8:9], 0, v[76:77]
	v_lshl_add_u64 v[104:105], v[76:77], 0, v[140:141]
	v_lshlrev_b32_e32 v77, 16, v108
	v_mul_f32_e32 v2, 0xbfb8aa3b, v77
	v_exp_f32_e32 v2, v2
	v_mov_b32_e32 v76, v100
	flat_store_dwordx4 v[104:105], v[80:83]
	v_add_f32_e32 v2, 1.0, v2
	v_rcp_f32_e32 v79, v2
	s_nop 0
	v_pk_mul_f32 v[76:77], v[78:79], v[76:77]
	s_nop 0
	v_mul_f32_e32 v2, v76, v77
	v_and_b32_e32 v77, 0xffff0000, v108
	v_mul_f32_e32 v72, 0xbfb8aa3b, v77
	v_exp_f32_e32 v72, v72
	v_mov_b32_e32 v78, v73
	v_mov_b32_e32 v76, v101
	v_add_f32_e32 v72, 1.0, v72
	v_rcp_f32_e32 v79, v72
	s_nop 0
	v_pk_mul_f32 v[72:73], v[78:79], v[76:77]
	s_nop 0
	v_mul_f32_e32 v72, v72, v73
	v_lshlrev_b32_e32 v77, 16, v109
	v_cvt_pk_bf16_f32 v72, v2, v72
	v_mul_f32_e32 v2, 0xbfb8aa3b, v77
	v_exp_f32_e32 v2, v2
	v_mov_b32_e32 v78, v74
	v_mov_b32_e32 v76, v102
	v_add_f32_e32 v2, 1.0, v2
	v_rcp_f32_e32 v79, v2
	s_nop 0
	v_pk_mul_f32 v[76:77], v[78:79], v[76:77]
	s_nop 0
	v_mul_f32_e32 v2, v76, v77
	v_and_b32_e32 v77, 0xffff0000, v109
	v_mul_f32_e32 v73, 0xbfb8aa3b, v77
	v_exp_f32_e32 v73, v73
	v_mov_b32_e32 v78, v75
	v_mov_b32_e32 v76, v103
	v_add_f32_e32 v73, 1.0, v73
	v_rcp_f32_e32 v79, v73
	s_nop 0
	v_pk_mul_f32 v[74:75], v[78:79], v[76:77]
	s_nop 0
	v_mul_f32_e32 v73, v74, v75
	v_lshlrev_b32_e32 v75, 16, v110
	v_cvt_pk_bf16_f32 v73, v2, v73
	v_mul_f32_e32 v2, 0xbfb8aa3b, v75
	v_exp_f32_e32 v2, v2
	v_mov_b32_e32 v76, v68
	v_mov_b32_e32 v74, v92
	v_add_f32_e32 v2, 1.0, v2
	v_rcp_f32_e32 v77, v2
	s_nop 0
	v_pk_mul_f32 v[74:75], v[76:77], v[74:75]
	s_nop 0
	v_mul_f32_e32 v2, v74, v75
	v_and_b32_e32 v75, 0xffff0000, v110
	v_mul_f32_e32 v68, 0xbfb8aa3b, v75
	v_exp_f32_e32 v68, v68
	v_mov_b32_e32 v76, v69
	v_mov_b32_e32 v74, v93
	v_add_f32_e32 v68, 1.0, v68
	v_rcp_f32_e32 v77, v68
	s_nop 0
	v_pk_mul_f32 v[68:69], v[76:77], v[74:75]
	s_nop 0
	v_mul_f32_e32 v68, v68, v69
	v_lshlrev_b32_e32 v69, 16, v111
	v_cvt_pk_bf16_f32 v74, v2, v68
	v_mul_f32_e32 v2, 0xbfb8aa3b, v69
	v_exp_f32_e32 v2, v2
	v_mov_b32_e32 v76, v70
	v_mov_b32_e32 v68, v94
	v_add_f32_e32 v2, 1.0, v2
	v_rcp_f32_e32 v77, v2
	s_nop 0
	v_pk_mul_f32 v[68:69], v[76:77], v[68:69]
	s_nop 0
	v_mul_f32_e32 v2, v68, v69
	v_and_b32_e32 v69, 0xffff0000, v111
	v_mul_f32_e32 v68, 0xbfb8aa3b, v69
	v_exp_f32_e32 v68, v68
	v_mov_b32_e32 v76, v71
	v_add_f32_e32 v68, 1.0, v68
	v_rcp_f32_e32 v77, v68
	v_mov_b32_e32 v68, v95
	v_lshl_add_u64 v[94:95], s[2:3], 0, v[174:175]
	v_pk_mul_f32 v[68:69], v[76:77], v[68:69]
	s_nop 0
	v_mul_f32_e32 v68, v68, v69
	v_cvt_pk_bf16_f32 v75, v2, v68
	v_lshlrev_b64 v[68:69], 12, v[142:143]
	v_lshl_add_u64 v[68:69], s[8:9], 0, v[68:69]
	v_lshl_add_u64 v[92:93], v[68:69], 0, v[140:141]
	flat_store_dwordx4 v[92:93], v[72:75]
	v_lshl_add_u64 v[76:77], v[94:95], 0, v[178:179]
	global_load_dwordx4 v[68:71], v[176:177], off offset:528
	global_load_dwordx4 v[72:75], v[176:177], off offset:512
	flat_load_dwordx4 v[88:91], v[76:77]
	v_lshl_add_u64 v[76:77], v[94:95], 0, v[180:181]
	flat_load_dwordx4 v[84:87], v[76:77]
	v_lshl_add_u64 v[76:77], v[94:95], 0, v[182:183]
	flat_load_dwordx4 v[80:83], v[76:77]
	v_lshl_add_u64 v[76:77], v[94:95], 0, v[184:185]
	flat_load_dwordx4 v[76:79], v[76:77]
	s_waitcnt vmcnt(0) lgkmcnt(0)
; __device__ __forceinline__ size_t pidx(size_t row, int col) { return ((size_t)(col >> 8) * MTOK + row) * PLD + (col & 255); }
; __device__ __forceinline__ float bflo(unsigned v) { return __uint_as_float(v << 16); }
; __device__ __forceinline__ float bfhi(unsigned v) { return __uint_as_float(v & 0xffff0000u); }
; __device__ __forceinline__ float siluf_(float x) { return x * __builtin_amdgcn_rcpf(1.0f + __expf(-x)); }
;   __device__ __forceinline__ void operator()(EPI_ARGS) const {
;     const size_t row0 = (size_t)u.pm * 256 + wr * 64 + fr;
;     const int col0 = u.pn * 256 + wc * 32 + 8 * fq;
; #pragma unroll
;     for (int bj = 0; bj < 2; ++bj) {
;       const int c = col0 + bj * HALF;
;       const f32x4 s0 = *(const f32x4*)(psc + c), s1 = *(const f32x4*)(psc + c + 4);
; #pragma unroll
;       for (int ai = 0; ai < 2; ++ai) {
;         u32x4 z[4];
; #pragma unroll
;         for (int m = 0; m < 4; ++m) z[m] = *(const u32x4*)(proj + pidx(row0 + ai * HALF + m * 16, PZ + c));
;         __builtin_amdgcn_sched_barrier(0);
; #pragma unroll
;         for (int m = 0; m < 4; ++m) {
;           const size_t row = row0 + ai * HALF + m * 16;
;           const f32x4 v0 = acc[ai][bj][m][0], v1 = acc[ai][bj][m][1];
;           u32x4 o;
;           o.x = pack2(v0[0] * s0[0] * siluf_(bflo(z[m].x)), v0[1] * s0[1] * siluf_(bfhi(z[m].x)));
;           o.y = pack2(v0[2] * s0[2] * siluf_(bflo(z[m].y)), v0[3] * s0[3] * siluf_(bfhi(z[m].y)));
;           o.z = pack2(v1[0] * s1[0] * siluf_(bflo(z[m].z)), v1[1] * s1[1] * siluf_(bfhi(z[m].z)));
;           o.w = pack2(v1[2] * s1[2] * siluf_(bflo(z[m].w)), v1[3] * s1[3] * siluf_(bfhi(z[m].w)));
;           *(u32x4*)(y0 + row * DM + c) = o;
;         }
;       }
;     }
;   }
	v_lshlrev_b32_e32 v101, 16, v88
	v_mul_f32_e32 v2, 0xbfb8aa3b, v101
	v_exp_f32_e32 v2, v2
	v_mov_b32_e32 v102, v64
	v_mov_b32_e32 v100, v72
	v_add_f32_e32 v2, 1.0, v2
	v_rcp_f32_e32 v103, v2
	s_nop 0
	v_pk_mul_f32 v[100:101], v[102:103], v[100:101]
	s_nop 0
	v_mul_f32_e32 v2, v100, v101
	v_and_b32_e32 v101, 0xffff0000, v88
	v_mul_f32_e32 v64, 0xbfb8aa3b, v101
	v_exp_f32_e32 v64, v64
	v_mov_b32_e32 v102, v65
	v_mov_b32_e32 v100, v73
	v_mov_b32_e32 v88, v75
	v_add_f32_e32 v64, 1.0, v64
	v_rcp_f32_e32 v103, v64
	s_nop 0
	v_pk_mul_f32 v[64:65], v[102:103], v[100:101]
	s_nop 0
	v_mul_f32_e32 v64, v64, v65
	v_lshlrev_b32_e32 v101, 16, v89
	v_cvt_pk_bf16_f32 v64, v2, v64
	v_mul_f32_e32 v2, 0xbfb8aa3b, v101
	v_exp_f32_e32 v2, v2
	v_and_b32_e32 v89, 0xffff0000, v89
	v_mul_f32_e32 v65, 0xbfb8aa3b, v89
	v_exp_f32_e32 v65, v65
	v_add_f32_e32 v2, 1.0, v2
	v_rcp_f32_e32 v103, v2
	v_mov_b32_e32 v102, v66
	v_mov_b32_e32 v100, v74
	v_add_f32_e32 v65, 1.0, v65
	v_pk_mul_f32 v[100:101], v[102:103], v[100:101]
	s_nop 0
	v_mul_f32_e32 v2, v100, v101
	v_rcp_f32_e32 v101, v65
	v_mov_b32_e32 v100, v67
	v_pk_mul_f32 v[66:67], v[100:101], v[88:89]
	s_nop 0
	v_mul_f32_e32 v65, v66, v67
	v_lshlrev_b32_e32 v67, 16, v90
	v_cvt_pk_bf16_f32 v65, v2, v65
	v_mul_f32_e32 v2, 0xbfb8aa3b, v67
	v_exp_f32_e32 v2, v2
	v_mov_b32_e32 v88, v60
	v_mov_b32_e32 v66, v68
	v_add_f32_e32 v2, 1.0, v2
	v_rcp_f32_e32 v89, v2
	s_nop 0
	v_pk_mul_f32 v[66:67], v[88:89], v[66:67]
	s_nop 0
	v_mul_f32_e32 v2, v66, v67
	v_and_b32_e32 v67, 0xffff0000, v90
	v_mul_f32_e32 v60, 0xbfb8aa3b, v67
	v_exp_f32_e32 v60, v60
	v_mov_b32_e32 v88, v61
	v_mov_b32_e32 v66, v69
	v_add_f32_e32 v60, 1.0, v60
	v_rcp_f32_e32 v89, v60
	s_nop 0
	v_pk_mul_f32 v[60:61], v[88:89], v[66:67]
	s_nop 0
	v_mul_f32_e32 v60, v60, v61
	v_lshlrev_b32_e32 v61, 16, v91
	v_cvt_pk_bf16_f32 v66, v2, v60
	v_mul_f32_e32 v2, 0xbfb8aa3b, v61
	v_exp_f32_e32 v2, v2
	v_mov_b32_e32 v88, v62
	v_mov_b32_e32 v60, v70
	v_mov_b32_e32 v62, v56
	v_add_f32_e32 v2, 1.0, v2
	v_rcp_f32_e32 v89, v2
	s_nop 0
	v_pk_mul_f32 v[60:61], v[88:89], v[60:61]
	s_nop 0
	v_mul_f32_e32 v2, v60, v61
	v_and_b32_e32 v61, 0xffff0000, v91
	v_mul_f32_e32 v60, 0xbfb8aa3b, v61
	v_exp_f32_e32 v60, v60
	v_mov_b32_e32 v88, v63
	v_add_f32_e32 v60, 1.0, v60
	v_rcp_f32_e32 v89, v60
	v_mov_b32_e32 v60, v71
	v_pk_mul_f32 v[60:61], v[88:89], v[60:61]
	s_nop 0
	v_mul_f32_e32 v60, v60, v61
	v_lshlrev_b32_e32 v61, 16, v84
	v_cvt_pk_bf16_f32 v67, v2, v60
	v_mul_f32_e32 v2, 0xbfb8aa3b, v61
	v_exp_f32_e32 v2, v2
	v_mov_b32_e32 v60, v72
	flat_store_dwordx4 v[136:137], v[64:67] offset:256
	v_add_f32_e32 v2, 1.0, v2
	v_rcp_f32_e32 v63, v2
	s_nop 0
	v_pk_mul_f32 v[60:61], v[62:63], v[60:61]
	s_nop 0
	v_mul_f32_e32 v2, v60, v61
	v_and_b32_e32 v61, 0xffff0000, v84
	v_mul_f32_e32 v56, 0xbfb8aa3b, v61
	v_exp_f32_e32 v56, v56
	v_mov_b32_e32 v62, v57
	v_mov_b32_e32 v60, v73
	v_add_f32_e32 v56, 1.0, v56
	v_rcp_f32_e32 v63, v56
	s_nop 0
	v_pk_mul_f32 v[56:57], v[62:63], v[60:61]
	s_nop 0
	v_mul_f32_e32 v56, v56, v57
	v_lshlrev_b32_e32 v61, 16, v85
	v_cvt_pk_bf16_f32 v56, v2, v56
	v_mul_f32_e32 v2, 0xbfb8aa3b, v61
	v_exp_f32_e32 v2, v2
	v_mov_b32_e32 v62, v58
	v_mov_b32_e32 v60, v74
	v_add_f32_e32 v2, 1.0, v2
	v_rcp_f32_e32 v63, v2
	s_nop 0
	v_pk_mul_f32 v[60:61], v[62:63], v[60:61]
	s_nop 0
	v_mul_f32_e32 v2, v60, v61
	v_and_b32_e32 v61, 0xffff0000, v85
	v_mul_f32_e32 v57, 0xbfb8aa3b, v61
	v_exp_f32_e32 v57, v57
	v_mov_b32_e32 v62, v59
	v_mov_b32_e32 v60, v75
	v_add_f32_e32 v57, 1.0, v57
	v_rcp_f32_e32 v63, v57
	s_nop 0
	v_pk_mul_f32 v[58:59], v[62:63], v[60:61]
	s_nop 0
	v_mul_f32_e32 v57, v58, v59
	v_lshlrev_b32_e32 v59, 16, v86
	v_cvt_pk_bf16_f32 v57, v2, v57
	v_mul_f32_e32 v2, 0xbfb8aa3b, v59
	v_exp_f32_e32 v2, v2
	v_mov_b32_e32 v60, v52
	v_mov_b32_e32 v58, v68
	v_add_f32_e32 v2, 1.0, v2
	v_rcp_f32_e32 v61, v2
	s_nop 0
	v_pk_mul_f32 v[58:59], v[60:61], v[58:59]
	s_nop 0
	v_mul_f32_e32 v2, v58, v59
	v_and_b32_e32 v59, 0xffff0000, v86
	v_mul_f32_e32 v52, 0xbfb8aa3b, v59
	v_exp_f32_e32 v52, v52
	v_mov_b32_e32 v60, v53
	v_mov_b32_e32 v58, v69
	v_add_f32_e32 v52, 1.0, v52
	v_rcp_f32_e32 v61, v52
	s_nop 0
	v_pk_mul_f32 v[52:53], v[60:61], v[58:59]
	s_nop 0
	v_mul_f32_e32 v52, v52, v53
	v_lshlrev_b32_e32 v53, 16, v87
	v_cvt_pk_bf16_f32 v58, v2, v52
	v_mul_f32_e32 v2, 0xbfb8aa3b, v53
	v_exp_f32_e32 v2, v2
	v_mov_b32_e32 v60, v54
	v_mov_b32_e32 v52, v70
	v_mov_b32_e32 v54, v48
	v_add_f32_e32 v2, 1.0, v2
	v_rcp_f32_e32 v61, v2
	s_nop 0
	v_pk_mul_f32 v[52:53], v[60:61], v[52:53]
	s_nop 0
	v_mul_f32_e32 v2, v52, v53
	v_and_b32_e32 v53, 0xffff0000, v87
	v_mul_f32_e32 v52, 0xbfb8aa3b, v53
	v_exp_f32_e32 v52, v52
	v_mov_b32_e32 v60, v55
	v_add_f32_e32 v52, 1.0, v52
	v_rcp_f32_e32 v61, v52
	v_mov_b32_e32 v52, v71
	v_pk_mul_f32 v[52:53], v[60:61], v[52:53]
	s_nop 0
	v_mul_f32_e32 v52, v52, v53
	v_lshlrev_b32_e32 v53, 16, v80
	v_cvt_pk_bf16_f32 v59, v2, v52
	v_mul_f32_e32 v2, 0xbfb8aa3b, v53
	v_exp_f32_e32 v2, v2
	v_mov_b32_e32 v52, v72
	flat_store_dwordx4 v[124:125], v[56:59] offset:256
	v_add_f32_e32 v2, 1.0, v2
	v_rcp_f32_e32 v55, v2
	s_nop 0
	v_pk_mul_f32 v[52:53], v[54:55], v[52:53]
	s_nop 0
	v_mul_f32_e32 v2, v52, v53
	v_and_b32_e32 v53, 0xffff0000, v80
	v_mul_f32_e32 v48, 0xbfb8aa3b, v53
	v_exp_f32_e32 v48, v48
	v_mov_b32_e32 v54, v49
	v_mov_b32_e32 v52, v73
	v_add_f32_e32 v48, 1.0, v48
	v_rcp_f32_e32 v55, v48
	s_nop 0
	v_pk_mul_f32 v[48:49], v[54:55], v[52:53]
	s_nop 0
	v_mul_f32_e32 v48, v48, v49
	v_lshlrev_b32_e32 v53, 16, v81
	v_cvt_pk_bf16_f32 v48, v2, v48
	v_mul_f32_e32 v2, 0xbfb8aa3b, v53
	v_exp_f32_e32 v2, v2
	v_mov_b32_e32 v54, v50
	v_mov_b32_e32 v52, v74
	v_add_f32_e32 v2, 1.0, v2
	v_rcp_f32_e32 v55, v2
; __device__ __forceinline__ size_t pidx(size_t row, int col) { return ((size_t)(col >> 8) * MTOK + row) * PLD + (col & 255); }
; __device__ __forceinline__ float bflo(unsigned v) { return __uint_as_float(v << 16); }
; __device__ __forceinline__ float bfhi(unsigned v) { return __uint_as_float(v & 0xffff0000u); }
; __device__ __forceinline__ float siluf_(float x) { return x * __builtin_amdgcn_rcpf(1.0f + __expf(-x)); }
;   __device__ __forceinline__ void operator()(EPI_ARGS) const {
;     const size_t row0 = (size_t)u.pm * 256 + wr * 64 + fr;
;     const int col0 = u.pn * 256 + wc * 32 + 8 * fq;
; #pragma unroll
;     for (int bj = 0; bj < 2; ++bj) {
;       const int c = col0 + bj * HALF;
;       const f32x4 s0 = *(const f32x4*)(psc + c), s1 = *(const f32x4*)(psc + c + 4);
; #pragma unroll
;       for (int ai = 0; ai < 2; ++ai) {
;         u32x4 z[4];
; #pragma unroll
;         for (int m = 0; m < 4; ++m) z[m] = *(const u32x4*)(proj + pidx(row0 + ai * HALF + m * 16, PZ + c));
;         __builtin_amdgcn_sched_barrier(0);
; #pragma unroll
;         for (int m = 0; m < 4; ++m) {
;           const size_t row = row0 + ai * HALF + m * 16;
;           const f32x4 v0 = acc[ai][bj][m][0], v1 = acc[ai][bj][m][1];
;           u32x4 o;
;           o.x = pack2(v0[0] * s0[0] * siluf_(bflo(z[m].x)), v0[1] * s0[1] * siluf_(bfhi(z[m].x)));
;           o.y = pack2(v0[2] * s0[2] * siluf_(bflo(z[m].y)), v0[3] * s0[3] * siluf_(bfhi(z[m].y)));
;           o.z = pack2(v1[0] * s1[0] * siluf_(bflo(z[m].z)), v1[1] * s1[1] * siluf_(bfhi(z[m].z)));
;           o.w = pack2(v1[2] * s1[2] * siluf_(bflo(z[m].w)), v1[3] * s1[3] * siluf_(bfhi(z[m].w)));
;           *(u32x4*)(y0 + row * DM + c) = o;
;         }
;       }
;     }
;   }
	s_nop 0
	v_pk_mul_f32 v[52:53], v[54:55], v[52:53]
	s_nop 0
	v_mul_f32_e32 v2, v52, v53
	v_and_b32_e32 v53, 0xffff0000, v81
	v_mul_f32_e32 v49, 0xbfb8aa3b, v53
	v_exp_f32_e32 v49, v49
	v_mov_b32_e32 v54, v51
	v_mov_b32_e32 v52, v75
	v_add_f32_e32 v49, 1.0, v49
	v_rcp_f32_e32 v55, v49
	s_nop 0
	v_pk_mul_f32 v[50:51], v[54:55], v[52:53]
	s_nop 0
	v_mul_f32_e32 v49, v50, v51
	v_lshlrev_b32_e32 v51, 16, v82
	v_cvt_pk_bf16_f32 v49, v2, v49
	v_mul_f32_e32 v2, 0xbfb8aa3b, v51
	v_exp_f32_e32 v2, v2
	v_mov_b32_e32 v52, v44
	v_mov_b32_e32 v50, v68
	v_add_f32_e32 v2, 1.0, v2
	v_rcp_f32_e32 v53, v2
	s_nop 0
	v_pk_mul_f32 v[50:51], v[52:53], v[50:51]
	s_nop 0
	v_mul_f32_e32 v2, v50, v51
	v_and_b32_e32 v51, 0xffff0000, v82
	v_mul_f32_e32 v44, 0xbfb8aa3b, v51
	v_exp_f32_e32 v44, v44
	v_mov_b32_e32 v52, v45
	v_mov_b32_e32 v50, v69
	v_add_f32_e32 v44, 1.0, v44
	v_rcp_f32_e32 v53, v44
	s_nop 0
	v_pk_mul_f32 v[44:45], v[52:53], v[50:51]
	s_nop 0
	v_mul_f32_e32 v44, v44, v45
	v_lshlrev_b32_e32 v45, 16, v83
	v_cvt_pk_bf16_f32 v50, v2, v44
	v_mul_f32_e32 v2, 0xbfb8aa3b, v45
	v_exp_f32_e32 v2, v2
	v_mov_b32_e32 v52, v46
	v_mov_b32_e32 v44, v70
	v_mov_b32_e32 v46, v40
	v_add_f32_e32 v2, 1.0, v2
	v_rcp_f32_e32 v53, v2
	s_nop 0
	v_pk_mul_f32 v[44:45], v[52:53], v[44:45]
	s_nop 0
	v_mul_f32_e32 v2, v44, v45
	v_and_b32_e32 v45, 0xffff0000, v83
	v_mul_f32_e32 v44, 0xbfb8aa3b, v45
	v_exp_f32_e32 v44, v44
	v_mov_b32_e32 v52, v47
	v_add_f32_e32 v44, 1.0, v44
	v_rcp_f32_e32 v53, v44
	v_mov_b32_e32 v44, v71
	v_pk_mul_f32 v[44:45], v[52:53], v[44:45]
	s_nop 0
	v_mul_f32_e32 v44, v44, v45
	v_lshlrev_b32_e32 v45, 16, v76
	v_cvt_pk_bf16_f32 v51, v2, v44
	v_mul_f32_e32 v2, 0xbfb8aa3b, v45
	v_exp_f32_e32 v2, v2
	v_mov_b32_e32 v44, v72
	flat_store_dwordx4 v[128:129], v[48:51] offset:256
	v_add_f32_e32 v2, 1.0, v2
	v_rcp_f32_e32 v47, v2
	s_nop 0
	v_pk_mul_f32 v[44:45], v[46:47], v[44:45]
	s_nop 0
	v_mul_f32_e32 v2, v44, v45
	v_and_b32_e32 v45, 0xffff0000, v76
	v_mul_f32_e32 v40, 0xbfb8aa3b, v45
	v_exp_f32_e32 v40, v40
	v_mov_b32_e32 v46, v41
	v_mov_b32_e32 v44, v73
	v_add_f32_e32 v40, 1.0, v40
	v_rcp_f32_e32 v47, v40
	s_nop 0
	v_pk_mul_f32 v[40:41], v[46:47], v[44:45]
	s_nop 0
	v_mul_f32_e32 v40, v40, v41
	v_lshlrev_b32_e32 v45, 16, v77
	v_cvt_pk_bf16_f32 v40, v2, v40
	v_mul_f32_e32 v2, 0xbfb8aa3b, v45
	v_exp_f32_e32 v2, v2
	v_mov_b32_e32 v46, v42
	v_mov_b32_e32 v44, v74
	v_add_f32_e32 v2, 1.0, v2
	v_rcp_f32_e32 v47, v2
	s_nop 0
	v_pk_mul_f32 v[44:45], v[46:47], v[44:45]
	s_nop 0
	v_mul_f32_e32 v2, v44, v45
	v_and_b32_e32 v45, 0xffff0000, v77
	v_mul_f32_e32 v41, 0xbfb8aa3b, v45
	v_exp_f32_e32 v41, v41
	v_mov_b32_e32 v46, v43
	v_mov_b32_e32 v44, v75
	v_add_f32_e32 v41, 1.0, v41
	v_rcp_f32_e32 v47, v41
	s_nop 0
	v_pk_mul_f32 v[42:43], v[46:47], v[44:45]
	s_nop 0
	v_mul_f32_e32 v41, v42, v43
	v_lshlrev_b32_e32 v43, 16, v78
	v_cvt_pk_bf16_f32 v41, v2, v41
	v_mul_f32_e32 v2, 0xbfb8aa3b, v43
	v_exp_f32_e32 v2, v2
	v_mov_b32_e32 v44, v36
	v_mov_b32_e32 v42, v68
	v_add_f32_e32 v2, 1.0, v2
	v_rcp_f32_e32 v45, v2
	s_nop 0
	v_pk_mul_f32 v[42:43], v[44:45], v[42:43]
	s_nop 0
	v_mul_f32_e32 v2, v42, v43
	v_and_b32_e32 v43, 0xffff0000, v78
	v_mul_f32_e32 v36, 0xbfb8aa3b, v43
	v_exp_f32_e32 v36, v36
	v_mov_b32_e32 v44, v37
	v_mov_b32_e32 v42, v69
	v_add_f32_e32 v36, 1.0, v36
	v_rcp_f32_e32 v45, v36
	s_nop 0
	v_pk_mul_f32 v[36:37], v[44:45], v[42:43]
	s_nop 0
	v_mul_f32_e32 v36, v36, v37
	v_lshlrev_b32_e32 v37, 16, v79
	v_cvt_pk_bf16_f32 v42, v2, v36
	v_mul_f32_e32 v2, 0xbfb8aa3b, v37
	v_exp_f32_e32 v2, v2
	v_mov_b32_e32 v44, v38
	v_mov_b32_e32 v36, v70
	v_add_f32_e32 v2, 1.0, v2
	v_rcp_f32_e32 v45, v2
	s_nop 0
	v_pk_mul_f32 v[36:37], v[44:45], v[36:37]
	s_nop 0
	v_mul_f32_e32 v2, v36, v37
	v_and_b32_e32 v37, 0xffff0000, v79
	v_mul_f32_e32 v36, 0xbfb8aa3b, v37
	v_exp_f32_e32 v36, v36
	v_mov_b32_e32 v44, v39
	v_add_f32_e32 v36, 1.0, v36
	v_rcp_f32_e32 v45, v36
	v_mov_b32_e32 v36, v71
	v_pk_mul_f32 v[36:37], v[44:45], v[36:37]
	s_nop 0
	v_mul_f32_e32 v36, v36, v37
	v_cvt_pk_bf16_f32 v43, v2, v36
	flat_store_dwordx4 v[126:127], v[40:43] offset:256
	v_lshl_add_u64 v[36:37], v[94:95], 0, v[130:131]
	flat_load_dwordx4 v[48:51], v[36:37]
	v_lshl_add_u64 v[36:37], v[94:95], 0, v[132:133]
	flat_load_dwordx4 v[44:47], v[36:37]
	v_lshl_add_u64 v[36:37], v[94:95], 0, v[134:135]
	flat_load_dwordx4 v[40:43], v[36:37]
	v_lshl_add_u64 v[36:37], v[94:95], 0, v[138:139]
	flat_load_dwordx4 v[36:39], v[36:37]
	s_waitcnt vmcnt(0) lgkmcnt(0)
; __device__ __forceinline__ size_t pidx(size_t row, int col) { return ((size_t)(col >> 8) * MTOK + row) * PLD + (col & 255); }
; __device__ __forceinline__ float bflo(unsigned v) { return __uint_as_float(v << 16); }
; __device__ __forceinline__ float bfhi(unsigned v) { return __uint_as_float(v & 0xffff0000u); }
; __device__ __forceinline__ float siluf_(float x) { return x * __builtin_amdgcn_rcpf(1.0f + __expf(-x)); }
;   __device__ __forceinline__ void operator()(EPI_ARGS) const {
;     const size_t row0 = (size_t)u.pm * 256 + wr * 64 + fr;
;     const int col0 = u.pn * 256 + wc * 32 + 8 * fq;
; #pragma unroll
;     for (int bj = 0; bj < 2; ++bj) {
;       const int c = col0 + bj * HALF;
;       const f32x4 s0 = *(const f32x4*)(psc + c), s1 = *(const f32x4*)(psc + c + 4);
; #pragma unroll
;       for (int ai = 0; ai < 2; ++ai) {
;         u32x4 z[4];
; #pragma unroll
;         for (int m = 0; m < 4; ++m) z[m] = *(const u32x4*)(proj + pidx(row0 + ai * HALF + m * 16, PZ + c));
;         __builtin_amdgcn_sched_barrier(0);
; #pragma unroll
;         for (int m = 0; m < 4; ++m) {
;           const size_t row = row0 + ai * HALF + m * 16;
;           const f32x4 v0 = acc[ai][bj][m][0], v1 = acc[ai][bj][m][1];
;           u32x4 o;
;           o.x = pack2(v0[0] * s0[0] * siluf_(bflo(z[m].x)), v0[1] * s0[1] * siluf_(bfhi(z[m].x)));
;           o.y = pack2(v0[2] * s0[2] * siluf_(bflo(z[m].y)), v0[3] * s0[3] * siluf_(bfhi(z[m].y)));
;           o.z = pack2(v1[0] * s1[0] * siluf_(bflo(z[m].z)), v1[1] * s1[1] * siluf_(bfhi(z[m].z)));
;           o.w = pack2(v1[2] * s1[2] * siluf_(bflo(z[m].w)), v1[3] * s1[3] * siluf_(bfhi(z[m].w)));
;           *(u32x4*)(y0 + row * DM + c) = o;
;         }
;       }
;     }
;   }
	v_lshlrev_b32_e32 v53, 16, v48
	v_mul_f32_e32 v2, 0xbfb8aa3b, v53
	v_exp_f32_e32 v2, v2
	v_mov_b32_e32 v54, v32
	v_mov_b32_e32 v52, v72
	s_and_b64 vcc, exec, s[18:19]
	v_add_f32_e32 v2, 1.0, v2
	v_rcp_f32_e32 v55, v2
	s_mov_b32 s33, s16
	s_mov_b32 s2, s14
	s_mov_b64 s[4:5], s[22:23]
	v_pk_mul_f32 v[52:53], v[54:55], v[52:53]
	v_mov_b32_e32 v54, v33
	v_mul_f32_e32 v2, v52, v53
	v_and_b32_e32 v53, 0xffff0000, v48
	v_mul_f32_e32 v32, 0xbfb8aa3b, v53
	v_exp_f32_e32 v32, v32
	v_mov_b32_e32 v52, v73
	v_mov_b32_e32 v48, v75
	s_mov_b64 s[6:7], s[20:21]
	v_add_f32_e32 v32, 1.0, v32
	v_rcp_f32_e32 v55, v32
	s_nop 0
	v_pk_mul_f32 v[32:33], v[54:55], v[52:53]
	s_nop 0
	v_mul_f32_e32 v32, v32, v33
	v_lshlrev_b32_e32 v53, 16, v49
	v_cvt_pk_bf16_f32 v32, v2, v32
	v_mul_f32_e32 v2, 0xbfb8aa3b, v53
	v_exp_f32_e32 v2, v2
	v_and_b32_e32 v49, 0xffff0000, v49
	v_mul_f32_e32 v33, 0xbfb8aa3b, v49
	v_exp_f32_e32 v33, v33
	v_add_f32_e32 v2, 1.0, v2
	v_rcp_f32_e32 v55, v2
	v_mov_b32_e32 v54, v34
	v_mov_b32_e32 v52, v74
	v_add_f32_e32 v33, 1.0, v33
	v_pk_mul_f32 v[52:53], v[54:55], v[52:53]
	s_nop 0
	v_mul_f32_e32 v2, v52, v53
	v_rcp_f32_e32 v53, v33
	v_mov_b32_e32 v52, v35
	v_pk_mul_f32 v[34:35], v[52:53], v[48:49]
	s_nop 0
	v_mul_f32_e32 v33, v34, v35
	v_lshlrev_b32_e32 v35, 16, v50
	v_cvt_pk_bf16_f32 v33, v2, v33
	v_mul_f32_e32 v2, 0xbfb8aa3b, v35
	v_exp_f32_e32 v2, v2
	v_mov_b32_e32 v48, v28
	v_mov_b32_e32 v34, v68
	v_add_f32_e32 v2, 1.0, v2
	v_rcp_f32_e32 v49, v2
	s_nop 0
	v_pk_mul_f32 v[34:35], v[48:49], v[34:35]
	s_nop 0
	v_mul_f32_e32 v2, v34, v35
	v_and_b32_e32 v35, 0xffff0000, v50
	v_mul_f32_e32 v28, 0xbfb8aa3b, v35
	v_exp_f32_e32 v28, v28
	v_mov_b32_e32 v48, v29
	v_mov_b32_e32 v34, v69
	v_add_f32_e32 v28, 1.0, v28
	v_rcp_f32_e32 v49, v28
	s_nop 0
	v_pk_mul_f32 v[28:29], v[48:49], v[34:35]
	s_nop 0
	v_mul_f32_e32 v28, v28, v29
	v_lshlrev_b32_e32 v29, 16, v51
	v_cvt_pk_bf16_f32 v34, v2, v28
	v_mul_f32_e32 v2, 0xbfb8aa3b, v29
	v_exp_f32_e32 v2, v2
	v_mov_b32_e32 v48, v30
	v_mov_b32_e32 v28, v70
	v_mov_b32_e32 v30, v24
	v_add_f32_e32 v2, 1.0, v2
	v_rcp_f32_e32 v49, v2
	s_nop 0
	v_pk_mul_f32 v[28:29], v[48:49], v[28:29]
	s_nop 0
	v_mul_f32_e32 v2, v28, v29
	v_and_b32_e32 v29, 0xffff0000, v51
	v_mul_f32_e32 v28, 0xbfb8aa3b, v29
	v_exp_f32_e32 v28, v28
	v_mov_b32_e32 v48, v31
	v_add_f32_e32 v28, 1.0, v28
	v_rcp_f32_e32 v49, v28
	v_mov_b32_e32 v28, v71
	v_pk_mul_f32 v[28:29], v[48:49], v[28:29]
	s_nop 0
	v_mul_f32_e32 v28, v28, v29
	v_lshlrev_b32_e32 v29, 16, v44
	v_cvt_pk_bf16_f32 v35, v2, v28
	v_mul_f32_e32 v2, 0xbfb8aa3b, v29
	v_exp_f32_e32 v2, v2
	v_mov_b32_e32 v28, v72
	flat_store_dwordx4 v[96:97], v[32:35] offset:256
	v_add_f32_e32 v2, 1.0, v2
	v_rcp_f32_e32 v31, v2
	s_nop 0
	v_pk_mul_f32 v[28:29], v[30:31], v[28:29]
	s_nop 0
	v_mul_f32_e32 v2, v28, v29
	v_and_b32_e32 v29, 0xffff0000, v44
	v_mul_f32_e32 v24, 0xbfb8aa3b, v29
	v_exp_f32_e32 v24, v24
	v_mov_b32_e32 v30, v25
	v_mov_b32_e32 v28, v73
	v_add_f32_e32 v24, 1.0, v24
	v_rcp_f32_e32 v31, v24
	s_nop 0
	v_pk_mul_f32 v[24:25], v[30:31], v[28:29]
	s_nop 0
	v_mul_f32_e32 v24, v24, v25
	v_lshlrev_b32_e32 v29, 16, v45
	v_cvt_pk_bf16_f32 v24, v2, v24
	v_mul_f32_e32 v2, 0xbfb8aa3b, v29
	v_exp_f32_e32 v2, v2
	v_mov_b32_e32 v30, v26
	v_mov_b32_e32 v28, v74
	v_add_f32_e32 v2, 1.0, v2
	v_rcp_f32_e32 v31, v2
	s_nop 0
	v_pk_mul_f32 v[28:29], v[30:31], v[28:29]
	s_nop 0
	v_mul_f32_e32 v2, v28, v29
	v_and_b32_e32 v29, 0xffff0000, v45
	v_mul_f32_e32 v25, 0xbfb8aa3b, v29
	v_exp_f32_e32 v25, v25
	v_mov_b32_e32 v30, v27
	v_mov_b32_e32 v28, v75
	v_add_f32_e32 v25, 1.0, v25
	v_rcp_f32_e32 v31, v25
	s_nop 0
	v_pk_mul_f32 v[26:27], v[30:31], v[28:29]
	s_nop 0
	v_mul_f32_e32 v25, v26, v27
	v_lshlrev_b32_e32 v27, 16, v46
	v_cvt_pk_bf16_f32 v25, v2, v25
	v_mul_f32_e32 v2, 0xbfb8aa3b, v27
	v_exp_f32_e32 v2, v2
	v_mov_b32_e32 v28, v20
	v_mov_b32_e32 v26, v68
	v_add_f32_e32 v2, 1.0, v2
	v_rcp_f32_e32 v29, v2
	s_nop 0
	v_pk_mul_f32 v[26:27], v[28:29], v[26:27]
	s_nop 0
	v_mul_f32_e32 v2, v26, v27
	v_and_b32_e32 v27, 0xffff0000, v46
	v_mul_f32_e32 v20, 0xbfb8aa3b, v27
	v_exp_f32_e32 v20, v20
	v_mov_b32_e32 v28, v21
	v_mov_b32_e32 v26, v69
	v_add_f32_e32 v20, 1.0, v20
	v_rcp_f32_e32 v29, v20
	s_nop 0
	v_pk_mul_f32 v[20:21], v[28:29], v[26:27]
	s_nop 0
	v_mul_f32_e32 v20, v20, v21
	v_lshlrev_b32_e32 v21, 16, v47
	v_cvt_pk_bf16_f32 v26, v2, v20
	v_mul_f32_e32 v2, 0xbfb8aa3b, v21
	v_exp_f32_e32 v2, v2
	v_mov_b32_e32 v28, v22
	v_mov_b32_e32 v20, v70
	v_mov_b32_e32 v22, v16
	v_add_f32_e32 v2, 1.0, v2
	v_rcp_f32_e32 v29, v2
	s_nop 0
	v_pk_mul_f32 v[20:21], v[28:29], v[20:21]
	s_nop 0
	v_mul_f32_e32 v2, v20, v21
	v_and_b32_e32 v21, 0xffff0000, v47
	v_mul_f32_e32 v20, 0xbfb8aa3b, v21
	v_exp_f32_e32 v20, v20
	v_mov_b32_e32 v28, v23
	v_add_f32_e32 v20, 1.0, v20
	v_rcp_f32_e32 v29, v20
	v_mov_b32_e32 v20, v71
	v_pk_mul_f32 v[20:21], v[28:29], v[20:21]
	s_nop 0
	v_mul_f32_e32 v20, v20, v21
	v_lshlrev_b32_e32 v21, 16, v40
	v_cvt_pk_bf16_f32 v27, v2, v20
	v_mul_f32_e32 v2, 0xbfb8aa3b, v21
	v_exp_f32_e32 v2, v2
	v_mov_b32_e32 v20, v72
	flat_store_dwordx4 v[98:99], v[24:27] offset:256
; __device__ __forceinline__ float bflo(unsigned v) { return __uint_as_float(v << 16); }
; __device__ __forceinline__ float bfhi(unsigned v) { return __uint_as_float(v & 0xffff0000u); }
; __device__ __forceinline__ float siluf_(float x) { return x * __builtin_amdgcn_rcpf(1.0f + __expf(-x)); }
; #define PG8_WAIT_V(n) asm volatile("s_waitcnt vmcnt(" #n ")" ::: "memory")
; #define PG8_BAR __builtin_amdgcn_s_barrier()
; template <class Epi, class AddrA, class AddrB>
; __device__ __forceinline__ void gemm_phase(const Sched S, const int lda, const int ldb, const int K, const AddrA addrA,
;                                            const AddrB addrB, const Epi E) {
;     ...
;   PG8_WAIT_V(0);
;   if (wr == 0) PG8_BAR;
;   PG8_BAR;
;   __device__ __forceinline__ void operator()(EPI_ARGS) const {
;     ...
;         for (int m = 0; m < 4; ++m) {
;           const size_t row = row0 + ai * HALF + m * 16;
;           const f32x4 v0 = acc[ai][bj][m][0], v1 = acc[ai][bj][m][1];
;           u32x4 o;
;           o.x = pack2(v0[0] * s0[0] * siluf_(bflo(z[m].x)), v0[1] * s0[1] * siluf_(bfhi(z[m].x)));
;           o.y = pack2(v0[2] * s0[2] * siluf_(bflo(z[m].y)), v0[3] * s0[3] * siluf_(bfhi(z[m].y)));
;           o.z = pack2(v1[0] * s1[0] * siluf_(bflo(z[m].z)), v1[1] * s1[1] * siluf_(bfhi(z[m].z)));
;           o.w = pack2(v1[2] * s1[2] * siluf_(bflo(z[m].w)), v1[3] * s1[3] * siluf_(bfhi(z[m].w)));
;           *(u32x4*)(y0 + row * DM + c) = o;
;         }
	v_add_f32_e32 v2, 1.0, v2
	v_rcp_f32_e32 v23, v2
	s_nop 0
	v_pk_mul_f32 v[20:21], v[22:23], v[20:21]
	s_nop 0
	v_mul_f32_e32 v2, v20, v21
	v_and_b32_e32 v21, 0xffff0000, v40
	v_mul_f32_e32 v16, 0xbfb8aa3b, v21
	v_exp_f32_e32 v16, v16
	v_mov_b32_e32 v22, v17
	v_mov_b32_e32 v20, v73
	v_add_f32_e32 v16, 1.0, v16
	v_rcp_f32_e32 v23, v16
	s_nop 0
	v_pk_mul_f32 v[16:17], v[22:23], v[20:21]
	s_nop 0
	v_mul_f32_e32 v16, v16, v17
	v_lshlrev_b32_e32 v21, 16, v41
	v_cvt_pk_bf16_f32 v16, v2, v16
	v_mul_f32_e32 v2, 0xbfb8aa3b, v21
	v_exp_f32_e32 v2, v2
	v_mov_b32_e32 v22, v18
	v_mov_b32_e32 v20, v74
	v_add_f32_e32 v2, 1.0, v2
	v_rcp_f32_e32 v23, v2
	s_nop 0
	v_pk_mul_f32 v[20:21], v[22:23], v[20:21]
	s_nop 0
	v_mul_f32_e32 v2, v20, v21
	v_and_b32_e32 v21, 0xffff0000, v41
	v_mul_f32_e32 v17, 0xbfb8aa3b, v21
	v_exp_f32_e32 v17, v17
	v_mov_b32_e32 v22, v19
	v_mov_b32_e32 v20, v75
	v_add_f32_e32 v17, 1.0, v17
	v_rcp_f32_e32 v23, v17
	s_nop 0
	v_pk_mul_f32 v[18:19], v[22:23], v[20:21]
	s_nop 0
	v_mul_f32_e32 v17, v18, v19
	v_lshlrev_b32_e32 v19, 16, v42
	v_cvt_pk_bf16_f32 v17, v2, v17
	v_mul_f32_e32 v2, 0xbfb8aa3b, v19
	v_exp_f32_e32 v2, v2
	v_mov_b32_e32 v20, v12
	v_mov_b32_e32 v18, v68
	v_add_f32_e32 v2, 1.0, v2
	v_rcp_f32_e32 v21, v2
	s_nop 0
	v_pk_mul_f32 v[18:19], v[20:21], v[18:19]
	s_nop 0
	v_mul_f32_e32 v2, v18, v19
	v_and_b32_e32 v19, 0xffff0000, v42
	v_mul_f32_e32 v12, 0xbfb8aa3b, v19
	v_exp_f32_e32 v12, v12
	v_mov_b32_e32 v20, v13
	v_mov_b32_e32 v18, v69
	v_add_f32_e32 v12, 1.0, v12
	v_rcp_f32_e32 v21, v12
	s_nop 0
	v_pk_mul_f32 v[12:13], v[20:21], v[18:19]
	s_nop 0
	v_mul_f32_e32 v12, v12, v13
	v_lshlrev_b32_e32 v13, 16, v43
	v_cvt_pk_bf16_f32 v18, v2, v12
	v_mul_f32_e32 v2, 0xbfb8aa3b, v13
	v_exp_f32_e32 v2, v2
	v_mov_b32_e32 v20, v14
	v_mov_b32_e32 v12, v70
	v_mov_b32_e32 v14, v8
	v_add_f32_e32 v2, 1.0, v2
	v_rcp_f32_e32 v21, v2
	s_nop 0
	v_pk_mul_f32 v[12:13], v[20:21], v[12:13]
	s_nop 0
	v_mul_f32_e32 v2, v12, v13
	v_and_b32_e32 v13, 0xffff0000, v43
	v_mul_f32_e32 v12, 0xbfb8aa3b, v13
	v_exp_f32_e32 v12, v12
	v_mov_b32_e32 v20, v15
	v_add_f32_e32 v12, 1.0, v12
	v_rcp_f32_e32 v21, v12
	v_mov_b32_e32 v12, v71
	v_pk_mul_f32 v[12:13], v[20:21], v[12:13]
	s_nop 0
	v_mul_f32_e32 v12, v12, v13
	v_lshlrev_b32_e32 v13, 16, v36
	v_cvt_pk_bf16_f32 v19, v2, v12
	v_mul_f32_e32 v2, 0xbfb8aa3b, v13
	v_exp_f32_e32 v2, v2
	v_mov_b32_e32 v12, v72
	flat_store_dwordx4 v[104:105], v[16:19] offset:256
	v_add_f32_e32 v2, 1.0, v2
	v_rcp_f32_e32 v15, v2
	s_nop 0
	v_pk_mul_f32 v[12:13], v[14:15], v[12:13]
	s_nop 0
	v_mul_f32_e32 v2, v12, v13
	v_and_b32_e32 v13, 0xffff0000, v36
	v_mul_f32_e32 v8, 0xbfb8aa3b, v13
	v_exp_f32_e32 v8, v8
	v_mov_b32_e32 v14, v9
	v_mov_b32_e32 v12, v73
	v_add_f32_e32 v8, 1.0, v8
	v_rcp_f32_e32 v15, v8
	s_nop 0
	v_pk_mul_f32 v[8:9], v[14:15], v[12:13]
	s_nop 0
	v_mul_f32_e32 v8, v8, v9
	v_lshlrev_b32_e32 v13, 16, v37
	v_cvt_pk_bf16_f32 v8, v2, v8
	v_mul_f32_e32 v2, 0xbfb8aa3b, v13
	v_exp_f32_e32 v2, v2
	v_mov_b32_e32 v14, v10
	v_mov_b32_e32 v12, v74
	v_add_f32_e32 v2, 1.0, v2
	v_rcp_f32_e32 v15, v2
	s_nop 0
	v_pk_mul_f32 v[12:13], v[14:15], v[12:13]
	s_nop 0
	v_mul_f32_e32 v2, v12, v13
	v_and_b32_e32 v13, 0xffff0000, v37
	v_mul_f32_e32 v9, 0xbfb8aa3b, v13
	v_exp_f32_e32 v9, v9
	v_mov_b32_e32 v14, v11
	v_mov_b32_e32 v12, v75
	v_add_f32_e32 v9, 1.0, v9
	v_rcp_f32_e32 v15, v9
	s_nop 0
	v_pk_mul_f32 v[10:11], v[14:15], v[12:13]
	s_nop 0
	v_mul_f32_e32 v9, v10, v11
	v_lshlrev_b32_e32 v11, 16, v38
	v_cvt_pk_bf16_f32 v9, v2, v9
	v_mul_f32_e32 v2, 0xbfb8aa3b, v11
	v_exp_f32_e32 v2, v2
	v_mov_b32_e32 v12, v4
	v_mov_b32_e32 v10, v68
	v_add_f32_e32 v2, 1.0, v2
	v_rcp_f32_e32 v13, v2
	s_nop 0
	v_pk_mul_f32 v[10:11], v[12:13], v[10:11]
	s_nop 0
	v_mul_f32_e32 v2, v10, v11
	v_and_b32_e32 v11, 0xffff0000, v38
	v_mul_f32_e32 v4, 0xbfb8aa3b, v11
	v_exp_f32_e32 v4, v4
	v_mov_b32_e32 v12, v5
	v_mov_b32_e32 v10, v69
	v_add_f32_e32 v4, 1.0, v4
	v_rcp_f32_e32 v13, v4
	s_nop 0
	v_pk_mul_f32 v[4:5], v[12:13], v[10:11]
	s_nop 0
	v_mul_f32_e32 v4, v4, v5
	v_lshlrev_b32_e32 v5, 16, v39
	v_cvt_pk_bf16_f32 v10, v2, v4
	v_mul_f32_e32 v2, 0xbfb8aa3b, v5
	v_exp_f32_e32 v2, v2
	v_mov_b32_e32 v12, v6
	v_mov_b32_e32 v4, v70
	v_add_f32_e32 v2, 1.0, v2
	v_rcp_f32_e32 v13, v2
	s_nop 0
	v_pk_mul_f32 v[4:5], v[12:13], v[4:5]
	s_nop 0
	v_mul_f32_e32 v2, v4, v5
	v_and_b32_e32 v5, 0xffff0000, v39
	v_mul_f32_e32 v4, 0xbfb8aa3b, v5
	v_exp_f32_e32 v4, v4
	v_mov_b32_e32 v12, v7
	v_add_f32_e32 v4, 1.0, v4
	v_rcp_f32_e32 v13, v4
	v_mov_b32_e32 v4, v71
	v_pk_mul_f32 v[4:5], v[12:13], v[4:5]
	s_nop 0
	v_mul_f32_e32 v4, v4, v5
	v_cvt_pk_bf16_f32 v11, v2, v4
	flat_store_dwordx4 v[92:93], v[8:11] offset:256
	s_cbranch_vccz .LBB0_482
	s_waitcnt vmcnt(0)
	v_readlane_b32 s44, v244, 59
	v_readlane_b32 s40, v243, 18
	s_cmpk_gt_u32 s24, 0xff
	s_mov_b32 s43, 0x800000
	v_readlane_b32 s45, v244, 60
	v_readlane_b32 s46, v244, 61
	v_readlane_b32 s47, v244, 62
	v_readlane_b32 s48, v244, 63
	v_readlane_b32 s49, v243, 0
	v_readlane_b32 s50, v243, 1
	v_readlane_b32 s51, v243, 2
	v_readlane_b32 s41, v243, 19
	s_cbranch_scc1 .LBB0_489
	s_barrier

; #define PG8_WAIT_V(n) asm volatile("s_waitcnt vmcnt(" #n ")" ::: "memory")
; #define PG8_WAIT_L(n) asm volatile("s_waitcnt lgkmcnt(" #n ")" ::: "memory")
; #define PG8_BAR __builtin_amdgcn_s_barrier()
; #define PG8_SCHED __builtin_amdgcn_sched_barrier(0)
; template <class Epi, class AddrA, class AddrB>
; __device__ __forceinline__ void gemm_phase(const Sched S, const int lda, const int ldb, const int K, const AddrA addrA,
;                                            const AddrB addrB, const Epi E) {
;     ...
;     for (int t = 0; t < nt; t += 2) {
;       const bool last = (t == nt - 2);
;       const char* a1 = cA + (size_t)(t + 1) * kstep;
;       const char* a2 = last ? nA : cA + (size_t)(t + 2) * kstep;
;       const char* b2 = last ? nB : cB + (size_t)(t + 2) * kstep;
;       const char* a3 = a2 + kstep;
;       const char* b3 = b2 + kstep;
;       PG8_LDB(B0, 0, 0); PG8_SCHED; PG8_LDA(At, 0, 0); PG8_STAGE(PG8_SA(1, 1), a1 + hstepA, voffA);
;       PG8_WAIT_L(8); PG8_BAR; PG8_WAIT_L(0); PG8_MMA(0, 0, At, B0); PG8_BAR; PG8_SCHED;
;       PG8_LDB(B1, 0, 1); PG8_STAGE(PG8_SB(0, 0), b2, voffB);
;       PG8_BAR; PG8_WAIT_L(0); PG8_MMA(0, 1, At, B1); PG8_BAR;
;       PG8_LDA(At, 0, 1); PG8_STAGE(PG8_SA(0, 0), a2, voffA);
;       PG8_BAR; PG8_WAIT_L(0); PG8_MMA(1, 0, At, B0); PG8_BAR; PG8_SCHED;
;       PG8_STAGE(PG8_SB(0, 1), b2 + hstepB, voffB);
;       PG8_WAIT_V(6); PG8_BAR; PG8_MMA(1, 1, At, B1); PG8_BAR;
;       PG8_LDB(B0, 1, 0); PG8_SCHED; PG8_LDA(At, 1, 0); PG8_STAGE(PG8_SA(0, 1), a2 + hstepA, voffA);
;       PG8_WAIT_L(8); PG8_BAR; PG8_WAIT_L(0); PG8_MMA(0, 0, At, B0); PG8_BAR; PG8_SCHED;
;       PG8_LDB(B1, 1, 1); PG8_STAGE(PG8_SB(1, 0), b3, voffB);
;       PG8_BAR; PG8_WAIT_L(0); PG8_MMA(0, 1, At, B1); PG8_BAR;
;       PG8_LDA(At, 1, 1); PG8_STAGE(PG8_SA(1, 0), a3, voffA);
;       PG8_BAR; PG8_WAIT_L(0); PG8_MMA(1, 0, At, B0); PG8_BAR; PG8_SCHED;
;       PG8_STAGE(PG8_SB(1, 1), b3 + hstepB, voffB);
;       PG8_WAIT_V(6); PG8_BAR; PG8_MMA(1, 1, At, B1); PG8_BAR;
.LBB0_619:
	s_add_i32 s39, 0, 0x10000
	ds_read_b128 v[148:151], v246
	ds_read_b128 v[152:155], v246 offset:1024
	ds_read_b128 v[156:159], v246 offset:2048
	ds_read_b128 v[160:163], v246 offset:3072
	s_add_i32 m0, s26, 0xc000
	ds_read_b128 v[168:171], v146
	ds_read_b128 v[172:175], v146 offset:1024
	ds_read_b128 v[176:179], v146 offset:2048
	ds_read_b128 v[180:183], v146 offset:3072
	ds_read_b128 v[184:187], v146 offset:4096
	ds_read_b128 v[188:191], v146 offset:5120
	ds_read_b128 v[192:195], v146 offset:6144
	ds_read_b128 v[212:215], v146 offset:7168
	global_load_lds_dwordx4 v140, s[14:15]
	s_add_i32 m0, s26, 0xe000
	s_nop 0
	global_load_lds_dwordx4 v138, s[14:15]
	s_waitcnt lgkmcnt(6)
	s_setprio 1
	s_barrier
	v_mfma_f32_16x16x32_bf16 v[128:131], v[148:151], v[168:171], v[128:131]
	v_mfma_f32_16x16x32_bf16 v[128:131], v[152:155], v[172:175], v[128:131]
	s_waitcnt lgkmcnt(0)
	v_mfma_f32_16x16x32_bf16 v[120:123], v[148:151], v[176:179], v[120:123]
	v_mfma_f32_16x16x32_bf16 v[120:123], v[152:155], v[180:183], v[120:123]
	v_mfma_f32_16x16x32_bf16 v[112:115], v[148:151], v[184:187], v[112:115]
	v_mfma_f32_16x16x32_bf16 v[112:115], v[152:155], v[188:191], v[112:115]
	v_mfma_f32_16x16x32_bf16 v[104:107], v[148:151], v[192:195], v[104:107]
	v_mfma_f32_16x16x32_bf16 v[104:107], v[152:155], v[212:215], v[104:107]
	v_mfma_f32_16x16x32_bf16 v[124:127], v[156:159], v[168:171], v[124:127]
	v_mfma_f32_16x16x32_bf16 v[124:127], v[160:163], v[172:175], v[124:127]
	v_mfma_f32_16x16x32_bf16 v[116:119], v[156:159], v[176:179], v[116:119]
	v_mfma_f32_16x16x32_bf16 v[116:119], v[160:163], v[180:183], v[116:119]
	v_mfma_f32_16x16x32_bf16 v[108:111], v[156:159], v[184:187], v[108:111]
	v_mfma_f32_16x16x32_bf16 v[108:111], v[160:163], v[188:191], v[108:111]
	v_mfma_f32_16x16x32_bf16 v[100:103], v[156:159], v[192:195], v[100:103]
	v_mfma_f32_16x16x32_bf16 v[100:103], v[160:163], v[212:215], v[100:103]
	s_barrier
	s_setprio 0
	s_add_u32 s16, s14, 0xfff80080
	s_addc_u32 s17, s15, -1
	s_cmp_eq_u32 s38, 28
	s_cselect_b32 s19, s3, s17
	s_cselect_b32 s18, s13, s16
	s_cselect_b32 s17, s5, s37
	s_cselect_b32 s16, s35, s36
	s_add_i32 s42, 0, 0x14000
	s_add_i32 s39, s39, s25
	ds_read_b128 v[216:219], v246 offset:16384
	ds_read_b128 v[220:223], v246 offset:17408
	ds_read_b128 v[224:227], v246 offset:18432
	ds_read_b128 v[228:231], v246 offset:19456
	s_add_u32 s98, s16, 0x80
	s_addc_u32 s99, s17, 0
	s_mov_b32 m0, s39
	s_nop 0
	global_load_lds_dwordx4 v2, s[16:17]
	s_add_i32 m0, s39, 0x2000
	s_nop 0
	global_load_lds_dwordx4 v0, s[16:17]
	s_mov_b32 m0, s26
	s_add_u32 s100, s18, 0x80
	s_addc_u32 s101, s19, 0
	s_waitcnt vmcnt(10)
	s_waitcnt lgkmcnt(2)
	s_setprio 1
	s_barrier
	v_mfma_f32_16x16x32_bf16 v[96:99], v[216:219], v[168:171], v[96:99]
	v_mfma_f32_16x16x32_bf16 v[96:99], v[220:223], v[172:175], v[96:99]
	s_waitcnt lgkmcnt(0)
	v_mfma_f32_16x16x32_bf16 v[88:91], v[216:219], v[176:179], v[88:91]
	v_mfma_f32_16x16x32_bf16 v[88:91], v[220:223], v[180:183], v[88:91]
	v_mfma_f32_16x16x32_bf16 v[80:83], v[216:219], v[184:187], v[80:83]
	v_mfma_f32_16x16x32_bf16 v[80:83], v[220:223], v[188:191], v[80:83]
	v_mfma_f32_16x16x32_bf16 v[72:75], v[216:219], v[192:195], v[72:75]
	v_mfma_f32_16x16x32_bf16 v[72:75], v[220:223], v[212:215], v[72:75]
	v_mfma_f32_16x16x32_bf16 v[92:95], v[224:227], v[168:171], v[92:95]
	v_mfma_f32_16x16x32_bf16 v[92:95], v[228:231], v[172:175], v[92:95]
	v_mfma_f32_16x16x32_bf16 v[84:87], v[224:227], v[176:179], v[84:87]
	v_mfma_f32_16x16x32_bf16 v[84:87], v[228:231], v[180:183], v[84:87]
	v_mfma_f32_16x16x32_bf16 v[76:79], v[224:227], v[184:187], v[76:79]
	v_mfma_f32_16x16x32_bf16 v[76:79], v[228:231], v[188:191], v[76:79]
	v_mfma_f32_16x16x32_bf16 v[68:71], v[224:227], v[192:195], v[68:71]
	v_mfma_f32_16x16x32_bf16 v[68:71], v[228:231], v[212:215], v[68:71]
	s_barrier
	s_setprio 0
	ds_read_b128 v[168:171], v146 offset:16384
	ds_read_b128 v[172:175], v146 offset:17408
	ds_read_b128 v[176:179], v146 offset:18432
	ds_read_b128 v[180:183], v146 offset:19456
	ds_read_b128 v[184:187], v146 offset:20480
	ds_read_b128 v[188:191], v146 offset:21504
	ds_read_b128 v[192:195], v146 offset:22528
	ds_read_b128 v[212:215], v146 offset:23552
	global_load_lds_dwordx4 v134, s[18:19]
	s_mov_b32 m0, s27
	s_nop 0
	global_load_lds_dwordx4 v132, s[18:19]
	s_waitcnt lgkmcnt(6)
	s_setprio 1
	s_barrier
	v_mfma_f32_16x16x32_bf16 v[64:67], v[148:151], v[168:171], v[64:67]
	v_mfma_f32_16x16x32_bf16 v[64:67], v[152:155], v[172:175], v[64:67]
	s_waitcnt lgkmcnt(0)
	v_mfma_f32_16x16x32_bf16 v[56:59], v[148:151], v[176:179], v[56:59]
	v_mfma_f32_16x16x32_bf16 v[56:59], v[152:155], v[180:183], v[56:59]
	v_mfma_f32_16x16x32_bf16 v[48:51], v[148:151], v[184:187], v[48:51]
	v_mfma_f32_16x16x32_bf16 v[48:51], v[152:155], v[188:191], v[48:51]
	v_mfma_f32_16x16x32_bf16 v[40:43], v[148:151], v[192:195], v[40:43]
	v_mfma_f32_16x16x32_bf16 v[40:43], v[152:155], v[212:215], v[40:43]
	v_mfma_f32_16x16x32_bf16 v[60:63], v[156:159], v[168:171], v[60:63]
	v_mfma_f32_16x16x32_bf16 v[60:63], v[160:163], v[172:175], v[60:63]
	v_mfma_f32_16x16x32_bf16 v[52:55], v[156:159], v[176:179], v[52:55]
	v_mfma_f32_16x16x32_bf16 v[52:55], v[160:163], v[180:183], v[52:55]
	v_mfma_f32_16x16x32_bf16 v[44:47], v[156:159], v[184:187], v[44:47]
	v_mfma_f32_16x16x32_bf16 v[44:47], v[160:163], v[188:191], v[44:47]
	v_mfma_f32_16x16x32_bf16 v[36:39], v[156:159], v[192:195], v[36:39]
	v_mfma_f32_16x16x32_bf16 v[36:39], v[160:163], v[212:215], v[36:39]
	s_barrier
	s_setprio 0
	s_add_u32 s40, s16, 0x80000
	s_addc_u32 s41, s17, 0
	s_add_i32 s39, s42, s25
	s_mov_b32 m0, s39
	s_nop 0
	global_load_lds_dwordx4 v2, s[40:41]
	s_add_i32 m0, s39, 0x2000
	s_nop 0
	global_load_lds_dwordx4 v0, s[40:41]
	s_add_i32 s39, 0, 0x18000
	s_waitcnt vmcnt(8)
	s_setprio 1
	s_barrier
; #define PG8_WAIT_V(n) asm volatile("s_waitcnt vmcnt(" #n ")" ::: "memory")
; #define PG8_WAIT_L(n) asm volatile("s_waitcnt lgkmcnt(" #n ")" ::: "memory")
; #define PG8_BAR __builtin_amdgcn_s_barrier()
; #define PG8_SCHED __builtin_amdgcn_sched_barrier(0)
; template <class Epi, class AddrA, class AddrB>
; __device__ __forceinline__ void gemm_phase(const Sched S, const int lda, const int ldb, const int K, const AddrA addrA,
;                                            const AddrB addrB, const Epi E) {
;     ...
;       PG8_BAR; PG8_WAIT_L(0); PG8_MMA(1, 0, At, B0); PG8_BAR; PG8_SCHED;
;       PG8_STAGE(PG8_SB(0, 1), b2 + hstepB, voffB);
;       PG8_WAIT_V(6); PG8_BAR; PG8_MMA(1, 1, At, B1); PG8_BAR;
;       PG8_LDB(B0, 1, 0); PG8_SCHED; PG8_LDA(At, 1, 0); PG8_STAGE(PG8_SA(0, 1), a2 + hstepA, voffA);
;       PG8_WAIT_L(8); PG8_BAR; PG8_WAIT_L(0); PG8_MMA(0, 0, At, B0); PG8_BAR; PG8_SCHED;
;       PG8_LDB(B1, 1, 1); PG8_STAGE(PG8_SB(1, 0), b3, voffB);
;       PG8_BAR; PG8_WAIT_L(0); PG8_MMA(0, 1, At, B1); PG8_BAR;
;       PG8_LDA(At, 1, 1); PG8_STAGE(PG8_SA(1, 0), a3, voffA);
;       PG8_BAR; PG8_WAIT_L(0); PG8_MMA(1, 0, At, B0); PG8_BAR; PG8_SCHED;
	v_mfma_f32_16x16x32_bf16 v[32:35], v[216:219], v[168:171], v[32:35]
	v_mfma_f32_16x16x32_bf16 v[32:35], v[220:223], v[172:175], v[32:35]
	v_mfma_f32_16x16x32_bf16 v[24:27], v[216:219], v[176:179], v[24:27]
	v_mfma_f32_16x16x32_bf16 v[24:27], v[220:223], v[180:183], v[24:27]
	v_mfma_f32_16x16x32_bf16 v[16:19], v[216:219], v[184:187], v[16:19]
	v_mfma_f32_16x16x32_bf16 v[16:19], v[220:223], v[188:191], v[16:19]
	v_mfma_f32_16x16x32_bf16 v[8:11], v[216:219], v[192:195], v[8:11]
	v_mfma_f32_16x16x32_bf16 v[8:11], v[220:223], v[212:215], v[8:11]
	v_mfma_f32_16x16x32_bf16 v[28:31], v[224:227], v[168:171], v[28:31]
	v_mfma_f32_16x16x32_bf16 v[28:31], v[228:231], v[172:175], v[28:31]
	v_mfma_f32_16x16x32_bf16 v[20:23], v[224:227], v[176:179], v[20:23]
	v_mfma_f32_16x16x32_bf16 v[20:23], v[228:231], v[180:183], v[20:23]
	v_mfma_f32_16x16x32_bf16 v[12:15], v[224:227], v[184:187], v[12:15]
	v_mfma_f32_16x16x32_bf16 v[12:15], v[228:231], v[188:191], v[12:15]
	v_mfma_f32_16x16x32_bf16 v[4:7], v[224:227], v[192:195], v[4:7]
	v_mfma_f32_16x16x32_bf16 v[4:7], v[228:231], v[212:215], v[4:7]
	s_barrier
	s_setprio 0
	ds_read_b128 v[148:151], v246 offset:32768
	ds_read_b128 v[152:155], v246 offset:33792
	ds_read_b128 v[156:159], v246 offset:34816
	ds_read_b128 v[160:163], v246 offset:35840
	s_add_u32 s18, s18, 0x80000
	s_addc_u32 s19, s19, 0
	s_mov_b32 m0, s28
	ds_read_b128 v[168:171], v146 offset:32768
	ds_read_b128 v[172:175], v146 offset:33792
	ds_read_b128 v[176:179], v146 offset:34816
	ds_read_b128 v[180:183], v146 offset:35840
	ds_read_b128 v[184:187], v146 offset:36864
	ds_read_b128 v[188:191], v146 offset:37888
	ds_read_b128 v[192:195], v146 offset:38912
	ds_read_b128 v[212:215], v146 offset:39936
	global_load_lds_dwordx4 v134, s[18:19]
	s_mov_b32 m0, s29
	s_nop 0
	global_load_lds_dwordx4 v132, s[18:19]
	s_waitcnt lgkmcnt(6)
	s_setprio 1
	s_barrier
	v_mfma_f32_16x16x32_bf16 v[128:131], v[148:151], v[168:171], v[128:131]
	v_mfma_f32_16x16x32_bf16 v[128:131], v[152:155], v[172:175], v[128:131]
	s_waitcnt lgkmcnt(0)
	v_mfma_f32_16x16x32_bf16 v[120:123], v[148:151], v[176:179], v[120:123]
	v_mfma_f32_16x16x32_bf16 v[120:123], v[152:155], v[180:183], v[120:123]
	v_mfma_f32_16x16x32_bf16 v[112:115], v[148:151], v[184:187], v[112:115]
	v_mfma_f32_16x16x32_bf16 v[112:115], v[152:155], v[188:191], v[112:115]
	v_mfma_f32_16x16x32_bf16 v[104:107], v[148:151], v[192:195], v[104:107]
	v_mfma_f32_16x16x32_bf16 v[104:107], v[152:155], v[212:215], v[104:107]
	v_mfma_f32_16x16x32_bf16 v[124:127], v[156:159], v[168:171], v[124:127]
	v_mfma_f32_16x16x32_bf16 v[124:127], v[160:163], v[172:175], v[124:127]
	v_mfma_f32_16x16x32_bf16 v[116:119], v[156:159], v[176:179], v[116:119]
	v_mfma_f32_16x16x32_bf16 v[116:119], v[160:163], v[180:183], v[116:119]
	v_mfma_f32_16x16x32_bf16 v[108:111], v[156:159], v[184:187], v[108:111]
	v_mfma_f32_16x16x32_bf16 v[108:111], v[160:163], v[188:191], v[108:111]
	v_mfma_f32_16x16x32_bf16 v[100:103], v[156:159], v[192:195], v[100:103]
	v_mfma_f32_16x16x32_bf16 v[100:103], v[160:163], v[212:215], v[100:103]
	s_barrier
	s_setprio 0
	s_add_i32 s18, 0, 0x1c000
	s_add_i32 s19, s39, s25
	s_mov_b32 m0, s19
	ds_read_b128 v[216:219], v246 offset:49152
	ds_read_b128 v[220:223], v246 offset:50176
	ds_read_b128 v[224:227], v246 offset:51200
	ds_read_b128 v[228:231], v246 offset:52224
	global_load_lds_dwordx4 v2, s[98:99]
	s_add_i32 m0, s19, 0x2000
	s_nop 0
	global_load_lds_dwordx4 v0, s[98:99]
	s_mov_b32 m0, s30
	s_waitcnt vmcnt(10)
	s_waitcnt lgkmcnt(2)
	s_setprio 1
	s_barrier
	v_mfma_f32_16x16x32_bf16 v[96:99], v[216:219], v[168:171], v[96:99]
	v_mfma_f32_16x16x32_bf16 v[96:99], v[220:223], v[172:175], v[96:99]
	s_waitcnt lgkmcnt(0)
	v_mfma_f32_16x16x32_bf16 v[88:91], v[216:219], v[176:179], v[88:91]
	v_mfma_f32_16x16x32_bf16 v[88:91], v[220:223], v[180:183], v[88:91]
	v_mfma_f32_16x16x32_bf16 v[80:83], v[216:219], v[184:187], v[80:83]
	v_mfma_f32_16x16x32_bf16 v[80:83], v[220:223], v[188:191], v[80:83]
	v_mfma_f32_16x16x32_bf16 v[72:75], v[216:219], v[192:195], v[72:75]
	v_mfma_f32_16x16x32_bf16 v[72:75], v[220:223], v[212:215], v[72:75]
	v_mfma_f32_16x16x32_bf16 v[92:95], v[224:227], v[168:171], v[92:95]
	v_mfma_f32_16x16x32_bf16 v[92:95], v[228:231], v[172:175], v[92:95]
	v_mfma_f32_16x16x32_bf16 v[84:87], v[224:227], v[176:179], v[84:87]
	v_mfma_f32_16x16x32_bf16 v[84:87], v[228:231], v[180:183], v[84:87]
	v_mfma_f32_16x16x32_bf16 v[76:79], v[224:227], v[184:187], v[76:79]
	v_mfma_f32_16x16x32_bf16 v[76:79], v[228:231], v[188:191], v[76:79]
	v_mfma_f32_16x16x32_bf16 v[68:71], v[224:227], v[192:195], v[68:71]
	v_mfma_f32_16x16x32_bf16 v[68:71], v[228:231], v[212:215], v[68:71]
	s_barrier
	s_setprio 0
	ds_read_b128 v[168:171], v146 offset:49152
	ds_read_b128 v[172:175], v146 offset:50176
	ds_read_b128 v[176:179], v146 offset:51200
	ds_read_b128 v[180:183], v146 offset:52224
	ds_read_b128 v[184:187], v146 offset:53248
	ds_read_b128 v[188:191], v146 offset:54272
	ds_read_b128 v[192:195], v146 offset:55296
	ds_read_b128 v[212:215], v146 offset:56320
	global_load_lds_dwordx4 v134, s[100:101]
	s_mov_b32 m0, s31
	s_nop 0
	global_load_lds_dwordx4 v132, s[100:101]
	s_waitcnt lgkmcnt(6)
	s_setprio 1
	s_barrier
; #define PG8_WAIT_V(n) asm volatile("s_waitcnt vmcnt(" #n ")" ::: "memory")
; #define PG8_WAIT_L(n) asm volatile("s_waitcnt lgkmcnt(" #n ")" ::: "memory")
; #define PG8_BAR __builtin_amdgcn_s_barrier()
; #define PG8_SCHED __builtin_amdgcn_sched_barrier(0)
; template <class Epi, class AddrA, class AddrB>
; __device__ __forceinline__ void gemm_phase(const Sched S, const int lda, const int ldb, const int K, const AddrA addrA,
;                                            const AddrB addrB, const Epi E) {
;     ...
;       PG8_BAR; PG8_WAIT_L(0); PG8_MMA(1, 0, At, B0); PG8_BAR; PG8_SCHED;
;       PG8_STAGE(PG8_SB(1, 1), b3 + hstepB, voffB);
;       PG8_WAIT_V(6); PG8_BAR; PG8_MMA(1, 1, At, B1); PG8_BAR;
;   __device__ __forceinline__ void operator()(EPI_ARGS) const {
;     const size_t row0 = (size_t)u.pm * 256 + wr * 64 + fr;
;     const int col0 = u.pn * 256 + wc * 32 + 8 * fq;
; #pragma unroll
;     for (int ai = 0; ai < 2; ++ai)
; #pragma unroll
;       for (int bj = 0; bj < 2; ++bj) {
;         f32x4 x0[4], x1[4];
; #pragma unroll
;         for (int m = 0; m < 4; ++m) {
;           const size_t o = (row0 + ai * HALF + m * 16) * DM + col0 + bj * HALF;
;           x0[m] = *(const f32x4*)(xres + o);
;           x1[m] = *(const f32x4*)(xres + o + 4);
;         }
;         __builtin_amdgcn_sched_barrier(0);
; #pragma unroll
;         for (int m = 0; m < 4; ++m) {
;           const size_t o = (row0 + ai * HALF + m * 16) * DM + col0 + bj * HALF;
;           *(f32x4*)(hbuf + o) = acc[ai][bj][m][0] + x0[m] * ALPHA;
;           *(f32x4*)(hbuf + o + 4) = acc[ai][bj][m][1] + x1[m] * ALPHA;
;         }
	v_mfma_f32_16x16x32_bf16 v[64:67], v[148:151], v[168:171], v[64:67]
	v_mfma_f32_16x16x32_bf16 v[64:67], v[152:155], v[172:175], v[64:67]
	s_waitcnt lgkmcnt(0)
	v_mfma_f32_16x16x32_bf16 v[56:59], v[148:151], v[176:179], v[56:59]
	v_mfma_f32_16x16x32_bf16 v[56:59], v[152:155], v[180:183], v[56:59]
	v_mfma_f32_16x16x32_bf16 v[48:51], v[148:151], v[184:187], v[48:51]
	v_mfma_f32_16x16x32_bf16 v[48:51], v[152:155], v[188:191], v[48:51]
	v_mfma_f32_16x16x32_bf16 v[40:43], v[148:151], v[192:195], v[40:43]
	v_mfma_f32_16x16x32_bf16 v[40:43], v[152:155], v[212:215], v[40:43]
	v_mfma_f32_16x16x32_bf16 v[60:63], v[156:159], v[168:171], v[60:63]
	v_mfma_f32_16x16x32_bf16 v[60:63], v[160:163], v[172:175], v[60:63]
	v_mfma_f32_16x16x32_bf16 v[52:55], v[156:159], v[176:179], v[52:55]
	v_mfma_f32_16x16x32_bf16 v[52:55], v[160:163], v[180:183], v[52:55]
	v_mfma_f32_16x16x32_bf16 v[44:47], v[156:159], v[184:187], v[44:47]
	v_mfma_f32_16x16x32_bf16 v[44:47], v[160:163], v[188:191], v[44:47]
	v_mfma_f32_16x16x32_bf16 v[36:39], v[156:159], v[192:195], v[36:39]
	v_mfma_f32_16x16x32_bf16 v[36:39], v[160:163], v[212:215], v[36:39]
	s_barrier
	s_setprio 0
	s_add_u32 s16, s16, 0x80080
	s_addc_u32 s17, s17, 0
	s_add_i32 s18, s18, s25
	s_mov_b32 m0, s18
	s_nop 0
	global_load_lds_dwordx4 v2, s[16:17]
	s_add_i32 m0, s18, 0x2000
	s_nop 0
	global_load_lds_dwordx4 v0, s[16:17]
	s_add_i32 s38, s38, 2
	s_add_u32 s36, s36, 0x100
	s_addc_u32 s37, s37, 0
	s_add_u32 s14, s14, 0x100
	s_addc_u32 s15, s15, 0
	s_waitcnt vmcnt(8)
	s_setprio 1
	s_barrier
	v_mfma_f32_16x16x32_bf16 v[32:35], v[216:219], v[168:171], v[32:35]
	v_mfma_f32_16x16x32_bf16 v[32:35], v[220:223], v[172:175], v[32:35]
	v_mfma_f32_16x16x32_bf16 v[24:27], v[216:219], v[176:179], v[24:27]
	v_mfma_f32_16x16x32_bf16 v[24:27], v[220:223], v[180:183], v[24:27]
	v_mfma_f32_16x16x32_bf16 v[16:19], v[216:219], v[184:187], v[16:19]
	v_mfma_f32_16x16x32_bf16 v[16:19], v[220:223], v[188:191], v[16:19]
	v_mfma_f32_16x16x32_bf16 v[8:11], v[216:219], v[192:195], v[8:11]
	v_mfma_f32_16x16x32_bf16 v[8:11], v[220:223], v[212:215], v[8:11]
	v_mfma_f32_16x16x32_bf16 v[28:31], v[224:227], v[168:171], v[28:31]
	v_mfma_f32_16x16x32_bf16 v[28:31], v[228:231], v[172:175], v[28:31]
	v_mfma_f32_16x16x32_bf16 v[20:23], v[224:227], v[176:179], v[20:23]
	v_mfma_f32_16x16x32_bf16 v[20:23], v[228:231], v[180:183], v[20:23]
	v_mfma_f32_16x16x32_bf16 v[12:15], v[224:227], v[184:187], v[12:15]
	v_mfma_f32_16x16x32_bf16 v[12:15], v[228:231], v[188:191], v[12:15]
	v_mfma_f32_16x16x32_bf16 v[4:7], v[224:227], v[192:195], v[4:7]
	v_mfma_f32_16x16x32_bf16 v[4:7], v[228:231], v[212:215], v[4:7]
	s_barrier
	s_setprio 0
	s_cmp_gt_u32 s38, 29
	s_cbranch_scc0 .LBB0_619
	s_ashr_i32 s13, s12, 31
	v_lshl_or_b32 v142, s34, 8, v145
	v_ashrrev_i32_e32 v143, 31, v142
	s_lshl_b64 s[12:13], s[12:13], 21
	v_lshlrev_b64 v[184:185], 2, v[142:143]
	v_lshl_add_u64 v[188:189], s[12:13], 0, v[136:137]
	v_lshl_add_u64 v[186:187], s[0:1], 0, v[184:185]
	v_or_b32_e32 v190, 0x20000, v188
	v_mov_b32_e32 v191, v189
	v_or_b32_e32 v192, 0x40000, v188
	v_mov_b32_e32 v193, v189
	v_or_b32_e32 v194, 0x60000, v188
	v_mov_b32_e32 v195, v189
	v_lshl_add_u64 v[142:143], v[186:187], 0, v[188:189]
	v_lshl_add_u64 v[160:161], v[186:187], 0, v[190:191]
	v_lshl_add_u64 v[172:173], v[186:187], 0, v[192:193]
	v_lshl_add_u64 v[180:181], v[186:187], 0, v[194:195]
	flat_load_dwordx4 v[148:151], v[142:143]
	flat_load_dwordx4 v[152:155], v[142:143] offset:16
	flat_load_dwordx4 v[156:159], v[160:161]
	s_nop 0
	flat_load_dwordx4 v[160:163], v[160:161] offset:16
	s_nop 0
	flat_load_dwordx4 v[168:171], v[172:173]
	s_nop 0
	flat_load_dwordx4 v[172:175], v[172:173] offset:16
	s_nop 0
	flat_load_dwordx4 v[176:179], v[180:181]
	s_nop 0
	flat_load_dwordx4 v[180:183], v[180:181] offset:16
	v_lshl_add_u64 v[184:185], s[48:49], 0, v[184:185]
	s_mov_b32 s14, 0x3fb504f3
	s_waitcnt vmcnt(0) lgkmcnt(0)
	v_pk_fma_f32 v[148:149], v[148:149], s[14:15], v[128:129] op_sel_hi:[1,0,1]
	v_lshl_add_u64 v[128:129], v[184:185], 0, v[188:189]
	v_pk_fma_f32 v[126:127], v[154:155], s[14:15], v[126:127] op_sel_hi:[1,0,1]
	v_pk_fma_f32 v[124:125], v[152:153], s[14:15], v[124:125] op_sel_hi:[1,0,1]
	global_store_dwordx4 v[128:129], v[124:127], off offset:16
	v_pk_fma_f32 v[118:119], v[162:163], s[14:15], v[118:119] op_sel_hi:[1,0,1]
	v_pk_fma_f32 v[116:117], v[160:161], s[14:15], v[116:117] op_sel_hi:[1,0,1]
	v_lshl_add_u64 v[124:125], v[184:185], 0, v[190:191]
	v_pk_fma_f32 v[122:123], v[158:159], s[14:15], v[122:123] op_sel_hi:[1,0,1]
	v_pk_fma_f32 v[120:121], v[156:157], s[14:15], v[120:121] op_sel_hi:[1,0,1]
	global_store_dwordx4 v[124:125], v[116:119], off offset:16
	v_pk_fma_f32 v[110:111], v[174:175], s[14:15], v[110:111] op_sel_hi:[1,0,1]
	v_pk_fma_f32 v[108:109], v[172:173], s[14:15], v[108:109] op_sel_hi:[1,0,1]
	v_lshl_add_u64 v[116:117], v[184:185], 0, v[192:193]
	s_mov_b64 s[12:13], 0x200
	v_pk_fma_f32 v[150:151], v[150:151], s[14:15], v[130:131] op_sel_hi:[1,0,1]
	global_store_dwordx4 v[124:125], v[120:123], off
	v_pk_fma_f32 v[114:115], v[170:171], s[14:15], v[114:115] op_sel_hi:[1,0,1]
	v_pk_fma_f32 v[112:113], v[168:169], s[14:15], v[112:113] op_sel_hi:[1,0,1]
	global_store_dwordx4 v[116:117], v[108:111], off offset:16
	v_pk_fma_f32 v[106:107], v[178:179], s[14:15], v[106:107] op_sel_hi:[1,0,1]
	v_pk_fma_f32 v[104:105], v[176:177], s[14:15], v[104:105] op_sel_hi:[1,0,1]
	v_lshl_add_u64 v[108:109], v[184:185], 0, v[194:195]
	v_pk_fma_f32 v[102:103], v[182:183], s[14:15], v[102:103] op_sel_hi:[1,0,1]
	v_pk_fma_f32 v[100:101], v[180:181], s[14:15], v[100:101] op_sel_hi:[1,0,1]
	v_lshl_add_u64 v[124:125], v[186:187], 0, s[12:13]
	global_store_dwordx4 v[128:129], v[148:151], off
	global_store_dwordx4 v[116:117], v[112:115], off
	global_store_dwordx4 v[108:109], v[104:107], off
	global_store_dwordx4 v[108:109], v[100:103], off offset:16
	v_lshl_add_u64 v[112:113], v[124:125], 0, v[190:191]
	v_lshl_add_u64 v[120:121], v[124:125], 0, v[192:193]
	v_lshl_add_u64 v[130:131], v[124:125], 0, v[194:195]
	flat_load_dwordx4 v[100:103], v[142:143] offset:512
	flat_load_dwordx4 v[104:107], v[142:143] offset:528
	flat_load_dwordx4 v[108:111], v[112:113]
	s_nop 0
	flat_load_dwordx4 v[112:115], v[112:113] offset:16
	s_nop 0
	flat_load_dwordx4 v[116:119], v[120:121]
	s_nop 0
	flat_load_dwordx4 v[120:123], v[120:121] offset:16
	s_nop 0
	flat_load_dwordx4 v[124:127], v[130:131]
	flat_load_dwordx4 v[148:151], v[130:131] offset:16
	s_mov_b32 s3, 0x100000
	s_waitcnt vmcnt(0) lgkmcnt(0)
;   __device__ __forceinline__ void operator()(EPI_ARGS) const {
;     ...
;     for (int ai = 0; ai < 2; ++ai)
; #pragma unroll
;       for (int bj = 0; bj < 2; ++bj) {
;         f32x4 x0[4], x1[4];
; #pragma unroll
;         for (int m = 0; m < 4; ++m) {
;           const size_t o = (row0 + ai * HALF + m * 16) * DM + col0 + bj * HALF;
;           x0[m] = *(const f32x4*)(xres + o);
;           x1[m] = *(const f32x4*)(xres + o + 4);
;         }
;         __builtin_amdgcn_sched_barrier(0);
; #pragma unroll
;         for (int m = 0; m < 4; ++m) {
;           const size_t o = (row0 + ai * HALF + m * 16) * DM + col0 + bj * HALF;
;           *(f32x4*)(hbuf + o) = acc[ai][bj][m][0] + x0[m] * ALPHA;
;           *(f32x4*)(hbuf + o + 4) = acc[ai][bj][m][1] + x1[m] * ALPHA;
;         }
	v_pk_fma_f32 v[96:97], v[100:101], s[14:15], v[96:97] op_sel_hi:[1,0,1]
	v_add_co_u32_e32 v100, vcc, s3, v142
	s_mov_b32 s5, 0x120000
	s_nop 0
	v_addc_co_u32_e32 v101, vcc, 0, v143, vcc
	v_pk_fma_f32 v[98:99], v[102:103], s[14:15], v[98:99] op_sel_hi:[1,0,1]
	v_add_co_u32_e32 v102, vcc, s5, v142
	v_lshl_add_u64 v[130:131], v[184:185], 0, s[12:13]
	v_pk_fma_f32 v[94:95], v[106:107], s[14:15], v[94:95] op_sel_hi:[1,0,1]
	v_pk_fma_f32 v[92:93], v[104:105], s[14:15], v[92:93] op_sel_hi:[1,0,1]
	v_addc_co_u32_e32 v103, vcc, 0, v143, vcc
	s_mov_b32 s12, 0x140000
	global_store_dwordx4 v[128:129], v[92:95], off offset:528
	v_pk_fma_f32 v[86:87], v[114:115], s[14:15], v[86:87] op_sel_hi:[1,0,1]
	v_pk_fma_f32 v[84:85], v[112:113], s[14:15], v[84:85] op_sel_hi:[1,0,1]
	v_lshl_add_u64 v[92:93], v[130:131], 0, v[190:191]
	v_add_co_u32_e32 v104, vcc, s12, v142
	global_store_dwordx4 v[92:93], v[84:87], off offset:16
	v_pk_fma_f32 v[78:79], v[122:123], s[14:15], v[78:79] op_sel_hi:[1,0,1]
	v_pk_fma_f32 v[76:77], v[120:121], s[14:15], v[76:77] op_sel_hi:[1,0,1]
	v_lshl_add_u64 v[84:85], v[130:131], 0, v[192:193]
	v_addc_co_u32_e32 v105, vcc, 0, v143, vcc
	s_mov_b32 s13, 0x160000
	v_pk_fma_f32 v[90:91], v[110:111], s[14:15], v[90:91] op_sel_hi:[1,0,1]
	v_pk_fma_f32 v[88:89], v[108:109], s[14:15], v[88:89] op_sel_hi:[1,0,1]
	v_pk_fma_f32 v[82:83], v[118:119], s[14:15], v[82:83] op_sel_hi:[1,0,1]
	v_pk_fma_f32 v[80:81], v[116:117], s[14:15], v[80:81] op_sel_hi:[1,0,1]
	global_store_dwordx4 v[84:85], v[76:79], off offset:16
	v_pk_fma_f32 v[74:75], v[126:127], s[14:15], v[74:75] op_sel_hi:[1,0,1]
	v_pk_fma_f32 v[72:73], v[124:125], s[14:15], v[72:73] op_sel_hi:[1,0,1]
	v_lshl_add_u64 v[76:77], v[130:131], 0, v[194:195]
	v_pk_fma_f32 v[70:71], v[150:151], s[14:15], v[70:71] op_sel_hi:[1,0,1]
	v_pk_fma_f32 v[68:69], v[148:149], s[14:15], v[68:69] op_sel_hi:[1,0,1]
	s_mov_b64 s[16:17], 0x100000
	s_mov_b64 s[18:19], 0x120000
	s_mov_b64 s[34:35], 0x140000
	s_mov_b64 s[36:37], 0x160000
	v_add_co_u32_e32 v106, vcc, s13, v142
	global_store_dwordx4 v[128:129], v[96:99], off offset:512
	global_store_dwordx4 v[92:93], v[88:91], off
	global_store_dwordx4 v[84:85], v[80:83], off
	global_store_dwordx4 v[76:77], v[72:75], off
	global_store_dwordx4 v[76:77], v[68:71], off offset:16
	v_lshl_add_u64 v[80:81], v[142:143], 0, s[18:19]
	v_lshl_add_u64 v[72:73], v[142:143], 0, s[16:17]
	v_lshl_add_u64 v[88:89], v[142:143], 0, s[34:35]
	v_lshl_add_u64 v[96:97], v[142:143], 0, s[36:37]
	v_addc_co_u32_e32 v107, vcc, 0, v143, vcc
	flat_load_dwordx4 v[68:71], v[100:101]
	s_nop 0
	flat_load_dwordx4 v[72:75], v[72:73] offset:16
	s_nop 0
	flat_load_dwordx4 v[76:79], v[102:103]
	s_nop 0
	flat_load_dwordx4 v[80:83], v[80:81] offset:16
	s_nop 0
	flat_load_dwordx4 v[84:87], v[104:105]
	s_nop 0
	flat_load_dwordx4 v[88:91], v[88:89] offset:16
	s_nop 0
	flat_load_dwordx4 v[92:95], v[106:107]
	s_nop 0
	flat_load_dwordx4 v[96:99], v[96:97] offset:16
	s_waitcnt vmcnt(0) lgkmcnt(0)
; #define PG8_WAIT_V(n) asm volatile("s_waitcnt vmcnt(" #n ")" ::: "memory")
; #define PG8_BAR __builtin_amdgcn_s_barrier()
; template <class Epi, class AddrA, class AddrB>
; __device__ __forceinline__ void gemm_phase(const Sched S, const int lda, const int ldb, const int K, const AddrA addrA,
;                                            const AddrB addrB, const Epi E) {
;     ...
;     if (!has_next) break;
;     if (!(Epi::KEEP && cur.br + 1 < S.nbr)) {
; #pragma unroll
;       for (int a = 0; a < 2; ++a)
; #pragma unroll
;         for (int b = 0; b < 2; ++b)
; #pragma unroll
;           for (int m = 0; m < 4; ++m)
; #pragma unroll
;             for (int n = 0; n < 2; ++n) acc[a][b][m][n] = (f32x4){0.f, 0.f, 0.f, 0.f};
;     }
;     cur = nxt; cA = nA; cB = nB; ++ui;
;   }
;   PG8_WAIT_V(0);
;   if (wr == 0) PG8_BAR;
;   PG8_BAR;
;   __device__ __forceinline__ void operator()(EPI_ARGS) const {
;     ...
;     for (int ai = 0; ai < 2; ++ai)
; #pragma unroll
;       for (int bj = 0; bj < 2; ++bj) {
;         f32x4 x0[4], x1[4];
; #pragma unroll
;         for (int m = 0; m < 4; ++m) {
;           const size_t o = (row0 + ai * HALF + m * 16) * DM + col0 + bj * HALF;
;           x0[m] = *(const f32x4*)(xres + o);
;           x1[m] = *(const f32x4*)(xres + o + 4);
;         }
;         __builtin_amdgcn_sched_barrier(0);
; #pragma unroll
;         for (int m = 0; m < 4; ++m) {
;           const size_t o = (row0 + ai * HALF + m * 16) * DM + col0 + bj * HALF;
;           *(f32x4*)(hbuf + o) = acc[ai][bj][m][0] + x0[m] * ALPHA;
;           *(f32x4*)(hbuf + o + 4) = acc[ai][bj][m][1] + x1[m] * ALPHA;
;         }
	v_pk_fma_f32 v[66:67], v[70:71], s[14:15], v[66:67] op_sel_hi:[1,0,1]
	v_add_co_u32_e32 v70, vcc, s3, v128
	v_pk_fma_f32 v[64:65], v[68:69], s[14:15], v[64:65] op_sel_hi:[1,0,1]
	v_lshl_add_u64 v[68:69], v[128:129], 0, s[16:17]
	v_addc_co_u32_e32 v71, vcc, 0, v129, vcc
	v_pk_fma_f32 v[62:63], v[74:75], s[14:15], v[62:63] op_sel_hi:[1,0,1]
	v_pk_fma_f32 v[60:61], v[72:73], s[14:15], v[60:61] op_sel_hi:[1,0,1]
	global_store_dwordx4 v[68:69], v[60:63], off offset:16
	v_add_co_u32_e32 v68, vcc, s5, v128
	s_nop 0
	v_lshl_add_u64 v[60:61], v[128:129], 0, s[18:19]
	v_addc_co_u32_e32 v69, vcc, 0, v129, vcc
	v_add_co_u32_e32 v72, vcc, s12, v128
	v_pk_fma_f32 v[54:55], v[82:83], s[14:15], v[54:55] op_sel_hi:[1,0,1]
	v_pk_fma_f32 v[52:53], v[80:81], s[14:15], v[52:53] op_sel_hi:[1,0,1]
	v_addc_co_u32_e32 v73, vcc, 0, v129, vcc
	global_store_dwordx4 v[60:61], v[52:55], off offset:16
	v_pk_fma_f32 v[46:47], v[90:91], s[14:15], v[46:47] op_sel_hi:[1,0,1]
	v_pk_fma_f32 v[44:45], v[88:89], s[14:15], v[44:45] op_sel_hi:[1,0,1]
	v_lshl_add_u64 v[52:53], v[128:129], 0, s[34:35]
	v_add_co_u32_e32 v74, vcc, s13, v128
	v_pk_fma_f32 v[58:59], v[78:79], s[14:15], v[58:59] op_sel_hi:[1,0,1]
	v_pk_fma_f32 v[56:57], v[76:77], s[14:15], v[56:57] op_sel_hi:[1,0,1]
	v_pk_fma_f32 v[50:51], v[86:87], s[14:15], v[50:51] op_sel_hi:[1,0,1]
	v_pk_fma_f32 v[48:49], v[84:85], s[14:15], v[48:49] op_sel_hi:[1,0,1]
	global_store_dwordx4 v[52:53], v[44:47], off offset:16
	v_pk_fma_f32 v[42:43], v[94:95], s[14:15], v[42:43] op_sel_hi:[1,0,1]
	v_pk_fma_f32 v[40:41], v[92:93], s[14:15], v[40:41] op_sel_hi:[1,0,1]
	v_lshl_add_u64 v[44:45], v[128:129], 0, s[36:37]
	v_addc_co_u32_e32 v75, vcc, 0, v129, vcc
	v_pk_fma_f32 v[38:39], v[98:99], s[14:15], v[38:39] op_sel_hi:[1,0,1]
	v_pk_fma_f32 v[36:37], v[96:97], s[14:15], v[36:37] op_sel_hi:[1,0,1]
	s_mov_b64 s[12:13], 0x100200
	s_mov_b64 s[16:17], 0x120200
	s_mov_b64 s[18:19], 0x140200
	s_mov_b64 s[34:35], 0x160200
	global_store_dwordx4 v[70:71], v[64:67], off
	global_store_dwordx4 v[68:69], v[56:59], off
	global_store_dwordx4 v[72:73], v[48:51], off
	global_store_dwordx4 v[74:75], v[40:43], off
	global_store_dwordx4 v[44:45], v[36:39], off offset:16
	v_lshl_add_u64 v[44:45], v[142:143], 0, s[12:13]
	v_lshl_add_u64 v[48:49], v[142:143], 0, s[16:17]
	v_lshl_add_u64 v[60:61], v[142:143], 0, s[18:19]
	v_lshl_add_u64 v[64:65], v[142:143], 0, s[34:35]
	flat_load_dwordx4 v[36:39], v[100:101] offset:512
	flat_load_dwordx4 v[40:43], v[102:103] offset:512
	s_nop 0
	flat_load_dwordx4 v[44:47], v[44:45] offset:16
	s_nop 0
	flat_load_dwordx4 v[48:51], v[48:49] offset:16
	s_nop 0
	flat_load_dwordx4 v[52:55], v[104:105] offset:512
	flat_load_dwordx4 v[56:59], v[106:107] offset:512
	s_nop 0
	flat_load_dwordx4 v[60:63], v[60:61] offset:16
	s_nop 0
	flat_load_dwordx4 v[64:67], v[64:65] offset:16
	s_waitcnt vmcnt(0) lgkmcnt(0)
	v_pk_fma_f32 v[32:33], v[36:37], s[14:15], v[32:33] op_sel_hi:[1,0,1]
	v_lshl_add_u64 v[36:37], v[128:129], 0, s[12:13]
	v_pk_fma_f32 v[30:31], v[46:47], s[14:15], v[30:31] op_sel_hi:[1,0,1]
	v_pk_fma_f32 v[28:29], v[44:45], s[14:15], v[28:29] op_sel_hi:[1,0,1]
	global_store_dwordx4 v[36:37], v[28:31], off offset:16
	v_pk_fma_f32 v[22:23], v[50:51], s[14:15], v[22:23] op_sel_hi:[1,0,1]
	v_pk_fma_f32 v[20:21], v[48:49], s[14:15], v[20:21] op_sel_hi:[1,0,1]
	v_lshl_add_u64 v[28:29], v[128:129], 0, s[16:17]
	global_store_dwordx4 v[28:29], v[20:23], off offset:16
	v_pk_fma_f32 v[14:15], v[62:63], s[14:15], v[14:15] op_sel_hi:[1,0,1]
	v_pk_fma_f32 v[12:13], v[60:61], s[14:15], v[12:13] op_sel_hi:[1,0,1]
	v_lshl_add_u64 v[20:21], v[128:129], 0, s[18:19]
	v_pk_fma_f32 v[34:35], v[38:39], s[14:15], v[34:35] op_sel_hi:[1,0,1]
	v_pk_fma_f32 v[26:27], v[42:43], s[14:15], v[26:27] op_sel_hi:[1,0,1]
	v_pk_fma_f32 v[24:25], v[40:41], s[14:15], v[24:25] op_sel_hi:[1,0,1]
	v_pk_fma_f32 v[18:19], v[54:55], s[14:15], v[18:19] op_sel_hi:[1,0,1]
	v_pk_fma_f32 v[16:17], v[52:53], s[14:15], v[16:17] op_sel_hi:[1,0,1]
	global_store_dwordx4 v[20:21], v[12:15], off offset:16
	v_pk_fma_f32 v[10:11], v[58:59], s[14:15], v[10:11] op_sel_hi:[1,0,1]
	v_pk_fma_f32 v[8:9], v[56:57], s[14:15], v[8:9] op_sel_hi:[1,0,1]
	v_lshl_add_u64 v[12:13], v[128:129], 0, s[34:35]
	v_pk_fma_f32 v[6:7], v[66:67], s[14:15], v[6:7] op_sel_hi:[1,0,1]
	v_pk_fma_f32 v[4:5], v[64:65], s[14:15], v[4:5] op_sel_hi:[1,0,1]
	s_and_b64 vcc, exec, s[6:7]
	s_mov_b32 s34, s4
	s_mov_b32 s12, s2
	s_mov_b64 s[14:15], s[10:11]
	s_mov_b64 s[16:17], s[8:9]
	global_store_dwordx4 v[70:71], v[32:35], off offset:512
	global_store_dwordx4 v[68:69], v[24:27], off offset:512
	global_store_dwordx4 v[72:73], v[16:19], off offset:512
	global_store_dwordx4 v[74:75], v[8:11], off offset:512
	global_store_dwordx4 v[12:13], v[4:7], off offset:16
	s_cbranch_vccz .LBB0_616
	s_waitcnt vmcnt(0)
	s_cmpk_gt_u32 s20, 0xff
	s_cbranch_scc1 .LBB0_623
	s_barrier
